# speedup vs baseline: 1.0182x; 1.0182x over previous
.Llate_p1_done:
.LBB0_89:
	ds_read_b128 v[128:131], v222
	ds_read_b128 v[132:135], v222 offset:2048
	ds_read_b128 v[136:139], v223
	ds_read_b128 v[140:143], v223 offset:2048
	v_lshl_add_u64 v[192:193], s[38:39], 0, v[212:213]
	s_mov_b64 s[82:83], 0x80080
	s_mov_b32 m0, s74
	v_lshl_add_u64 v[176:177], v[192:193], 0, s[82:83]
	s_mov_b64 s[82:83], 0xc0080
	ds_read_b128 v[144:147], v224
	ds_read_b128 v[148:151], v224 offset:2048
	ds_read_b128 v[152:155], v225
	ds_read_b128 v[156:159], v225 offset:2048
	ds_read_b128 v[160:163], v224 offset:4096
	ds_read_b128 v[164:167], v224 offset:6144
	ds_read_b128 v[168:171], v225 offset:4096
	ds_read_b128 v[172:175], v225 offset:6144
	global_load_lds_dwordx4 v[176:177], off
	v_lshl_add_u64 v[176:177], v[192:193], 0, s[82:83]
	s_mov_b32 m0, s75
	s_nop 0
	global_load_lds_dwordx4 v[176:177], off
	s_waitcnt lgkmcnt(8)
	s_barrier
	s_waitcnt lgkmcnt(0)
	v_mfma_f32_16x16x32_bf16 v[124:127], v[128:131], v[144:147], v[124:127]
	v_mfma_f32_16x16x32_bf16 v[120:123], v[132:135], v[144:147], v[120:123]
	v_mfma_f32_16x16x32_bf16 v[116:119], v[128:131], v[148:151], v[116:119]
	v_mfma_f32_16x16x32_bf16 v[112:115], v[132:135], v[148:151], v[112:115]
	v_mfma_f32_16x16x32_bf16 v[108:111], v[128:131], v[160:163], v[108:111]
	v_mfma_f32_16x16x32_bf16 v[104:107], v[132:135], v[160:163], v[104:107]
	v_mfma_f32_16x16x32_bf16 v[100:103], v[128:131], v[164:167], v[100:103]
	v_mfma_f32_16x16x32_bf16 v[96:99], v[132:135], v[164:167], v[96:99]
	v_mfma_f32_16x16x32_bf16 v[124:127], v[136:139], v[152:155], v[124:127]
	v_mfma_f32_16x16x32_bf16 v[120:123], v[140:143], v[152:155], v[120:123]
	v_mfma_f32_16x16x32_bf16 v[116:119], v[136:139], v[156:159], v[116:119]
	v_mfma_f32_16x16x32_bf16 v[112:115], v[140:143], v[156:159], v[112:115]
	v_mfma_f32_16x16x32_bf16 v[108:111], v[136:139], v[168:171], v[108:111]
	v_mfma_f32_16x16x32_bf16 v[104:107], v[140:143], v[168:171], v[104:107]
	v_mfma_f32_16x16x32_bf16 v[100:103], v[136:139], v[172:175], v[100:103]
	v_mfma_f32_16x16x32_bf16 v[96:99], v[140:143], v[172:175], v[96:99]
	s_barrier
	v_lshl_add_u64 v[194:195], s[40:41], 0, v[212:213]
	s_mov_b32 m0, s30
	v_lshl_add_u64 v[196:197], v[194:195], 0, s[24:25]
	ds_read_b128 v[176:179], v226
	ds_read_b128 v[180:183], v226 offset:2048
	ds_read_b128 v[184:187], v227
	ds_read_b128 v[188:191], v227 offset:2048
	global_load_lds_dwordx4 v[196:197], off
	v_lshl_add_u64 v[196:197], v[194:195], 0, s[26:27]
	s_mov_b32 m0, s31
	s_nop 0
	global_load_lds_dwordx4 v[196:197], off
	s_barrier
	s_waitcnt lgkmcnt(0)
	v_mfma_f32_16x16x32_bf16 v[92:95], v[176:179], v[144:147], v[92:95]
	v_mfma_f32_16x16x32_bf16 v[88:91], v[180:183], v[144:147], v[88:91]
	v_mfma_f32_16x16x32_bf16 v[84:87], v[176:179], v[148:151], v[84:87]
	v_mfma_f32_16x16x32_bf16 v[80:83], v[180:183], v[148:151], v[80:83]
	v_mfma_f32_16x16x32_bf16 v[76:79], v[176:179], v[160:163], v[76:79]
	v_mfma_f32_16x16x32_bf16 v[72:75], v[180:183], v[160:163], v[72:75]
	v_mfma_f32_16x16x32_bf16 v[68:71], v[176:179], v[164:167], v[68:71]
	v_mfma_f32_16x16x32_bf16 v[56:59], v[180:183], v[164:167], v[56:59]
	v_mfma_f32_16x16x32_bf16 v[92:95], v[184:187], v[152:155], v[92:95]
	v_mfma_f32_16x16x32_bf16 v[88:91], v[188:191], v[152:155], v[88:91]
	v_mfma_f32_16x16x32_bf16 v[84:87], v[184:187], v[156:159], v[84:87]
	v_mfma_f32_16x16x32_bf16 v[80:83], v[188:191], v[156:159], v[80:83]
	v_mfma_f32_16x16x32_bf16 v[76:79], v[184:187], v[168:171], v[76:79]
	v_mfma_f32_16x16x32_bf16 v[72:75], v[188:191], v[168:171], v[72:75]
	v_mfma_f32_16x16x32_bf16 v[68:71], v[184:187], v[172:175], v[68:71]
	v_mfma_f32_16x16x32_bf16 v[56:59], v[188:191], v[172:175], v[56:59]
	s_barrier
	s_mov_b32 m0, s22
	v_lshl_add_u64 v[196:197], v[192:193], 0, s[24:25]
	ds_read_b128 v[144:147], v224 offset:16384
	ds_read_b128 v[148:151], v224 offset:18432
	ds_read_b128 v[152:155], v225 offset:16384
	ds_read_b128 v[156:159], v225 offset:18432
	ds_read_b128 v[160:163], v224 offset:20480
	ds_read_b128 v[164:167], v224 offset:22528
	ds_read_b128 v[168:171], v225 offset:20480
	ds_read_b128 v[172:175], v225 offset:22528
	global_load_lds_dwordx4 v[196:197], off
	v_lshl_add_u64 v[196:197], v[192:193], 0, s[26:27]
	s_mov_b32 m0, s33
	s_nop 0
	global_load_lds_dwordx4 v[196:197], off
	s_barrier
	s_waitcnt lgkmcnt(0)
	v_mfma_f32_16x16x32_bf16 v[28:31], v[128:131], v[144:147], v[28:31]
	v_mfma_f32_16x16x32_bf16 v[24:27], v[132:135], v[144:147], v[24:27]
	v_mfma_f32_16x16x32_bf16 v[20:23], v[128:131], v[148:151], v[20:23]
	v_mfma_f32_16x16x32_bf16 v[16:19], v[132:135], v[148:151], v[16:19]
	v_mfma_f32_16x16x32_bf16 v[12:15], v[128:131], v[160:163], v[12:15]
	v_mfma_f32_16x16x32_bf16 v[8:11], v[132:135], v[160:163], v[8:11]
	v_mfma_f32_16x16x32_bf16 v[4:7], v[128:131], v[164:167], v[4:7]
	v_mfma_f32_16x16x32_bf16 v[0:3], v[132:135], v[164:167], v[0:3]
	v_mfma_f32_16x16x32_bf16 v[28:31], v[136:139], v[152:155], v[28:31]
	v_mfma_f32_16x16x32_bf16 v[24:27], v[140:143], v[152:155], v[24:27]
	v_mfma_f32_16x16x32_bf16 v[20:23], v[136:139], v[156:159], v[20:23]
	v_mfma_f32_16x16x32_bf16 v[16:19], v[140:143], v[156:159], v[16:19]
	v_mfma_f32_16x16x32_bf16 v[12:15], v[136:139], v[168:171], v[12:15]
	v_mfma_f32_16x16x32_bf16 v[8:11], v[140:143], v[168:171], v[8:11]
	v_mfma_f32_16x16x32_bf16 v[4:7], v[136:139], v[172:175], v[4:7]
	v_mfma_f32_16x16x32_bf16 v[0:3], v[140:143], v[172:175], v[0:3]
	s_barrier
	v_lshl_add_u64 v[196:197], s[4:5], 0, v[212:213]
	s_mov_b32 m0, s34
	v_lshl_add_u64 v[128:129], v[196:197], 0, s[24:25]
	global_load_lds_dwordx4 v[128:129], off
	v_lshl_add_u64 v[128:129], v[196:197], 0, s[26:27]
	s_mov_b32 m0, s35
	s_nop 0
	global_load_lds_dwordx4 v[128:129], off
	s_waitcnt vmcnt(6)
	s_barrier
	v_mfma_f32_16x16x32_bf16 v[32:35], v[176:179], v[144:147], v[32:35]
	v_mfma_f32_16x16x32_bf16 v[36:39], v[180:183], v[144:147], v[36:39]
	v_mfma_f32_16x16x32_bf16 v[40:43], v[176:179], v[148:151], v[40:43]
	v_mfma_f32_16x16x32_bf16 v[44:47], v[180:183], v[148:151], v[44:47]
	v_mfma_f32_16x16x32_bf16 v[48:51], v[176:179], v[160:163], v[48:51]
	v_mfma_f32_16x16x32_bf16 v[52:55], v[180:183], v[160:163], v[52:55]
	v_mfma_f32_16x16x32_bf16 v[60:63], v[176:179], v[164:167], v[60:63]
	v_mfma_f32_16x16x32_bf16 v[64:67], v[180:183], v[164:167], v[64:67]
	v_mfma_f32_16x16x32_bf16 v[32:35], v[184:187], v[152:155], v[32:35]
	v_mfma_f32_16x16x32_bf16 v[36:39], v[188:191], v[152:155], v[36:39]
	v_mfma_f32_16x16x32_bf16 v[40:43], v[184:187], v[156:159], v[40:43]
	v_mfma_f32_16x16x32_bf16 v[44:47], v[188:191], v[156:159], v[44:47]
	v_mfma_f32_16x16x32_bf16 v[48:51], v[184:187], v[168:171], v[48:51]
	v_mfma_f32_16x16x32_bf16 v[52:55], v[188:191], v[168:171], v[52:55]
	v_mfma_f32_16x16x32_bf16 v[60:63], v[184:187], v[172:175], v[60:63]
	v_mfma_f32_16x16x32_bf16 v[64:67], v[188:191], v[172:175], v[64:67]
	s_barrier
	ds_read_b128 v[128:131], v228
	ds_read_b128 v[132:135], v228 offset:2048
	ds_read_b128 v[136:139], v229
	ds_read_b128 v[140:143], v229 offset:2048
	s_mov_b64 s[82:83], 0x80100
	s_mov_b32 m0, s42
	v_lshl_add_u64 v[176:177], v[192:193], 0, s[82:83]
	s_mov_b64 s[82:83], 0xc0100
	ds_read_b128 v[144:147], v224 offset:32768
	ds_read_b128 v[148:151], v224 offset:34816
	ds_read_b128 v[152:155], v225 offset:32768
	ds_read_b128 v[156:159], v225 offset:34816
	ds_read_b128 v[160:163], v224 offset:36864
	ds_read_b128 v[164:167], v224 offset:38912
	ds_read_b128 v[168:171], v225 offset:36864
	ds_read_b128 v[172:175], v225 offset:38912
	global_load_lds_dwordx4 v[176:177], off
	v_lshl_add_u64 v[176:177], v[192:193], 0, s[82:83]
	s_mov_b32 m0, s43
	s_nop 0
	global_load_lds_dwordx4 v[176:177], off
	s_waitcnt lgkmcnt(8)
	s_barrier
	s_waitcnt lgkmcnt(0)
	v_mfma_f32_16x16x32_bf16 v[124:127], v[128:131], v[144:147], v[124:127]
	v_mfma_f32_16x16x32_bf16 v[120:123], v[132:135], v[144:147], v[120:123]
	v_mfma_f32_16x16x32_bf16 v[116:119], v[128:131], v[148:151], v[116:119]
	v_mfma_f32_16x16x32_bf16 v[112:115], v[132:135], v[148:151], v[112:115]
	v_mfma_f32_16x16x32_bf16 v[108:111], v[128:131], v[160:163], v[108:111]
	v_mfma_f32_16x16x32_bf16 v[104:107], v[132:135], v[160:163], v[104:107]
	v_mfma_f32_16x16x32_bf16 v[100:103], v[128:131], v[164:167], v[100:103]
	v_mfma_f32_16x16x32_bf16 v[96:99], v[132:135], v[164:167], v[96:99]
	v_mfma_f32_16x16x32_bf16 v[124:127], v[136:139], v[152:155], v[124:127]
	v_mfma_f32_16x16x32_bf16 v[120:123], v[140:143], v[152:155], v[120:123]
	v_mfma_f32_16x16x32_bf16 v[116:119], v[136:139], v[156:159], v[116:119]
	v_mfma_f32_16x16x32_bf16 v[112:115], v[140:143], v[156:159], v[112:115]
	v_mfma_f32_16x16x32_bf16 v[108:111], v[136:139], v[168:171], v[108:111]
	v_mfma_f32_16x16x32_bf16 v[104:107], v[140:143], v[168:171], v[104:107]
	v_mfma_f32_16x16x32_bf16 v[100:103], v[136:139], v[172:175], v[100:103]
	v_mfma_f32_16x16x32_bf16 v[96:99], v[140:143], v[172:175], v[96:99]
	s_barrier
	s_mov_b32 m0, s44
	v_lshl_add_u64 v[198:199], v[194:195], 0, s[28:29]
	ds_read_b128 v[176:179], v232
	ds_read_b128 v[180:183], v232 offset:2048
	ds_read_b128 v[184:187], v233
	ds_read_b128 v[188:191], v233 offset:2048
	global_load_lds_dwordx4 v[198:199], off
	v_lshl_add_u64 v[194:195], v[194:195], 0, s[36:37]
	s_mov_b32 m0, s45
	s_nop 0
	global_load_lds_dwordx4 v[194:195], off
	s_barrier
	s_waitcnt lgkmcnt(0)
	v_mfma_f32_16x16x32_bf16 v[92:95], v[176:179], v[144:147], v[92:95]
	v_mfma_f32_16x16x32_bf16 v[88:91], v[180:183], v[144:147], v[88:91]
	v_mfma_f32_16x16x32_bf16 v[84:87], v[176:179], v[148:151], v[84:87]
	v_mfma_f32_16x16x32_bf16 v[80:83], v[180:183], v[148:151], v[80:83]
	v_mfma_f32_16x16x32_bf16 v[76:79], v[176:179], v[160:163], v[76:79]
	v_mfma_f32_16x16x32_bf16 v[72:75], v[180:183], v[160:163], v[72:75]
	v_mfma_f32_16x16x32_bf16 v[68:71], v[176:179], v[164:167], v[68:71]
	v_mfma_f32_16x16x32_bf16 v[56:59], v[180:183], v[164:167], v[56:59]
	v_mfma_f32_16x16x32_bf16 v[92:95], v[184:187], v[152:155], v[92:95]
	v_mfma_f32_16x16x32_bf16 v[88:91], v[188:191], v[152:155], v[88:91]
	v_mfma_f32_16x16x32_bf16 v[84:87], v[184:187], v[156:159], v[84:87]
	v_mfma_f32_16x16x32_bf16 v[80:83], v[188:191], v[156:159], v[80:83]
	v_mfma_f32_16x16x32_bf16 v[76:79], v[184:187], v[168:171], v[76:79]
	v_mfma_f32_16x16x32_bf16 v[72:75], v[188:191], v[168:171], v[72:75]
	v_mfma_f32_16x16x32_bf16 v[68:71], v[184:187], v[172:175], v[68:71]
	v_mfma_f32_16x16x32_bf16 v[56:59], v[188:191], v[172:175], v[56:59]
	s_barrier
	s_mov_b32 m0, s46
	v_lshl_add_u64 v[194:195], v[192:193], 0, s[28:29]
	ds_read_b128 v[144:147], v224 offset:49152
	ds_read_b128 v[148:151], v224 offset:51200
	ds_read_b128 v[152:155], v225 offset:49152
	ds_read_b128 v[156:159], v225 offset:51200
	ds_read_b128 v[160:163], v224 offset:53248
	ds_read_b128 v[164:167], v224 offset:55296
	ds_read_b128 v[168:171], v225 offset:53248
	ds_read_b128 v[172:175], v225 offset:55296
	global_load_lds_dwordx4 v[194:195], off
	v_lshl_add_u64 v[192:193], v[192:193], 0, s[36:37]
	s_mov_b32 m0, s47
	s_nop 0
	global_load_lds_dwordx4 v[192:193], off
	s_barrier
; template <int K, int EPI, bool MIX = false>
; __device__ __forceinline__ void gemm_phase(const Params& p, const u16* __restrict__ A, const u16* __restrict__ Bt,
;                            const float* __restrict__ rs_in, float* __restrict__ ssq_out, float alpha, bool rev = false) {
;     ...
;     if constexpr (MIX) {
;       for (int t = 0; t < nt / 2; t += 2) KBODY(t);
	s_waitcnt lgkmcnt(0)
	v_mfma_f32_16x16x32_bf16 v[28:31], v[128:131], v[144:147], v[28:31]
	v_mfma_f32_16x16x32_bf16 v[24:27], v[132:135], v[144:147], v[24:27]
	v_mfma_f32_16x16x32_bf16 v[20:23], v[128:131], v[148:151], v[20:23]
	v_mfma_f32_16x16x32_bf16 v[16:19], v[132:135], v[148:151], v[16:19]
	v_mfma_f32_16x16x32_bf16 v[12:15], v[128:131], v[160:163], v[12:15]
	v_mfma_f32_16x16x32_bf16 v[8:11], v[132:135], v[160:163], v[8:11]
	v_mfma_f32_16x16x32_bf16 v[4:7], v[128:131], v[164:167], v[4:7]
	v_mfma_f32_16x16x32_bf16 v[0:3], v[132:135], v[164:167], v[0:3]
	v_mfma_f32_16x16x32_bf16 v[28:31], v[136:139], v[152:155], v[28:31]
	v_mfma_f32_16x16x32_bf16 v[24:27], v[140:143], v[152:155], v[24:27]
	v_mfma_f32_16x16x32_bf16 v[20:23], v[136:139], v[156:159], v[20:23]
	v_mfma_f32_16x16x32_bf16 v[16:19], v[140:143], v[156:159], v[16:19]
	v_mfma_f32_16x16x32_bf16 v[12:15], v[136:139], v[168:171], v[12:15]
	v_mfma_f32_16x16x32_bf16 v[8:11], v[140:143], v[168:171], v[8:11]
	v_mfma_f32_16x16x32_bf16 v[4:7], v[136:139], v[172:175], v[4:7]
	v_mfma_f32_16x16x32_bf16 v[0:3], v[140:143], v[172:175], v[0:3]
	s_barrier
	s_mov_b32 m0, s48
	v_lshl_add_u64 v[128:129], v[196:197], 0, s[28:29]
	global_load_lds_dwordx4 v[128:129], off
	v_lshl_add_u64 v[128:129], v[196:197], 0, s[36:37]
	s_mov_b32 m0, s49
	s_nop 0
	global_load_lds_dwordx4 v[128:129], off
	s_waitcnt vmcnt(6)
	s_barrier
	v_mfma_f32_16x16x32_bf16 v[32:35], v[176:179], v[144:147], v[32:35]
	v_mfma_f32_16x16x32_bf16 v[36:39], v[180:183], v[144:147], v[36:39]
	v_mfma_f32_16x16x32_bf16 v[40:43], v[176:179], v[148:151], v[40:43]
	v_mfma_f32_16x16x32_bf16 v[44:47], v[180:183], v[148:151], v[44:47]
	v_mfma_f32_16x16x32_bf16 v[48:51], v[176:179], v[160:163], v[48:51]
	v_mfma_f32_16x16x32_bf16 v[52:55], v[180:183], v[160:163], v[52:55]
	v_mfma_f32_16x16x32_bf16 v[60:63], v[176:179], v[164:167], v[60:63]
	v_mfma_f32_16x16x32_bf16 v[64:67], v[180:183], v[164:167], v[64:67]
	v_mfma_f32_16x16x32_bf16 v[32:35], v[184:187], v[152:155], v[32:35]
	v_mfma_f32_16x16x32_bf16 v[36:39], v[188:191], v[152:155], v[36:39]
	v_mfma_f32_16x16x32_bf16 v[40:43], v[184:187], v[156:159], v[40:43]
	v_mfma_f32_16x16x32_bf16 v[44:47], v[188:191], v[156:159], v[44:47]
	v_mfma_f32_16x16x32_bf16 v[48:51], v[184:187], v[168:171], v[48:51]
	v_mfma_f32_16x16x32_bf16 v[52:55], v[188:191], v[168:171], v[52:55]
	v_mfma_f32_16x16x32_bf16 v[60:63], v[184:187], v[172:175], v[60:63]
	v_mfma_f32_16x16x32_bf16 v[64:67], v[188:191], v[172:175], v[64:67]
	s_barrier
	s_add_i32 s81, s81, 2
	s_add_u32 s40, s40, 0x100
	s_addc_u32 s41, s41, 0
	s_add_u32 s38, s38, 0x100
	s_addc_u32 s39, s39, 0
	s_add_u32 s4, s4, 0x100
	s_addc_u32 s5, s5, 0
	s_cmp_lt_u32 s81, 28
	s_cbranch_scc1 .LBB0_89
; #define LDA(dst,b,h) _Pragma("unroll") for(int m=0;m<4;++m) _Pragma("unroll") for(int k=0;k<2;++k) \
;     dst[m][k]=*reinterpret_cast<const bf16x8*>(SA(b,h)+(wr*64+m*16)*128+koff[k])
; #define LDB(dst,b,h) _Pragma("unroll") for(int n=0;n<2;++n) _Pragma("unroll") for(int k=0;k<2;++k) \
;     dst[n][k]=*reinterpret_cast<const bf16x8*>(SB(b,h)+(wc*32+n*16)*128+koff[k])
; #define MMA(ai,bj,Af,Bf) do{__builtin_amdgcn_s_setprio(1); \
;     _Pragma("unroll") for(int m=0;m<4;++m) _Pragma("unroll") for(int n=0;n<2;++n) _Pragma("unroll") for(int k=0;k<2;++k) \
;       acc[ai][bj][m][n]=__builtin_amdgcn_mfma_f32_16x16x32_bf16(Bf[n][k],Af[m][k],acc[ai][bj][m][n],0,0,0); \
;     __builtin_amdgcn_s_setprio(0);}while(0)
; #define WAIT_L(n) asm volatile("s_waitcnt lgkmcnt(" #n ")":::"memory")
; #define BAR __builtin_amdgcn_s_barrier()
; #define SCHED __builtin_amdgcn_sched_barrier(0)
; #define STAGE_A(b,h,kt) do{ unsigned char* _d = SA(b,h) + wbase; \
;     if constexpr (BLK) { const char* _s = baseA + ((size_t)(h)*(K/64) + (kt)) * 16384; GLDS(_s + voa, _d); GLDS(_s + 8192 + voa, _d + 8192); } \
;     else { const char* _s = baseA + ((size_t)(h)*128*K + (kt)*64) * 2; GLDS(_s + voa, _d); GLDS(_s + (size_t)128*K + voa, _d + 8192); } }while(0)
; template <int K, int EPI, bool MIX = false>
; __device__ __forceinline__ void gemm_phase(const Params& p, const u16* __restrict__ A, const u16* __restrict__ Bt,
;                            const float* __restrict__ rs_in, float* __restrict__ ssq_out, float alpha, bool rev = false) {
;     ...
;     const int cpm = pm, cpn = pn;
;     float rsq[2][4];
;     if constexpr (EPI == EPI_SWIGLU || EPI == EPI_Z || MIX) {
;       const float* rsrc = MIX ? p.ssqb : rs_in;
;       int fr_p = fr;
;       asm volatile("" : "+v"(fr_p));
; #pragma unroll
;       for (int ai = 0; ai < 2; ++ai)
; #pragma unroll
;         for (int m = 0; m < 4; ++m) rsq[ai][m] = rsrc[cpm * 256 + ai * 128 + wr * 64 + m * 16 + fr_p];
;     }
;     ++it;
;     id = item_id(it);
;     const bool more = id < ntiles;
;     if (rev) id = ntiles - 1 - id;
;     {
;       LDB(B0,0,0); SCHED; LDA(At,0,0); STAGE_A(1,1,nt-1);
;       WAIT_L(8); BAR; WAIT_L(0); MMA(0,0,At,B0); BAR; SCHED;
;       if (more) SETUP_TILE();
	v_mov_b32_e32 v128, v221
	s_lshl_b32 s41, s23, 8
	s_add_i32 s41, s41, s50
	v_add_u32_e32 v128, s41, v128
	v_readlane_b32 s52, v254, 32
	v_ashrrev_i32_e32 v129, 31, v128
	v_readlane_b32 s62, v254, 42
	v_readlane_b32 s63, v254, 43
	s_add_i32 s79, s79, 1
	s_mul_i32 s4, s79, s76
	v_lshl_add_u64 v[128:129], v[128:129], 2, s[62:63]
	global_load_dword v210, v[128:129], off
	global_load_dword v241, v[128:129], off offset:64
	global_load_dword v240, v[128:129], off offset:128
	global_load_dword v239, v[128:129], off offset:192
	global_load_dword v238, v[128:129], off offset:512
	global_load_dword v237, v[128:129], off offset:576
	global_load_dword v236, v[128:129], off offset:640
	global_load_dword v235, v[128:129], off offset:704
	ds_read_b128 v[144:147], v222
	ds_read_b128 v[148:151], v222 offset:2048
	ds_read_b128 v[156:159], v223
	ds_read_b128 v[152:155], v223 offset:2048
	s_add_i32 s4, s4, s77
	v_readlane_b32 s53, v254, 33
	v_readlane_b32 s54, v254, 34
	v_readlane_b32 s55, v254, 35
	v_readlane_b32 s56, v254, 36
	v_readlane_b32 s57, v254, 37
	v_readlane_b32 s58, v254, 38
	v_readlane_b32 s59, v254, 39
	v_readlane_b32 s60, v254, 40
	v_readlane_b32 s61, v254, 41
	v_readlane_b32 s64, v254, 44
	v_readlane_b32 s65, v254, 45
	v_readlane_b32 s66, v254, 46
	v_readlane_b32 s67, v254, 47
	v_lshl_add_u64 v[128:129], s[0:1], 0, v[208:209]
	s_mov_b64 s[38:39], 0x80f80
	s_mov_b32 m0, s74
	v_lshl_add_u64 v[130:131], v[128:129], 0, s[38:39]
	s_mov_b64 s[38:39], 0xc0f80
	ds_read_b128 v[160:163], v224
	ds_read_b128 v[164:167], v224 offset:2048
	ds_read_b128 v[188:191], v225
	ds_read_b128 v[180:183], v225 offset:2048
	ds_read_b128 v[168:171], v224 offset:4096
	ds_read_b128 v[172:175], v224 offset:6144
	ds_read_b128 v[184:187], v225 offset:4096
	ds_read_b128 v[176:179], v225 offset:6144
	global_load_lds_dwordx4 v[130:131], off
	v_lshl_add_u64 v[128:129], v[128:129], 0, s[38:39]
	s_mov_b32 m0, s75
	s_nop 0
	global_load_lds_dwordx4 v[128:129], off
	s_waitcnt lgkmcnt(8)
	s_barrier
	s_waitcnt lgkmcnt(0)
	v_mfma_f32_16x16x32_bf16 v[124:127], v[144:147], v[160:163], v[124:127]
	s_cmpk_lt_i32 s4, 0x2100
	s_cselect_b64 s[38:39], -1, 0
	s_cmpk_gt_i32 s4, 0x20ff
	v_mfma_f32_16x16x32_bf16 v[120:123], v[148:151], v[160:163], v[120:123]
	v_mfma_f32_16x16x32_bf16 v[116:119], v[144:147], v[164:167], v[116:119]
	v_mfma_f32_16x16x32_bf16 v[112:115], v[148:151], v[164:167], v[112:115]
	v_mfma_f32_16x16x32_bf16 v[108:111], v[144:147], v[168:171], v[108:111]
	v_mfma_f32_16x16x32_bf16 v[104:107], v[148:151], v[168:171], v[104:107]
	v_mfma_f32_16x16x32_bf16 v[100:103], v[144:147], v[172:175], v[100:103]
	v_mfma_f32_16x16x32_bf16 v[96:99], v[148:151], v[172:175], v[96:99]
	v_mfma_f32_16x16x32_bf16 v[124:127], v[156:159], v[188:191], v[124:127]
	v_mfma_f32_16x16x32_bf16 v[128:131], v[152:155], v[188:191], v[120:123]
	v_mfma_f32_16x16x32_bf16 v[116:119], v[156:159], v[180:183], v[116:119]
	v_mfma_f32_16x16x32_bf16 v[132:135], v[152:155], v[180:183], v[112:115]
	v_mfma_f32_16x16x32_bf16 v[108:111], v[156:159], v[184:187], v[108:111]
	v_mfma_f32_16x16x32_bf16 v[136:139], v[152:155], v[184:187], v[104:107]
	v_mfma_f32_16x16x32_bf16 v[100:103], v[156:159], v[176:179], v[100:103]
	v_mfma_f32_16x16x32_bf16 v[140:143], v[152:155], v[176:179], v[96:99]
	s_barrier
	s_mov_b32 s40, s80
	s_cbranch_scc1 .LBB0_92
	s_mul_hi_i32 s0, s4, 0x2e8ba2e9
	s_lshr_b32 s1, s0, 31
	s_ashr_i32 s0, s0, 6
	s_add_i32 s0, s0, s1
	s_lshl_b32 s1, s0, 3
	s_mulk_i32 s0, 0xfea0
	s_add_i32 s0, s0, s4
	s_and_b32 s4, s4, 7
	s_or_b32 s23, s1, s4
	s_ashr_i32 s40, s0, 3
	s_lshl_b32 s0, s23, 8
	s_ashr_i32 s1, s0, 31
	s_lshl_b64 s[0:1], s[0:1], 12
	s_add_u32 s0, s90, s0
	s_addc_u32 s1, s91, s1
	s_lshl_b32 s4, s40, 7
	s_ashr_i32 s5, s4, 31
	v_readlane_b32 s52, v254, 16
	s_lshl_b64 s[4:5], s[4:5], 12
	v_readlane_b32 s62, v254, 26
	v_readlane_b32 s63, v254, 27
	s_add_u32 s6, s62, s4
	s_addc_u32 s7, s63, s5
	s_add_u32 s8, s6, 0x1600000
	v_readlane_b32 s76, v255, 6
	s_addc_u32 s9, s7, 0
	v_readlane_b32 s53, v254, 17
	v_readlane_b32 s54, v254, 18
	v_readlane_b32 s55, v254, 19
	v_readlane_b32 s56, v254, 20
	v_readlane_b32 s57, v254, 21
	v_readlane_b32 s58, v254, 22
	v_readlane_b32 s59, v254, 23
	v_readlane_b32 s60, v254, 24
	v_readlane_b32 s61, v254, 25
	v_readlane_b32 s64, v254, 28
	v_readlane_b32 s65, v254, 29
	v_readlane_b32 s66, v254, 30
	v_readlane_b32 s67, v254, 31

; #define LDA(dst,b,h) _Pragma("unroll") for(int m=0;m<4;++m) _Pragma("unroll") for(int k=0;k<2;++k) \
;     dst[m][k]=*reinterpret_cast<const bf16x8*>(SA(b,h)+(wr*64+m*16)*128+koff[k])
; #define LDB(dst,b,h) _Pragma("unroll") for(int n=0;n<2;++n) _Pragma("unroll") for(int k=0;k<2;++k) \
;     dst[n][k]=*reinterpret_cast<const bf16x8*>(SB(b,h)+(wc*32+n*16)*128+koff[k])
; #define MMA(ai,bj,Af,Bf) do{__builtin_amdgcn_s_setprio(1); \
;     _Pragma("unroll") for(int m=0;m<4;++m) _Pragma("unroll") for(int n=0;n<2;++n) _Pragma("unroll") for(int k=0;k<2;++k) \
;       acc[ai][bj][m][n]=__builtin_amdgcn_mfma_f32_16x16x32_bf16(Bf[n][k],Af[m][k],acc[ai][bj][m][n],0,0,0); \
;     __builtin_amdgcn_s_setprio(0);}while(0)
; #define WAIT_V(n) asm volatile("s_waitcnt vmcnt(" #n ")":::"memory")
; #define WAIT_L(n) asm volatile("s_waitcnt lgkmcnt(" #n ")":::"memory")
; #define BAR __builtin_amdgcn_s_barrier()
; #define SCHED __builtin_amdgcn_sched_barrier(0)
; #define STAGE_A(b,h,kt) do{ unsigned char* _d = SA(b,h) + wbase; \
;     if constexpr (BLK) { const char* _s = baseA + ((size_t)(h)*(K/64) + (kt)) * 16384; GLDS(_s + voa, _d); GLDS(_s + 8192 + voa, _d + 8192); } \
;     else { const char* _s = baseA + ((size_t)(h)*128*K + (kt)*64) * 2; GLDS(_s + voa, _d); GLDS(_s + (size_t)128*K + voa, _d + 8192); } }while(0)
; #define STAGE_B(b,h,kt) do{ unsigned char* _d = SB(b,h) + wbase; \
;     if constexpr (BLK) { const char* _s = ((h)?baseB1:baseB0) + (size_t)(kt) * 16384; GLDS(_s + voa, _d); GLDS(_s + 8192 + voa, _d + 8192); } \
;     else { const char* _s = ((h)?baseB1:baseB0) + (kt)*128; GLDS(_s + voa, _d); GLDS(_s + (size_t)128*K + voa, _d + 8192); } }while(0)
; template <int K, int EPI, bool MIX = false>
; __device__ __forceinline__ void gemm_phase(const Params& p, const u16* __restrict__ A, const u16* __restrict__ Bt,
;                            const float* __restrict__ rs_in, float* __restrict__ ssq_out, float alpha, bool rev = false) {
;     ...
;       LDB(B1,0,1); if (more) STAGE_B(0,0,0);
;       BAR; WAIT_L(0); MMA(0,1,At,B1); BAR;
;       LDA(At,0,1); if (more) STAGE_A(0,0,0);
;       BAR; WAIT_L(0); MMA(1,0,At,B0); BAR; SCHED;
;       if (more) { STAGE_B(0,1,0); WAIT_V(6); } else { WAIT_V(0); }
.LBB0_94:
	s_barrier
	s_waitcnt lgkmcnt(0)
	v_mfma_f32_16x16x32_bf16 v[92:95], v[96:99], v[160:163], v[92:95]
	v_mfma_f32_16x16x32_bf16 v[88:91], v[104:107], v[160:163], v[88:91]
	v_mfma_f32_16x16x32_bf16 v[84:87], v[96:99], v[164:167], v[84:87]
	v_mfma_f32_16x16x32_bf16 v[80:83], v[104:107], v[164:167], v[80:83]
	v_mfma_f32_16x16x32_bf16 v[76:79], v[96:99], v[168:171], v[76:79]
	v_mfma_f32_16x16x32_bf16 v[72:75], v[104:107], v[168:171], v[72:75]
	v_mfma_f32_16x16x32_bf16 v[68:71], v[96:99], v[172:175], v[68:71]
	v_mfma_f32_16x16x32_bf16 v[56:59], v[104:107], v[172:175], v[56:59]
	v_mfma_f32_16x16x32_bf16 v[92:95], v[120:123], v[188:191], v[92:95]
	v_mfma_f32_16x16x32_bf16 v[160:163], v[112:115], v[188:191], v[88:91]
	v_mfma_f32_16x16x32_bf16 v[84:87], v[120:123], v[180:183], v[84:87]
	v_mfma_f32_16x16x32_bf16 v[164:167], v[112:115], v[180:183], v[80:83]
	v_mfma_f32_16x16x32_bf16 v[76:79], v[120:123], v[184:187], v[76:79]
	v_mfma_f32_16x16x32_bf16 v[168:171], v[112:115], v[184:187], v[72:75]
	v_mfma_f32_16x16x32_bf16 v[68:71], v[120:123], v[176:179], v[68:71]
	v_mfma_f32_16x16x32_bf16 v[56:59], v[112:115], v[176:179], v[56:59]
	s_barrier
	ds_read_b128 v[184:187], v224 offset:16384
	ds_read_b128 v[172:175], v224 offset:18432
	ds_read_b128 v[188:191], v225 offset:16384
	ds_read_b128 v[176:179], v225 offset:18432
	ds_read_b128 v[88:91], v224 offset:20480
	ds_read_b128 v[72:75], v224 offset:22528
	ds_read_b128 v[180:183], v225 offset:20480
	ds_read_b128 v[80:83], v225 offset:22528
	s_and_b64 vcc, exec, s[4:5]
	v_lshl_add_u64 v[216:217], s[0:1], 0, v[208:209]
	s_cbranch_vccnz .LBB0_96
	s_mov_b32 m0, s22
	v_lshl_add_u64 v[192:193], v[216:217], 0, s[2:3]
	global_load_lds_dwordx4 v[216:217], off
	s_mov_b32 m0, s33
	s_nop 0
	global_load_lds_dwordx4 v[192:193], off
.LBB0_96:
	s_barrier
	s_waitcnt lgkmcnt(0)
	v_mfma_f32_16x16x32_bf16 v[28:31], v[144:147], v[184:187], v[28:31]
	v_mfma_f32_16x16x32_bf16 v[24:27], v[148:151], v[184:187], v[24:27]
	v_mfma_f32_16x16x32_bf16 v[20:23], v[144:147], v[172:175], v[20:23]
	v_mfma_f32_16x16x32_bf16 v[16:19], v[148:151], v[172:175], v[16:19]
	v_mfma_f32_16x16x32_bf16 v[12:15], v[144:147], v[88:91], v[12:15]
	v_mfma_f32_16x16x32_bf16 v[8:11], v[148:151], v[88:91], v[8:11]
	v_mfma_f32_16x16x32_bf16 v[4:7], v[144:147], v[72:75], v[4:7]
	v_mfma_f32_16x16x32_bf16 v[0:3], v[148:151], v[72:75], v[0:3]
	v_mfma_f32_16x16x32_bf16 v[28:31], v[156:159], v[188:191], v[28:31]
	v_mfma_f32_16x16x32_bf16 v[24:27], v[152:155], v[188:191], v[24:27]
	v_mfma_f32_16x16x32_bf16 v[20:23], v[156:159], v[176:179], v[20:23]
	v_mfma_f32_16x16x32_bf16 v[16:19], v[152:155], v[176:179], v[16:19]
	v_mfma_f32_16x16x32_bf16 v[12:15], v[156:159], v[180:183], v[12:15]
	v_mfma_f32_16x16x32_bf16 v[8:11], v[152:155], v[180:183], v[8:11]
	v_mfma_f32_16x16x32_bf16 v[4:7], v[156:159], v[80:83], v[4:7]
	v_mfma_f32_16x16x32_bf16 v[0:3], v[152:155], v[80:83], v[0:3]
	s_barrier
	s_mov_b64 s[38:39], -1
	s_and_b64 vcc, exec, s[4:5]
	v_lshl_add_u64 v[214:215], s[8:9], 0, v[208:209]
	s_cbranch_vccnz .LBB0_98
	s_mov_b32 m0, s34
	v_lshl_add_u64 v[144:145], v[214:215], 0, s[2:3]
	global_load_lds_dwordx4 v[214:215], off
	s_mov_b32 m0, s35
	s_mov_b64 s[38:39], 0
	global_load_lds_dwordx4 v[144:145], off
	s_waitcnt vmcnt(6)

; #define LDA(dst,b,h) _Pragma("unroll") for(int m=0;m<4;++m) _Pragma("unroll") for(int k=0;k<2;++k) \
;     dst[m][k]=*reinterpret_cast<const bf16x8*>(SA(b,h)+(wr*64+m*16)*128+koff[k])
; #define LDB(dst,b,h) _Pragma("unroll") for(int n=0;n<2;++n) _Pragma("unroll") for(int k=0;k<2;++k) \
;     dst[n][k]=*reinterpret_cast<const bf16x8*>(SB(b,h)+(wc*32+n*16)*128+koff[k])
; #define MMA(ai,bj,Af,Bf) do{__builtin_amdgcn_s_setprio(1); \
;     _Pragma("unroll") for(int m=0;m<4;++m) _Pragma("unroll") for(int n=0;n<2;++n) _Pragma("unroll") for(int k=0;k<2;++k) \
;       acc[ai][bj][m][n]=__builtin_amdgcn_mfma_f32_16x16x32_bf16(Bf[n][k],Af[m][k],acc[ai][bj][m][n],0,0,0); \
;     __builtin_amdgcn_s_setprio(0);}while(0)
; #define WAIT_L(n) asm volatile("s_waitcnt lgkmcnt(" #n ")":::"memory")
; #define BAR __builtin_amdgcn_s_barrier()
; #define SCHED __builtin_amdgcn_sched_barrier(0)
; #define STAGE_A(b,h,kt) do{ unsigned char* _d = SA(b,h) + wbase; \
;     if constexpr (BLK) { const char* _s = baseA + ((size_t)(h)*(K/64) + (kt)) * 16384; GLDS(_s + voa, _d); GLDS(_s + 8192 + voa, _d + 8192); } \
;     else { const char* _s = baseA + ((size_t)(h)*128*K + (kt)*64) * 2; GLDS(_s + voa, _d); GLDS(_s + (size_t)128*K + voa, _d + 8192); } }while(0)
; #define STAGE_B(b,h,kt) do{ unsigned char* _d = SB(b,h) + wbase; \
;     if constexpr (BLK) { const char* _s = ((h)?baseB1:baseB0) + (size_t)(kt) * 16384; GLDS(_s + voa, _d); GLDS(_s + 8192 + voa, _d + 8192); } \
;     else { const char* _s = ((h)?baseB1:baseB0) + (kt)*128; GLDS(_s + voa, _d); GLDS(_s + (size_t)128*K + voa, _d + 8192); } }while(0)
; template <int K, int EPI, bool MIX = false>
; __device__ __forceinline__ void gemm_phase(const Params& p, const u16* __restrict__ A, const u16* __restrict__ Bt,
;                            const float* __restrict__ rs_in, float* __restrict__ ssq_out, float alpha, bool rev = false) {
;     ...
;       BAR; MMA(1,1,At,B1); BAR;
;       LDB(B0,1,0); SCHED; LDA(At,1,0); if (more) STAGE_A(0,1,0);
;       WAIT_L(8); BAR; WAIT_L(0); MMA(0,0,At,B0); BAR; SCHED;
;       LDB(B1,1,1); if (more) STAGE_B(1,0,1);
.LBB0_100:
	s_barrier
	v_mfma_f32_16x16x32_bf16 v[32:35], v[96:99], v[184:187], v[32:35]
	v_mfma_f32_16x16x32_bf16 v[144:147], v[120:123], v[188:191], v[32:35]
	v_mfma_f32_16x16x32_bf16 v[32:35], v[104:107], v[184:187], v[36:39]
	v_mfma_f32_16x16x32_bf16 v[36:39], v[112:115], v[188:191], v[32:35]
	v_mfma_f32_16x16x32_bf16 v[32:35], v[96:99], v[172:175], v[40:43]
	v_mfma_f32_16x16x32_bf16 v[148:151], v[120:123], v[176:179], v[32:35]
	v_mfma_f32_16x16x32_bf16 v[32:35], v[104:107], v[172:175], v[44:47]
	v_mfma_f32_16x16x32_bf16 v[152:155], v[112:115], v[176:179], v[32:35]
	v_mfma_f32_16x16x32_bf16 v[32:35], v[96:99], v[88:91], v[48:51]
	v_mfma_f32_16x16x32_bf16 v[156:159], v[120:123], v[180:183], v[32:35]
	v_mfma_f32_16x16x32_bf16 v[32:35], v[104:107], v[88:91], v[52:55]
	v_mfma_f32_16x16x32_bf16 v[172:175], v[112:115], v[180:183], v[32:35]
	v_mfma_f32_16x16x32_bf16 v[32:35], v[96:99], v[72:75], v[60:63]
	v_mfma_f32_16x16x32_bf16 v[176:179], v[120:123], v[80:83], v[32:35]
	v_mfma_f32_16x16x32_bf16 v[32:35], v[104:107], v[72:75], v[64:67]
	v_mfma_f32_16x16x32_bf16 v[180:183], v[112:115], v[80:83], v[32:35]
	s_barrier
	ds_read_b128 v[44:47], v228
	ds_read_b128 v[52:55], v228 offset:2048
	ds_read_b128 v[184:187], v229
	ds_read_b128 v[60:63], v229 offset:2048
	ds_read_b128 v[200:203], v224 offset:32768
	ds_read_b128 v[188:191], v224 offset:34816
	ds_read_b128 v[204:207], v225 offset:32768
	ds_read_b128 v[192:195], v225 offset:34816
	ds_read_b128 v[48:51], v224 offset:36864
	ds_read_b128 v[32:35], v224 offset:38912
	ds_read_b128 v[196:199], v225 offset:36864
	ds_read_b128 v[40:43], v225 offset:38912
	s_and_b64 vcc, exec, s[4:5]
	s_cbranch_vccnz .LBB0_102
	s_mov_b32 m0, s42
	v_lshl_add_u64 v[66:67], v[216:217], 0, s[10:11]
	v_lshl_add_u64 v[64:65], v[216:217], 0, s[12:13]
	global_load_lds_dwordx4 v[66:67], off
	s_mov_b32 m0, s43
	s_nop 0
	global_load_lds_dwordx4 v[64:65], off
.LBB0_102:
	s_waitcnt lgkmcnt(8)
	s_barrier
	s_waitcnt lgkmcnt(0)
	v_mfma_f32_16x16x32_bf16 v[64:67], v[44:47], v[200:203], v[124:127]
	v_mfma_f32_16x16x32_bf16 v[120:123], v[184:187], v[204:207], v[64:67]
	v_mfma_f32_16x16x32_bf16 v[64:67], v[52:55], v[200:203], v[128:131]
	v_mfma_f32_16x16x32_bf16 v[112:115], v[60:63], v[204:207], v[64:67]
	v_mfma_f32_16x16x32_bf16 v[64:67], v[44:47], v[188:191], v[116:119]
	v_mfma_f32_16x16x32_bf16 v[104:107], v[184:187], v[192:195], v[64:67]
	v_mfma_f32_16x16x32_bf16 v[64:67], v[52:55], v[188:191], v[132:135]
	v_mfma_f32_16x16x32_bf16 v[96:99], v[60:63], v[192:195], v[64:67]
	v_mfma_f32_16x16x32_bf16 v[64:67], v[44:47], v[48:51], v[108:111]
	v_mfma_f32_16x16x32_bf16 v[88:91], v[184:187], v[196:199], v[64:67]
	v_mfma_f32_16x16x32_bf16 v[64:67], v[52:55], v[48:51], v[136:139]
	v_mfma_f32_16x16x32_bf16 v[80:83], v[60:63], v[196:199], v[64:67]
	v_mfma_f32_16x16x32_bf16 v[64:67], v[44:47], v[32:35], v[100:103]
	v_mfma_f32_16x16x32_bf16 v[72:75], v[184:187], v[40:43], v[64:67]
	v_mfma_f32_16x16x32_bf16 v[64:67], v[52:55], v[32:35], v[140:143]
	v_mfma_f32_16x16x32_bf16 v[64:67], v[60:63], v[40:43], v[64:67]
	s_barrier
	ds_read_b128 v[128:131], v232
	ds_read_b128 v[132:135], v232 offset:2048
	ds_read_b128 v[140:143], v233
	ds_read_b128 v[136:139], v233 offset:2048
	s_and_b64 vcc, exec, s[4:5]
	s_cbranch_vccnz .LBB0_104
	s_mov_b32 m0, s44
	v_lshl_add_u64 v[102:103], v[218:219], 0, s[14:15]
	v_lshl_add_u64 v[100:101], v[218:219], 0, s[16:17]
	global_load_lds_dwordx4 v[102:103], off
	s_mov_b32 m0, s45
	s_nop 0
	global_load_lds_dwordx4 v[100:101], off
; #define LDA(dst,b,h) _Pragma("unroll") for(int m=0;m<4;++m) _Pragma("unroll") for(int k=0;k<2;++k) \
;     dst[m][k]=*reinterpret_cast<const bf16x8*>(SA(b,h)+(wr*64+m*16)*128+koff[k])
; #define MMA(ai,bj,Af,Bf) do{__builtin_amdgcn_s_setprio(1); \
;     _Pragma("unroll") for(int m=0;m<4;++m) _Pragma("unroll") for(int n=0;n<2;++n) _Pragma("unroll") for(int k=0;k<2;++k) \
;       acc[ai][bj][m][n]=__builtin_amdgcn_mfma_f32_16x16x32_bf16(Bf[n][k],Af[m][k],acc[ai][bj][m][n],0,0,0); \
;     __builtin_amdgcn_s_setprio(0);}while(0)
; #define WAIT_V(n) asm volatile("s_waitcnt vmcnt(" #n ")":::"memory")
; #define WAIT_L(n) asm volatile("s_waitcnt lgkmcnt(" #n ")":::"memory")
; #define BAR __builtin_amdgcn_s_barrier()
; #define SCHED __builtin_amdgcn_sched_barrier(0)
; #define STAGE_A(b,h,kt) do{ unsigned char* _d = SA(b,h) + wbase; \
;     if constexpr (BLK) { const char* _s = baseA + ((size_t)(h)*(K/64) + (kt)) * 16384; GLDS(_s + voa, _d); GLDS(_s + 8192 + voa, _d + 8192); } \
;     else { const char* _s = baseA + ((size_t)(h)*128*K + (kt)*64) * 2; GLDS(_s + voa, _d); GLDS(_s + (size_t)128*K + voa, _d + 8192); } }while(0)
; #define STAGE_B(b,h,kt) do{ unsigned char* _d = SB(b,h) + wbase; \
;     if constexpr (BLK) { const char* _s = ((h)?baseB1:baseB0) + (size_t)(kt) * 16384; GLDS(_s + voa, _d); GLDS(_s + 8192 + voa, _d + 8192); } \
;     else { const char* _s = ((h)?baseB1:baseB0) + (kt)*128; GLDS(_s + voa, _d); GLDS(_s + (size_t)128*K + voa, _d + 8192); } }while(0)
; template <int K, int EPI, bool MIX = false>
; __device__ __forceinline__ void gemm_phase(const Params& p, const u16* __restrict__ A, const u16* __restrict__ Bt,
;                            const float* __restrict__ rs_in, float* __restrict__ ssq_out, float alpha, bool rev = false) {
;     ...
;       BAR; WAIT_L(0); MMA(0,1,At,B1); BAR;
;       LDA(At,1,1); if (more) STAGE_A(1,0,1);
;       BAR; WAIT_L(0); MMA(1,0,At,B0); BAR; SCHED;
;       if (more) { STAGE_B(1,1,1); WAIT_V(6); }
;       BAR; MMA(1,1,At,B1); BAR;
;       if (!more && wr == 0) BAR;
.LBB0_104:
	s_barrier
	s_waitcnt lgkmcnt(0)
	v_mfma_f32_16x16x32_bf16 v[84:87], v[128:131], v[188:191], v[84:87]
	v_mfma_f32_16x16x32_bf16 v[92:95], v[128:131], v[200:203], v[92:95]
	v_mfma_f32_16x16x32_bf16 v[108:111], v[140:143], v[192:195], v[84:87]
	v_mfma_f32_16x16x32_bf16 v[84:87], v[132:135], v[188:191], v[164:167]
	v_mfma_f32_16x16x32_bf16 v[76:79], v[128:131], v[48:51], v[76:79]
	v_mfma_f32_16x16x32_bf16 v[48:51], v[132:135], v[48:51], v[168:171]
	v_mfma_f32_16x16x32_bf16 v[124:127], v[140:143], v[204:207], v[92:95]
	v_mfma_f32_16x16x32_bf16 v[92:95], v[132:135], v[200:203], v[160:163]
	v_mfma_f32_16x16x32_bf16 v[100:103], v[136:139], v[192:195], v[84:87]
	v_mfma_f32_16x16x32_bf16 v[84:87], v[136:139], v[196:199], v[48:51]
	v_mfma_f32_16x16x32_bf16 v[48:51], v[128:131], v[32:35], v[68:71]
	v_mfma_f32_16x16x32_bf16 v[32:35], v[132:135], v[32:35], v[56:59]
	v_mfma_f32_16x16x32_bf16 v[116:119], v[136:139], v[204:207], v[92:95]
	v_mfma_f32_16x16x32_bf16 v[92:95], v[140:143], v[196:199], v[76:79]
	v_mfma_f32_16x16x32_bf16 v[76:79], v[140:143], v[40:43], v[48:51]
	v_mfma_f32_16x16x32_bf16 v[68:71], v[136:139], v[40:43], v[32:35]
	s_barrier
	ds_read_b128 v[200:203], v224 offset:49152
	ds_read_b128 v[188:191], v224 offset:51200
	ds_read_b128 v[204:207], v225 offset:49152
	ds_read_b128 v[192:195], v225 offset:51200
	ds_read_b128 v[168:171], v224 offset:53248
	ds_read_b128 v[160:163], v224 offset:55296
	ds_read_b128 v[196:199], v225 offset:53248
	ds_read_b128 v[164:167], v225 offset:55296
	s_and_b64 vcc, exec, s[4:5]
	s_cbranch_vccnz .LBB0_106
	s_mov_b32 m0, s46
	v_lshl_add_u64 v[34:35], v[216:217], 0, s[14:15]
	v_lshl_add_u64 v[32:33], v[216:217], 0, s[16:17]
	global_load_lds_dwordx4 v[34:35], off
	s_mov_b32 m0, s47
	s_nop 0
	global_load_lds_dwordx4 v[32:33], off
.LBB0_106:
	s_barrier
	s_waitcnt lgkmcnt(0)
	v_mfma_f32_16x16x32_bf16 v[28:31], v[44:47], v[200:203], v[28:31]
	v_mfma_f32_16x16x32_bf16 v[24:27], v[52:55], v[200:203], v[24:27]
	v_mfma_f32_16x16x32_bf16 v[20:23], v[44:47], v[188:191], v[20:23]
	v_mfma_f32_16x16x32_bf16 v[16:19], v[52:55], v[188:191], v[16:19]
	v_mfma_f32_16x16x32_bf16 v[12:15], v[44:47], v[168:171], v[12:15]
	v_mfma_f32_16x16x32_bf16 v[8:11], v[52:55], v[168:171], v[8:11]
	v_mfma_f32_16x16x32_bf16 v[4:7], v[44:47], v[160:163], v[4:7]
	v_mfma_f32_16x16x32_bf16 v[0:3], v[52:55], v[160:163], v[0:3]
	v_mfma_f32_16x16x32_bf16 v[56:59], v[184:187], v[204:207], v[28:31]
	v_mfma_f32_16x16x32_bf16 v[48:51], v[60:63], v[204:207], v[24:27]
	v_mfma_f32_16x16x32_bf16 v[40:43], v[184:187], v[192:195], v[20:23]
	v_mfma_f32_16x16x32_bf16 v[32:35], v[60:63], v[192:195], v[16:19]
	v_mfma_f32_16x16x32_bf16 v[24:27], v[184:187], v[196:199], v[12:15]
	v_mfma_f32_16x16x32_bf16 v[16:19], v[60:63], v[196:199], v[8:11]
	v_mfma_f32_16x16x32_bf16 v[8:11], v[184:187], v[164:167], v[4:7]
	v_mfma_f32_16x16x32_bf16 v[0:3], v[60:63], v[164:167], v[0:3]
	s_barrier
	s_and_b64 vcc, exec, s[4:5]
	s_mov_b64 s[38:39], s[18:19]
	s_cbranch_vccnz .LBB0_108
	s_mov_b32 m0, s48
	v_lshl_add_u64 v[6:7], v[214:215], 0, s[14:15]
	v_lshl_add_u64 v[4:5], v[214:215], 0, s[16:17]
	global_load_lds_dwordx4 v[6:7], off
	s_mov_b32 m0, s49
	s_mov_b64 s[38:39], 0
	global_load_lds_dwordx4 v[4:5], off
	s_waitcnt vmcnt(6)
.LBB0_108:
	s_barrier
	v_mfma_f32_16x16x32_bf16 v[4:7], v[128:131], v[200:203], v[144:147]
	v_mfma_f32_16x16x32_bf16 v[60:63], v[140:143], v[204:207], v[4:7]
	v_mfma_f32_16x16x32_bf16 v[4:7], v[132:135], v[200:203], v[36:39]
	v_mfma_f32_16x16x32_bf16 v[52:55], v[136:139], v[204:207], v[4:7]
	v_mfma_f32_16x16x32_bf16 v[4:7], v[128:131], v[188:191], v[148:151]
	v_mfma_f32_16x16x32_bf16 v[44:47], v[140:143], v[192:195], v[4:7]
	v_mfma_f32_16x16x32_bf16 v[4:7], v[132:135], v[188:191], v[152:155]
	v_mfma_f32_16x16x32_bf16 v[36:39], v[136:139], v[192:195], v[4:7]
	v_mfma_f32_16x16x32_bf16 v[4:7], v[128:131], v[168:171], v[156:159]
	v_mfma_f32_16x16x32_bf16 v[28:31], v[140:143], v[196:199], v[4:7]
	v_mfma_f32_16x16x32_bf16 v[4:7], v[132:135], v[168:171], v[172:175]
	v_mfma_f32_16x16x32_bf16 v[20:23], v[136:139], v[196:199], v[4:7]
	v_mfma_f32_16x16x32_bf16 v[4:7], v[128:131], v[160:163], v[176:179]
	v_mfma_f32_16x16x32_bf16 v[12:15], v[140:143], v[164:167], v[4:7]
	v_mfma_f32_16x16x32_bf16 v[4:7], v[132:135], v[160:163], v[180:183]
	v_mfma_f32_16x16x32_bf16 v[4:7], v[136:139], v[164:167], v[4:7]
	s_or_b64 vcc, s[4:5], s[18:19]
	s_cbranch_scc0 .Llate_p1_defer
	s_barrier

.Llate_p2_done:
.LBB0_128:
	ds_read_b128 v[128:131], v219
	ds_read_b128 v[132:135], v219 offset:2048
	ds_read_b128 v[136:139], v220
	ds_read_b128 v[140:143], v220 offset:2048
	v_lshl_add_u64 v[192:193], s[46:47], 0, v[210:211]
	s_mov_b32 m0, s74
	v_lshl_add_u64 v[176:177], v[192:193], 0, s[18:19]
	ds_read_b128 v[144:147], v221
	ds_read_b128 v[148:151], v221 offset:2048
	ds_read_b128 v[152:155], v222
	ds_read_b128 v[156:159], v222 offset:2048
	ds_read_b128 v[160:163], v221 offset:4096
	ds_read_b128 v[164:167], v221 offset:6144
	ds_read_b128 v[168:171], v222 offset:4096
	ds_read_b128 v[172:175], v222 offset:6144
	global_load_lds_dwordx4 v[176:177], off
	v_lshl_add_u64 v[176:177], v[192:193], 0, s[20:21]
	s_mov_b32 m0, s75
	s_nop 0
	global_load_lds_dwordx4 v[176:177], off
	s_waitcnt lgkmcnt(8)
	s_barrier
	s_waitcnt lgkmcnt(0)
	v_mfma_f32_16x16x32_bf16 v[124:127], v[128:131], v[144:147], v[124:127]
	v_mfma_f32_16x16x32_bf16 v[120:123], v[132:135], v[144:147], v[120:123]
	v_mfma_f32_16x16x32_bf16 v[116:119], v[128:131], v[148:151], v[116:119]
	v_mfma_f32_16x16x32_bf16 v[112:115], v[132:135], v[148:151], v[112:115]
	v_mfma_f32_16x16x32_bf16 v[108:111], v[128:131], v[160:163], v[108:111]
	v_mfma_f32_16x16x32_bf16 v[104:107], v[132:135], v[160:163], v[104:107]
	v_mfma_f32_16x16x32_bf16 v[100:103], v[128:131], v[164:167], v[100:103]
	v_mfma_f32_16x16x32_bf16 v[96:99], v[132:135], v[164:167], v[96:99]
	v_mfma_f32_16x16x32_bf16 v[124:127], v[136:139], v[152:155], v[124:127]
	v_mfma_f32_16x16x32_bf16 v[120:123], v[140:143], v[152:155], v[120:123]
	v_mfma_f32_16x16x32_bf16 v[116:119], v[136:139], v[156:159], v[116:119]
	v_mfma_f32_16x16x32_bf16 v[112:115], v[140:143], v[156:159], v[112:115]
	v_mfma_f32_16x16x32_bf16 v[108:111], v[136:139], v[168:171], v[108:111]
	v_mfma_f32_16x16x32_bf16 v[104:107], v[140:143], v[168:171], v[104:107]
	v_mfma_f32_16x16x32_bf16 v[100:103], v[136:139], v[172:175], v[100:103]
	v_mfma_f32_16x16x32_bf16 v[96:99], v[140:143], v[172:175], v[96:99]
	s_barrier
	v_lshl_add_u64 v[194:195], s[62:63], 0, v[210:211]
	s_mov_b32 m0, s23
	v_lshl_add_u64 v[196:197], v[194:195], 0, s[28:29]
	ds_read_b128 v[176:179], v223
	ds_read_b128 v[180:183], v223 offset:2048
	ds_read_b128 v[184:187], v224
	ds_read_b128 v[188:191], v224 offset:2048
	global_load_lds_dwordx4 v[196:197], off
	v_lshl_add_u64 v[196:197], v[194:195], 0, s[36:37]
	s_mov_b32 m0, s30
	s_nop 0
	global_load_lds_dwordx4 v[196:197], off
	s_barrier
	s_waitcnt lgkmcnt(0)
	v_mfma_f32_16x16x32_bf16 v[92:95], v[176:179], v[144:147], v[92:95]
	v_mfma_f32_16x16x32_bf16 v[88:91], v[180:183], v[144:147], v[88:91]
	v_mfma_f32_16x16x32_bf16 v[84:87], v[176:179], v[148:151], v[84:87]
	v_mfma_f32_16x16x32_bf16 v[80:83], v[180:183], v[148:151], v[80:83]
	v_mfma_f32_16x16x32_bf16 v[76:79], v[176:179], v[160:163], v[76:79]
	v_mfma_f32_16x16x32_bf16 v[72:75], v[180:183], v[160:163], v[72:75]
	v_mfma_f32_16x16x32_bf16 v[68:71], v[176:179], v[164:167], v[68:71]
	v_mfma_f32_16x16x32_bf16 v[64:67], v[180:183], v[164:167], v[64:67]
	v_mfma_f32_16x16x32_bf16 v[92:95], v[184:187], v[152:155], v[92:95]
	v_mfma_f32_16x16x32_bf16 v[88:91], v[188:191], v[152:155], v[88:91]
	v_mfma_f32_16x16x32_bf16 v[84:87], v[184:187], v[156:159], v[84:87]
	v_mfma_f32_16x16x32_bf16 v[80:83], v[188:191], v[156:159], v[80:83]
	v_mfma_f32_16x16x32_bf16 v[76:79], v[184:187], v[168:171], v[76:79]
	v_mfma_f32_16x16x32_bf16 v[72:75], v[188:191], v[168:171], v[72:75]
	v_mfma_f32_16x16x32_bf16 v[68:71], v[184:187], v[172:175], v[68:71]
	v_mfma_f32_16x16x32_bf16 v[64:67], v[188:191], v[172:175], v[64:67]
	s_barrier
	s_mov_b32 m0, s22
	v_lshl_add_u64 v[196:197], v[192:193], 0, s[28:29]
	ds_read_b128 v[144:147], v221 offset:16384
	ds_read_b128 v[148:151], v221 offset:18432
	ds_read_b128 v[152:155], v222 offset:16384
	ds_read_b128 v[156:159], v222 offset:18432
	ds_read_b128 v[160:163], v221 offset:20480
	ds_read_b128 v[164:167], v221 offset:22528
	ds_read_b128 v[168:171], v222 offset:20480
	ds_read_b128 v[172:175], v222 offset:22528
	global_load_lds_dwordx4 v[196:197], off
	v_lshl_add_u64 v[196:197], v[192:193], 0, s[36:37]
	s_mov_b32 m0, s31
	s_nop 0
	global_load_lds_dwordx4 v[196:197], off
	s_barrier
	s_waitcnt lgkmcnt(0)
	v_mfma_f32_16x16x32_bf16 v[60:63], v[128:131], v[144:147], v[60:63]
	v_mfma_f32_16x16x32_bf16 v[56:59], v[132:135], v[144:147], v[56:59]
	v_mfma_f32_16x16x32_bf16 v[52:55], v[128:131], v[148:151], v[52:55]
	v_mfma_f32_16x16x32_bf16 v[48:51], v[132:135], v[148:151], v[48:51]
	v_mfma_f32_16x16x32_bf16 v[44:47], v[128:131], v[160:163], v[44:47]
	v_mfma_f32_16x16x32_bf16 v[40:43], v[132:135], v[160:163], v[40:43]
	v_mfma_f32_16x16x32_bf16 v[36:39], v[128:131], v[164:167], v[36:39]
	v_mfma_f32_16x16x32_bf16 v[32:35], v[132:135], v[164:167], v[32:35]
	v_mfma_f32_16x16x32_bf16 v[60:63], v[136:139], v[152:155], v[60:63]
	v_mfma_f32_16x16x32_bf16 v[56:59], v[140:143], v[152:155], v[56:59]
	v_mfma_f32_16x16x32_bf16 v[52:55], v[136:139], v[156:159], v[52:55]
	v_mfma_f32_16x16x32_bf16 v[48:51], v[140:143], v[156:159], v[48:51]
	v_mfma_f32_16x16x32_bf16 v[44:47], v[136:139], v[168:171], v[44:47]
	v_mfma_f32_16x16x32_bf16 v[40:43], v[140:143], v[168:171], v[40:43]
	v_mfma_f32_16x16x32_bf16 v[36:39], v[136:139], v[172:175], v[36:39]
	v_mfma_f32_16x16x32_bf16 v[32:35], v[140:143], v[172:175], v[32:35]
	s_barrier
	v_lshl_add_u64 v[196:197], s[4:5], 0, v[210:211]
	s_mov_b32 m0, s33
	v_lshl_add_u64 v[128:129], v[196:197], 0, s[28:29]
	global_load_lds_dwordx4 v[128:129], off
	v_lshl_add_u64 v[128:129], v[196:197], 0, s[36:37]
	s_mov_b32 m0, s34
	s_nop 0
	global_load_lds_dwordx4 v[128:129], off
	s_waitcnt vmcnt(6)
	s_barrier
	v_mfma_f32_16x16x32_bf16 v[28:31], v[176:179], v[144:147], v[28:31]
	v_mfma_f32_16x16x32_bf16 v[24:27], v[180:183], v[144:147], v[24:27]
	v_mfma_f32_16x16x32_bf16 v[20:23], v[176:179], v[148:151], v[20:23]
	v_mfma_f32_16x16x32_bf16 v[16:19], v[180:183], v[148:151], v[16:19]
	v_mfma_f32_16x16x32_bf16 v[12:15], v[176:179], v[160:163], v[12:15]
	v_mfma_f32_16x16x32_bf16 v[8:11], v[180:183], v[160:163], v[8:11]
	v_mfma_f32_16x16x32_bf16 v[4:7], v[176:179], v[164:167], v[4:7]
	v_mfma_f32_16x16x32_bf16 v[0:3], v[180:183], v[164:167], v[0:3]
	v_mfma_f32_16x16x32_bf16 v[28:31], v[184:187], v[152:155], v[28:31]
	v_mfma_f32_16x16x32_bf16 v[24:27], v[188:191], v[152:155], v[24:27]
	v_mfma_f32_16x16x32_bf16 v[20:23], v[184:187], v[156:159], v[20:23]
	v_mfma_f32_16x16x32_bf16 v[16:19], v[188:191], v[156:159], v[16:19]
	v_mfma_f32_16x16x32_bf16 v[12:15], v[184:187], v[168:171], v[12:15]
	v_mfma_f32_16x16x32_bf16 v[8:11], v[188:191], v[168:171], v[8:11]
	v_mfma_f32_16x16x32_bf16 v[4:7], v[184:187], v[172:175], v[4:7]
	v_mfma_f32_16x16x32_bf16 v[0:3], v[188:191], v[172:175], v[0:3]
	s_barrier
	ds_read_b128 v[128:131], v225
	ds_read_b128 v[132:135], v225 offset:2048
	ds_read_b128 v[136:139], v226
	ds_read_b128 v[140:143], v226 offset:2048
	s_mov_b64 s[96:97], 0x168000
	s_mov_b32 m0, s35
	v_lshl_add_u64 v[176:177], v[192:193], 0, s[96:97]
	s_mov_b64 s[96:97], 0x16a000
	ds_read_b128 v[144:147], v221 offset:32768
	ds_read_b128 v[148:151], v221 offset:34816
	ds_read_b128 v[152:155], v222 offset:32768
	ds_read_b128 v[156:159], v222 offset:34816
	ds_read_b128 v[160:163], v221 offset:36864
	ds_read_b128 v[164:167], v221 offset:38912
	ds_read_b128 v[168:171], v222 offset:36864
	ds_read_b128 v[172:175], v222 offset:38912
	global_load_lds_dwordx4 v[176:177], off
	v_lshl_add_u64 v[176:177], v[192:193], 0, s[96:97]
	s_mov_b32 m0, s42
	s_nop 0
	global_load_lds_dwordx4 v[176:177], off
	s_waitcnt lgkmcnt(8)
	s_barrier
	s_waitcnt lgkmcnt(0)
	v_mfma_f32_16x16x32_bf16 v[124:127], v[128:131], v[144:147], v[124:127]
	v_mfma_f32_16x16x32_bf16 v[120:123], v[132:135], v[144:147], v[120:123]
	v_mfma_f32_16x16x32_bf16 v[116:119], v[128:131], v[148:151], v[116:119]
	v_mfma_f32_16x16x32_bf16 v[112:115], v[132:135], v[148:151], v[112:115]
	v_mfma_f32_16x16x32_bf16 v[108:111], v[128:131], v[160:163], v[108:111]
	v_mfma_f32_16x16x32_bf16 v[104:107], v[132:135], v[160:163], v[104:107]
	v_mfma_f32_16x16x32_bf16 v[100:103], v[128:131], v[164:167], v[100:103]
	v_mfma_f32_16x16x32_bf16 v[96:99], v[132:135], v[164:167], v[96:99]
	v_mfma_f32_16x16x32_bf16 v[124:127], v[136:139], v[152:155], v[124:127]
	v_mfma_f32_16x16x32_bf16 v[120:123], v[140:143], v[152:155], v[120:123]
	v_mfma_f32_16x16x32_bf16 v[116:119], v[136:139], v[156:159], v[116:119]
	v_mfma_f32_16x16x32_bf16 v[112:115], v[140:143], v[156:159], v[112:115]
	v_mfma_f32_16x16x32_bf16 v[108:111], v[136:139], v[168:171], v[108:111]
	v_mfma_f32_16x16x32_bf16 v[104:107], v[140:143], v[168:171], v[104:107]
	v_mfma_f32_16x16x32_bf16 v[100:103], v[136:139], v[172:175], v[100:103]
	v_mfma_f32_16x16x32_bf16 v[96:99], v[140:143], v[172:175], v[96:99]
	s_barrier
	s_mov_b32 m0, s43
	v_lshl_add_u64 v[198:199], v[194:195], 0, s[38:39]
	ds_read_b128 v[176:179], v227
	ds_read_b128 v[180:183], v227 offset:2048
	ds_read_b128 v[184:187], v228
	ds_read_b128 v[188:191], v228 offset:2048
	global_load_lds_dwordx4 v[198:199], off
	v_lshl_add_u64 v[194:195], v[194:195], 0, s[40:41]
	s_mov_b32 m0, s44
	s_nop 0
	global_load_lds_dwordx4 v[194:195], off
	s_barrier
	s_waitcnt lgkmcnt(0)
	v_mfma_f32_16x16x32_bf16 v[92:95], v[176:179], v[144:147], v[92:95]
	v_mfma_f32_16x16x32_bf16 v[88:91], v[180:183], v[144:147], v[88:91]
	v_mfma_f32_16x16x32_bf16 v[84:87], v[176:179], v[148:151], v[84:87]
	v_mfma_f32_16x16x32_bf16 v[80:83], v[180:183], v[148:151], v[80:83]
	v_mfma_f32_16x16x32_bf16 v[76:79], v[176:179], v[160:163], v[76:79]
	v_mfma_f32_16x16x32_bf16 v[72:75], v[180:183], v[160:163], v[72:75]
	v_mfma_f32_16x16x32_bf16 v[68:71], v[176:179], v[164:167], v[68:71]
	v_mfma_f32_16x16x32_bf16 v[64:67], v[180:183], v[164:167], v[64:67]
	v_mfma_f32_16x16x32_bf16 v[92:95], v[184:187], v[152:155], v[92:95]
	v_mfma_f32_16x16x32_bf16 v[88:91], v[188:191], v[152:155], v[88:91]
	v_mfma_f32_16x16x32_bf16 v[84:87], v[184:187], v[156:159], v[84:87]
	v_mfma_f32_16x16x32_bf16 v[80:83], v[188:191], v[156:159], v[80:83]
	v_mfma_f32_16x16x32_bf16 v[76:79], v[184:187], v[168:171], v[76:79]
	v_mfma_f32_16x16x32_bf16 v[72:75], v[188:191], v[168:171], v[72:75]
	v_mfma_f32_16x16x32_bf16 v[68:71], v[184:187], v[172:175], v[68:71]
	v_mfma_f32_16x16x32_bf16 v[64:67], v[188:191], v[172:175], v[64:67]
	s_barrier
	s_mov_b32 m0, s45
	v_lshl_add_u64 v[194:195], v[192:193], 0, s[38:39]
	ds_read_b128 v[144:147], v221 offset:49152
	ds_read_b128 v[148:151], v221 offset:51200
	ds_read_b128 v[152:155], v222 offset:49152
	ds_read_b128 v[156:159], v222 offset:51200
	ds_read_b128 v[160:163], v221 offset:53248
	ds_read_b128 v[164:167], v221 offset:55296
	ds_read_b128 v[168:171], v222 offset:53248
	ds_read_b128 v[172:175], v222 offset:55296
	global_load_lds_dwordx4 v[194:195], off
	v_lshl_add_u64 v[192:193], v[192:193], 0, s[40:41]
	s_mov_b32 m0, s48
	s_nop 0
	global_load_lds_dwordx4 v[192:193], off
	s_barrier
; #define LDA(dst,b,h) _Pragma("unroll") for(int m=0;m<4;++m) _Pragma("unroll") for(int k=0;k<2;++k) \
;     dst[m][k]=*reinterpret_cast<const bf16x8*>(SA(b,h)+(wr*64+m*16)*128+koff[k])
; #define LDB(dst,b,h) _Pragma("unroll") for(int n=0;n<2;++n) _Pragma("unroll") for(int k=0;k<2;++k) \
;     dst[n][k]=*reinterpret_cast<const bf16x8*>(SB(b,h)+(wc*32+n*16)*128+koff[k])
; #define MMA(ai,bj,Af,Bf) do{__builtin_amdgcn_s_setprio(1); \
;     _Pragma("unroll") for(int m=0;m<4;++m) _Pragma("unroll") for(int n=0;n<2;++n) _Pragma("unroll") for(int k=0;k<2;++k) \
;       acc[ai][bj][m][n]=__builtin_amdgcn_mfma_f32_16x16x32_bf16(Bf[n][k],Af[m][k],acc[ai][bj][m][n],0,0,0); \
;     __builtin_amdgcn_s_setprio(0);}while(0)
; #define WAIT_L(n) asm volatile("s_waitcnt lgkmcnt(" #n ")":::"memory")
; #define BAR __builtin_amdgcn_s_barrier()
; #define SCHED __builtin_amdgcn_sched_barrier(0)
; #define STAGE_A(b,h,kt) do{ unsigned char* _d = SA(b,h) + wbase; \
;     if constexpr (BLK) { const char* _s = baseA + ((size_t)(h)*(K/64) + (kt)) * 16384; GLDS(_s + voa, _d); GLDS(_s + 8192 + voa, _d + 8192); } \
;     else { const char* _s = baseA + ((size_t)(h)*128*K + (kt)*64) * 2; GLDS(_s + voa, _d); GLDS(_s + (size_t)128*K + voa, _d + 8192); } }while(0)
; template <int K, int EPI, bool MIX = false>
; __device__ __forceinline__ void gemm_phase(const Params& p, const u16* __restrict__ A, const u16* __restrict__ Bt,
;                            const float* __restrict__ rs_in, float* __restrict__ ssq_out, float alpha, bool rev = false) {
;     ...
;     if constexpr (MIX) {
;       for (int t = 0; t < nt / 2; t += 2) KBODY(t);
;     ...
;     id = item_id(it);
;     const bool more = id < ntiles;
;     if (rev) id = ntiles - 1 - id;
;     {
;       LDB(B0,0,0); SCHED; LDA(At,0,0); STAGE_A(1,1,nt-1);
;       WAIT_L(8); BAR; WAIT_L(0); MMA(0,0,At,B0); BAR; SCHED;
;       if (more) SETUP_TILE();
	s_waitcnt lgkmcnt(0)
	v_mfma_f32_16x16x32_bf16 v[60:63], v[128:131], v[144:147], v[60:63]
	v_mfma_f32_16x16x32_bf16 v[56:59], v[132:135], v[144:147], v[56:59]
	v_mfma_f32_16x16x32_bf16 v[52:55], v[128:131], v[148:151], v[52:55]
	v_mfma_f32_16x16x32_bf16 v[48:51], v[132:135], v[148:151], v[48:51]
	v_mfma_f32_16x16x32_bf16 v[44:47], v[128:131], v[160:163], v[44:47]
	v_mfma_f32_16x16x32_bf16 v[40:43], v[132:135], v[160:163], v[40:43]
	v_mfma_f32_16x16x32_bf16 v[36:39], v[128:131], v[164:167], v[36:39]
	v_mfma_f32_16x16x32_bf16 v[32:35], v[132:135], v[164:167], v[32:35]
	v_mfma_f32_16x16x32_bf16 v[60:63], v[136:139], v[152:155], v[60:63]
	v_mfma_f32_16x16x32_bf16 v[56:59], v[140:143], v[152:155], v[56:59]
	v_mfma_f32_16x16x32_bf16 v[52:55], v[136:139], v[156:159], v[52:55]
	v_mfma_f32_16x16x32_bf16 v[48:51], v[140:143], v[156:159], v[48:51]
	v_mfma_f32_16x16x32_bf16 v[44:47], v[136:139], v[168:171], v[44:47]
	v_mfma_f32_16x16x32_bf16 v[40:43], v[140:143], v[168:171], v[40:43]
	v_mfma_f32_16x16x32_bf16 v[36:39], v[136:139], v[172:175], v[36:39]
	v_mfma_f32_16x16x32_bf16 v[32:35], v[140:143], v[172:175], v[32:35]
	s_barrier
	s_mov_b32 m0, s49
	v_lshl_add_u64 v[128:129], v[196:197], 0, s[38:39]
	global_load_lds_dwordx4 v[128:129], off
	v_lshl_add_u64 v[128:129], v[196:197], 0, s[40:41]
	s_mov_b32 m0, s50
	s_nop 0
	global_load_lds_dwordx4 v[128:129], off
	s_waitcnt vmcnt(6)
	s_barrier
	v_mfma_f32_16x16x32_bf16 v[28:31], v[176:179], v[144:147], v[28:31]
	v_mfma_f32_16x16x32_bf16 v[24:27], v[180:183], v[144:147], v[24:27]
	v_mfma_f32_16x16x32_bf16 v[20:23], v[176:179], v[148:151], v[20:23]
	v_mfma_f32_16x16x32_bf16 v[16:19], v[180:183], v[148:151], v[16:19]
	v_mfma_f32_16x16x32_bf16 v[12:15], v[176:179], v[160:163], v[12:15]
	v_mfma_f32_16x16x32_bf16 v[8:11], v[180:183], v[160:163], v[8:11]
	v_mfma_f32_16x16x32_bf16 v[4:7], v[176:179], v[164:167], v[4:7]
	v_mfma_f32_16x16x32_bf16 v[0:3], v[180:183], v[164:167], v[0:3]
	v_mfma_f32_16x16x32_bf16 v[28:31], v[184:187], v[152:155], v[28:31]
	v_mfma_f32_16x16x32_bf16 v[24:27], v[188:191], v[152:155], v[24:27]
	v_mfma_f32_16x16x32_bf16 v[20:23], v[184:187], v[156:159], v[20:23]
	v_mfma_f32_16x16x32_bf16 v[16:19], v[188:191], v[156:159], v[16:19]
	v_mfma_f32_16x16x32_bf16 v[12:15], v[184:187], v[168:171], v[12:15]
	v_mfma_f32_16x16x32_bf16 v[8:11], v[188:191], v[168:171], v[8:11]
	v_mfma_f32_16x16x32_bf16 v[4:7], v[184:187], v[172:175], v[4:7]
	v_mfma_f32_16x16x32_bf16 v[0:3], v[188:191], v[172:175], v[0:3]
	s_barrier
	s_add_i32 s79, s79, 2
	s_add_u32 s62, s62, 0x8000
	s_addc_u32 s63, s63, 0
	s_add_u32 s46, s46, 0x8000
	s_addc_u32 s47, s47, 0
	s_add_u32 s4, s4, 0x8000
	s_addc_u32 s5, s5, 0
	s_cmpk_lt_u32 s79, 0x54
	s_cbranch_scc1 .LBB0_128
	ds_read_b128 v[136:139], v219
	ds_read_b128 v[140:143], v219 offset:2048
	ds_read_b128 v[148:151], v220
	ds_read_b128 v[144:147], v220 offset:2048
	s_add_i32 s78, s78, 1
	s_mul_i32 s4, s78, s76
	s_add_i32 s4, s4, s77
	s_cmpk_lt_i32 s4, 0x600
	s_cselect_b64 s[46:47], -1, 0
	s_cmpk_gt_i32 s4, 0x5ff
	v_lshl_add_u64 v[128:129], s[2:3], 0, v[208:209]
	s_mov_b64 s[62:63], 0x2bc000
	s_mov_b32 m0, s74
	v_lshl_add_u64 v[130:131], v[128:129], 0, s[62:63]
	s_mov_b64 s[62:63], 0x2be000
	ds_read_b128 v[156:159], v221
	ds_read_b128 v[160:163], v221 offset:2048
	ds_read_b128 v[184:187], v222
	ds_read_b128 v[176:179], v222 offset:2048
	ds_read_b128 v[164:167], v221 offset:4096
	ds_read_b128 v[168:171], v221 offset:6144
	ds_read_b128 v[180:183], v222 offset:4096
	ds_read_b128 v[172:175], v222 offset:6144
	global_load_lds_dwordx4 v[130:131], off
	v_lshl_add_u64 v[128:129], v[128:129], 0, s[62:63]
	s_mov_b32 m0, s75
	s_nop 0
	global_load_lds_dwordx4 v[128:129], off
	s_waitcnt lgkmcnt(8)
	s_barrier
	s_waitcnt lgkmcnt(0)
	v_mfma_f32_16x16x32_bf16 v[124:127], v[136:139], v[156:159], v[124:127]
	v_mfma_f32_16x16x32_bf16 v[120:123], v[140:143], v[156:159], v[120:123]
	v_mfma_f32_16x16x32_bf16 v[116:119], v[136:139], v[160:163], v[116:119]
	v_mfma_f32_16x16x32_bf16 v[112:115], v[140:143], v[160:163], v[112:115]
	v_mfma_f32_16x16x32_bf16 v[108:111], v[136:139], v[164:167], v[108:111]
	v_mfma_f32_16x16x32_bf16 v[104:107], v[140:143], v[164:167], v[104:107]
	v_mfma_f32_16x16x32_bf16 v[100:103], v[136:139], v[168:171], v[100:103]
	v_mfma_f32_16x16x32_bf16 v[96:99], v[140:143], v[168:171], v[96:99]
	v_mfma_f32_16x16x32_bf16 v[124:127], v[148:151], v[184:187], v[124:127]
	v_mfma_f32_16x16x32_bf16 v[120:123], v[144:147], v[184:187], v[120:123]
	v_mfma_f32_16x16x32_bf16 v[116:119], v[148:151], v[176:179], v[116:119]
	v_mfma_f32_16x16x32_bf16 v[112:115], v[144:147], v[176:179], v[112:115]
	v_mfma_f32_16x16x32_bf16 v[128:131], v[148:151], v[180:183], v[108:111]
	v_mfma_f32_16x16x32_bf16 v[132:135], v[144:147], v[180:183], v[104:107]
	v_mfma_f32_16x16x32_bf16 v[100:103], v[148:151], v[172:175], v[100:103]
	v_mfma_f32_16x16x32_bf16 v[96:99], v[144:147], v[172:175], v[96:99]
	s_barrier
	s_mov_b32 s79, s81
	s_mov_b32 s80, s82
	s_cbranch_scc1 .LBB0_131
	s_sub_i32 s2, 0x5ff, s4
	s_lshr_b32 s3, s2, 3
	s_and_b32 s3, s3, 0x1ffffff8
	s_lshl_b32 s4, s3, 3
	s_sub_i32 s4, s2, s4
	s_and_b32 s2, s2, 7
	s_or_b32 s80, s3, s2
	s_ashr_i32 s79, s4, 3
	s_lshl_b32 s2, s80, 1
	s_mul_i32 s3, s80, 0x2c0000
	v_readlane_b32 s52, v254, 16
	s_mul_hi_u32 s4, s2, 0x160000
	s_add_u32 s2, s92, s3
	v_readlane_b32 s60, v254, 24
	v_readlane_b32 s61, v254, 25
	v_readlane_b32 s62, v254, 26
	v_readlane_b32 s63, v254, 27
	v_readlane_b32 s64, v254, 28
	v_readlane_b32 s65, v254, 29
	s_addc_u32 s3, s93, s4
	s_lshl_b32 s4, s79, 1
	s_mul_i32 s5, s79, 0x2c0000
	v_readlane_b32 s66, v254, 30
	v_readlane_b32 s67, v254, 31
	s_mov_b64 s[60:61], s[64:65]
	s_mul_hi_i32 s4, s4, 0x160000
	s_add_u32 s8, s60, s5
	s_addc_u32 s9, s61, s4
	s_add_u32 s10, s8, 0x160000
	v_readlane_b32 s76, v255, 6
	s_addc_u32 s11, s9, 0
	v_readlane_b32 s53, v254, 17
	v_readlane_b32 s54, v254, 18
	v_readlane_b32 s55, v254, 19
	v_readlane_b32 s56, v254, 20
	v_readlane_b32 s57, v254, 21
	v_readlane_b32 s58, v254, 22
	v_readlane_b32 s59, v254, 23
	s_mov_b64 s[62:63], s[66:67]

; #define LDA(dst,b,h) _Pragma("unroll") for(int m=0;m<4;++m) _Pragma("unroll") for(int k=0;k<2;++k) \
;     dst[m][k]=*reinterpret_cast<const bf16x8*>(SA(b,h)+(wr*64+m*16)*128+koff[k])
; #define LDB(dst,b,h) _Pragma("unroll") for(int n=0;n<2;++n) _Pragma("unroll") for(int k=0;k<2;++k) \
;     dst[n][k]=*reinterpret_cast<const bf16x8*>(SB(b,h)+(wc*32+n*16)*128+koff[k])
; #define MMA(ai,bj,Af,Bf) do{__builtin_amdgcn_s_setprio(1); \
;     _Pragma("unroll") for(int m=0;m<4;++m) _Pragma("unroll") for(int n=0;n<2;++n) _Pragma("unroll") for(int k=0;k<2;++k) \
;       acc[ai][bj][m][n]=__builtin_amdgcn_mfma_f32_16x16x32_bf16(Bf[n][k],Af[m][k],acc[ai][bj][m][n],0,0,0); \
;     __builtin_amdgcn_s_setprio(0);}while(0)
; #define WAIT_V(n) asm volatile("s_waitcnt vmcnt(" #n ")":::"memory")
; #define WAIT_L(n) asm volatile("s_waitcnt lgkmcnt(" #n ")":::"memory")
; #define BAR __builtin_amdgcn_s_barrier()
; #define SCHED __builtin_amdgcn_sched_barrier(0)
; #define STAGE_A(b,h,kt) do{ unsigned char* _d = SA(b,h) + wbase; \
;     if constexpr (BLK) { const char* _s = baseA + ((size_t)(h)*(K/64) + (kt)) * 16384; GLDS(_s + voa, _d); GLDS(_s + 8192 + voa, _d + 8192); } \
;     else { const char* _s = baseA + ((size_t)(h)*128*K + (kt)*64) * 2; GLDS(_s + voa, _d); GLDS(_s + (size_t)128*K + voa, _d + 8192); } }while(0)
; #define STAGE_B(b,h,kt) do{ unsigned char* _d = SB(b,h) + wbase; \
;     if constexpr (BLK) { const char* _s = ((h)?baseB1:baseB0) + (size_t)(kt) * 16384; GLDS(_s + voa, _d); GLDS(_s + 8192 + voa, _d + 8192); } \
;     else { const char* _s = ((h)?baseB1:baseB0) + (kt)*128; GLDS(_s + voa, _d); GLDS(_s + (size_t)128*K + voa, _d + 8192); } }while(0)
; template <int K, int EPI, bool MIX = false>
; __device__ __forceinline__ void gemm_phase(const Params& p, const u16* __restrict__ A, const u16* __restrict__ Bt,
;                            const float* __restrict__ rs_in, float* __restrict__ ssq_out, float alpha, bool rev = false) {
;     ...
;       LDB(B1,0,1); if (more) STAGE_B(0,0,0);
;       BAR; WAIT_L(0); MMA(0,1,At,B1); BAR;
;       LDA(At,0,1); if (more) STAGE_A(0,0,0);
;       BAR; WAIT_L(0); MMA(1,0,At,B0); BAR; SCHED;
;       if (more) { STAGE_B(0,1,0); WAIT_V(6); } else { WAIT_V(0); }
.LBB0_133:
	s_barrier
	s_waitcnt lgkmcnt(0)
	v_mfma_f32_16x16x32_bf16 v[92:95], v[104:107], v[156:159], v[92:95]
	v_mfma_f32_16x16x32_bf16 v[88:91], v[108:111], v[156:159], v[88:91]
	v_mfma_f32_16x16x32_bf16 v[84:87], v[104:107], v[160:163], v[84:87]
	v_mfma_f32_16x16x32_bf16 v[80:83], v[108:111], v[160:163], v[80:83]
	v_mfma_f32_16x16x32_bf16 v[76:79], v[104:107], v[164:167], v[76:79]
	v_mfma_f32_16x16x32_bf16 v[72:75], v[108:111], v[164:167], v[72:75]
	v_mfma_f32_16x16x32_bf16 v[68:71], v[104:107], v[168:171], v[68:71]
	v_mfma_f32_16x16x32_bf16 v[64:67], v[108:111], v[168:171], v[64:67]
	v_mfma_f32_16x16x32_bf16 v[152:155], v[192:195], v[184:187], v[92:95]
	v_mfma_f32_16x16x32_bf16 v[156:159], v[188:191], v[184:187], v[88:91]
	v_mfma_f32_16x16x32_bf16 v[84:87], v[192:195], v[176:179], v[84:87]
	v_mfma_f32_16x16x32_bf16 v[80:83], v[188:191], v[176:179], v[80:83]
	v_mfma_f32_16x16x32_bf16 v[160:163], v[192:195], v[180:183], v[76:79]
	v_mfma_f32_16x16x32_bf16 v[164:167], v[188:191], v[180:183], v[72:75]
	v_mfma_f32_16x16x32_bf16 v[68:71], v[192:195], v[172:175], v[68:71]
	v_mfma_f32_16x16x32_bf16 v[64:67], v[188:191], v[172:175], v[64:67]
	s_barrier
	ds_read_b128 v[184:187], v221 offset:16384
	ds_read_b128 v[92:95], v221 offset:18432
	ds_read_b128 v[196:199], v222 offset:16384
	ds_read_b128 v[176:179], v222 offset:18432
	ds_read_b128 v[88:91], v221 offset:20480
	ds_read_b128 v[72:75], v221 offset:22528
	ds_read_b128 v[180:183], v222 offset:20480
	ds_read_b128 v[76:79], v222 offset:22528
	s_and_b64 vcc, exec, s[4:5]
	v_lshl_add_u64 v[214:215], s[2:3], 0, v[208:209]
	s_cbranch_vccnz .LBB0_135
	s_mov_b32 m0, s22
	v_lshl_add_u64 v[168:169], v[214:215], 0, s[6:7]
	global_load_lds_dwordx4 v[214:215], off
	s_mov_b32 m0, s31
	s_nop 0
	global_load_lds_dwordx4 v[168:169], off
.LBB0_135:
	s_barrier
	s_waitcnt lgkmcnt(0)
	v_mfma_f32_16x16x32_bf16 v[60:63], v[136:139], v[184:187], v[60:63]
	v_mfma_f32_16x16x32_bf16 v[56:59], v[140:143], v[184:187], v[56:59]
	v_mfma_f32_16x16x32_bf16 v[52:55], v[136:139], v[92:95], v[52:55]
	v_mfma_f32_16x16x32_bf16 v[48:51], v[140:143], v[92:95], v[48:51]
	v_mfma_f32_16x16x32_bf16 v[44:47], v[136:139], v[88:91], v[44:47]
	v_mfma_f32_16x16x32_bf16 v[40:43], v[140:143], v[88:91], v[40:43]
	v_mfma_f32_16x16x32_bf16 v[36:39], v[136:139], v[72:75], v[36:39]
	v_mfma_f32_16x16x32_bf16 v[32:35], v[140:143], v[72:75], v[32:35]
	v_mfma_f32_16x16x32_bf16 v[60:63], v[148:151], v[196:199], v[60:63]
	v_mfma_f32_16x16x32_bf16 v[56:59], v[144:147], v[196:199], v[56:59]
	v_mfma_f32_16x16x32_bf16 v[52:55], v[148:151], v[176:179], v[52:55]
	v_mfma_f32_16x16x32_bf16 v[48:51], v[144:147], v[176:179], v[48:51]
	v_mfma_f32_16x16x32_bf16 v[168:171], v[148:151], v[180:183], v[44:47]
	v_mfma_f32_16x16x32_bf16 v[172:175], v[144:147], v[180:183], v[40:43]
	v_mfma_f32_16x16x32_bf16 v[36:39], v[148:151], v[76:79], v[36:39]
	v_mfma_f32_16x16x32_bf16 v[32:35], v[144:147], v[76:79], v[32:35]
	s_barrier
	s_mov_b64 s[46:47], -1
	s_and_b64 vcc, exec, s[4:5]
	v_lshl_add_u64 v[212:213], s[10:11], 0, v[208:209]
	s_cbranch_vccnz .LBB0_137
	s_mov_b32 m0, s33
	v_lshl_add_u64 v[40:41], v[212:213], 0, s[6:7]
	global_load_lds_dwordx4 v[212:213], off
	s_mov_b32 m0, s34
	s_mov_b64 s[46:47], 0
	global_load_lds_dwordx4 v[40:41], off
	s_waitcnt vmcnt(6)

; #define LDA(dst,b,h) _Pragma("unroll") for(int m=0;m<4;++m) _Pragma("unroll") for(int k=0;k<2;++k) \
;     dst[m][k]=*reinterpret_cast<const bf16x8*>(SA(b,h)+(wr*64+m*16)*128+koff[k])
; #define LDB(dst,b,h) _Pragma("unroll") for(int n=0;n<2;++n) _Pragma("unroll") for(int k=0;k<2;++k) \
;     dst[n][k]=*reinterpret_cast<const bf16x8*>(SB(b,h)+(wc*32+n*16)*128+koff[k])
; #define MMA(ai,bj,Af,Bf) do{__builtin_amdgcn_s_setprio(1); \
;     _Pragma("unroll") for(int m=0;m<4;++m) _Pragma("unroll") for(int n=0;n<2;++n) _Pragma("unroll") for(int k=0;k<2;++k) \
;       acc[ai][bj][m][n]=__builtin_amdgcn_mfma_f32_16x16x32_bf16(Bf[n][k],Af[m][k],acc[ai][bj][m][n],0,0,0); \
;     __builtin_amdgcn_s_setprio(0);}while(0)
; #define WAIT_L(n) asm volatile("s_waitcnt lgkmcnt(" #n ")":::"memory")
; #define BAR __builtin_amdgcn_s_barrier()
; #define SCHED __builtin_amdgcn_sched_barrier(0)
; #define STAGE_A(b,h,kt) do{ unsigned char* _d = SA(b,h) + wbase; \
;     if constexpr (BLK) { const char* _s = baseA + ((size_t)(h)*(K/64) + (kt)) * 16384; GLDS(_s + voa, _d); GLDS(_s + 8192 + voa, _d + 8192); } \
;     else { const char* _s = baseA + ((size_t)(h)*128*K + (kt)*64) * 2; GLDS(_s + voa, _d); GLDS(_s + (size_t)128*K + voa, _d + 8192); } }while(0)
; #define STAGE_B(b,h,kt) do{ unsigned char* _d = SB(b,h) + wbase; \
;     if constexpr (BLK) { const char* _s = ((h)?baseB1:baseB0) + (size_t)(kt) * 16384; GLDS(_s + voa, _d); GLDS(_s + 8192 + voa, _d + 8192); } \
;     else { const char* _s = ((h)?baseB1:baseB0) + (kt)*128; GLDS(_s + voa, _d); GLDS(_s + (size_t)128*K + voa, _d + 8192); } }while(0)
; template <int K, int EPI, bool MIX = false>
; __device__ __forceinline__ void gemm_phase(const Params& p, const u16* __restrict__ A, const u16* __restrict__ Bt,
;                            const float* __restrict__ rs_in, float* __restrict__ ssq_out, float alpha, bool rev = false) {
;     ...
;       BAR; MMA(1,1,At,B1); BAR;
;       LDB(B0,1,0); SCHED; LDA(At,1,0); if (more) STAGE_A(0,1,0);
;       WAIT_L(8); BAR; WAIT_L(0); MMA(0,0,At,B0); BAR; SCHED;
;       LDB(B1,1,1); if (more) STAGE_B(1,0,1);
.LBB0_139:
	s_barrier
	v_mfma_f32_16x16x32_bf16 v[28:31], v[104:107], v[184:187], v[28:31]
	v_mfma_f32_16x16x32_bf16 v[24:27], v[108:111], v[184:187], v[24:27]
	v_mfma_f32_16x16x32_bf16 v[20:23], v[104:107], v[92:95], v[20:23]
	v_mfma_f32_16x16x32_bf16 v[16:19], v[108:111], v[92:95], v[16:19]
	v_mfma_f32_16x16x32_bf16 v[12:15], v[104:107], v[88:91], v[12:15]
	v_mfma_f32_16x16x32_bf16 v[8:11], v[108:111], v[88:91], v[8:11]
	v_mfma_f32_16x16x32_bf16 v[4:7], v[104:107], v[72:75], v[4:7]
	v_mfma_f32_16x16x32_bf16 v[0:3], v[108:111], v[72:75], v[0:3]
	v_mfma_f32_16x16x32_bf16 v[136:139], v[192:195], v[196:199], v[28:31]
	v_mfma_f32_16x16x32_bf16 v[140:143], v[188:191], v[196:199], v[24:27]
	v_mfma_f32_16x16x32_bf16 v[20:23], v[192:195], v[176:179], v[20:23]
	v_mfma_f32_16x16x32_bf16 v[16:19], v[188:191], v[176:179], v[16:19]
	v_mfma_f32_16x16x32_bf16 v[144:147], v[192:195], v[180:183], v[12:15]
	v_mfma_f32_16x16x32_bf16 v[148:151], v[188:191], v[180:183], v[8:11]
	v_mfma_f32_16x16x32_bf16 v[4:7], v[192:195], v[76:79], v[4:7]
	v_mfma_f32_16x16x32_bf16 v[0:3], v[188:191], v[76:79], v[0:3]
	s_barrier
	ds_read_b128 v[8:11], v225
	ds_read_b128 v[176:179], v225 offset:2048
	ds_read_b128 v[12:15], v226
	ds_read_b128 v[180:183], v226 offset:2048
	ds_read_b128 v[200:203], v221 offset:32768
	ds_read_b128 v[44:47], v221 offset:34816
	ds_read_b128 v[204:207], v222 offset:32768
	ds_read_b128 v[192:195], v222 offset:34816
	ds_read_b128 v[40:43], v221 offset:36864
	ds_read_b128 v[24:27], v221 offset:38912
	ds_read_b128 v[196:199], v222 offset:36864
	ds_read_b128 v[28:31], v222 offset:38912
	s_and_b64 vcc, exec, s[4:5]
	s_cbranch_vccnz .LBB0_141
	s_mov_b32 m0, s35
	v_lshl_add_u64 v[74:75], v[214:215], 0, s[0:1]
	v_lshl_add_u64 v[72:73], v[214:215], 0, s[12:13]
	global_load_lds_dwordx4 v[74:75], off
	s_mov_b32 m0, s42
	s_nop 0
	global_load_lds_dwordx4 v[72:73], off
.LBB0_141:
	s_waitcnt lgkmcnt(8)
	s_barrier
	s_waitcnt lgkmcnt(0)
	v_mfma_f32_16x16x32_bf16 v[72:75], v[8:11], v[200:203], v[124:127]
	v_mfma_f32_16x16x32_bf16 v[124:127], v[12:15], v[204:207], v[72:75]
	v_mfma_f32_16x16x32_bf16 v[72:75], v[176:179], v[200:203], v[120:123]
	v_mfma_f32_16x16x32_bf16 v[120:123], v[180:183], v[204:207], v[72:75]
	v_mfma_f32_16x16x32_bf16 v[72:75], v[8:11], v[44:47], v[116:119]
	v_mfma_f32_16x16x32_bf16 v[108:111], v[12:15], v[192:195], v[72:75]
	v_mfma_f32_16x16x32_bf16 v[72:75], v[176:179], v[44:47], v[112:115]
	v_mfma_f32_16x16x32_bf16 v[104:107], v[180:183], v[192:195], v[72:75]
	v_mfma_f32_16x16x32_bf16 v[72:75], v[8:11], v[40:43], v[128:131]
	v_mfma_f32_16x16x32_bf16 v[92:95], v[12:15], v[196:199], v[72:75]
	v_mfma_f32_16x16x32_bf16 v[72:75], v[176:179], v[40:43], v[132:135]
	v_mfma_f32_16x16x32_bf16 v[88:91], v[180:183], v[196:199], v[72:75]
	v_mfma_f32_16x16x32_bf16 v[72:75], v[8:11], v[24:27], v[100:103]
	v_mfma_f32_16x16x32_bf16 v[76:79], v[12:15], v[28:31], v[72:75]
	v_mfma_f32_16x16x32_bf16 v[72:75], v[176:179], v[24:27], v[96:99]
	v_mfma_f32_16x16x32_bf16 v[72:75], v[180:183], v[28:31], v[72:75]
	s_barrier
	ds_read_b128 v[128:131], v227
	ds_read_b128 v[132:135], v227 offset:2048
	ds_read_b128 v[188:191], v228
	ds_read_b128 v[184:187], v228 offset:2048
	s_and_b64 vcc, exec, s[4:5]
	s_cbranch_vccnz .LBB0_143
	s_mov_b32 m0, s43
	v_lshl_add_u64 v[98:99], v[216:217], 0, s[14:15]
	v_lshl_add_u64 v[96:97], v[216:217], 0, s[16:17]
	global_load_lds_dwordx4 v[98:99], off
	s_mov_b32 m0, s44
	s_nop 0
	global_load_lds_dwordx4 v[96:97], off
; #define LDA(dst,b,h) _Pragma("unroll") for(int m=0;m<4;++m) _Pragma("unroll") for(int k=0;k<2;++k) \
;     dst[m][k]=*reinterpret_cast<const bf16x8*>(SA(b,h)+(wr*64+m*16)*128+koff[k])
; #define MMA(ai,bj,Af,Bf) do{__builtin_amdgcn_s_setprio(1); \
;     _Pragma("unroll") for(int m=0;m<4;++m) _Pragma("unroll") for(int n=0;n<2;++n) _Pragma("unroll") for(int k=0;k<2;++k) \
;       acc[ai][bj][m][n]=__builtin_amdgcn_mfma_f32_16x16x32_bf16(Bf[n][k],Af[m][k],acc[ai][bj][m][n],0,0,0); \
;     __builtin_amdgcn_s_setprio(0);}while(0)
; #define WAIT_V(n) asm volatile("s_waitcnt vmcnt(" #n ")":::"memory")
; #define WAIT_L(n) asm volatile("s_waitcnt lgkmcnt(" #n ")":::"memory")
; #define BAR __builtin_amdgcn_s_barrier()
; #define SCHED __builtin_amdgcn_sched_barrier(0)
; #define STAGE_A(b,h,kt) do{ unsigned char* _d = SA(b,h) + wbase; \
;     if constexpr (BLK) { const char* _s = baseA + ((size_t)(h)*(K/64) + (kt)) * 16384; GLDS(_s + voa, _d); GLDS(_s + 8192 + voa, _d + 8192); } \
;     else { const char* _s = baseA + ((size_t)(h)*128*K + (kt)*64) * 2; GLDS(_s + voa, _d); GLDS(_s + (size_t)128*K + voa, _d + 8192); } }while(0)
; #define STAGE_B(b,h,kt) do{ unsigned char* _d = SB(b,h) + wbase; \
;     if constexpr (BLK) { const char* _s = ((h)?baseB1:baseB0) + (size_t)(kt) * 16384; GLDS(_s + voa, _d); GLDS(_s + 8192 + voa, _d + 8192); } \
;     else { const char* _s = ((h)?baseB1:baseB0) + (kt)*128; GLDS(_s + voa, _d); GLDS(_s + (size_t)128*K + voa, _d + 8192); } }while(0)
; template <int K, int EPI, bool MIX = false>
; __device__ __forceinline__ void gemm_phase(const Params& p, const u16* __restrict__ A, const u16* __restrict__ Bt,
;                            const float* __restrict__ rs_in, float* __restrict__ ssq_out, float alpha, bool rev = false) {
;     ...
;       BAR; WAIT_L(0); MMA(0,1,At,B1); BAR;
;       LDA(At,1,1); if (more) STAGE_A(1,0,1);
;       BAR; WAIT_L(0); MMA(1,0,At,B0); BAR; SCHED;
;       if (more) { STAGE_B(1,1,1); WAIT_V(6); }
;       BAR; MMA(1,1,At,B1); BAR;
;       if (!more && wr == 0) BAR;
.LBB0_143:
	s_barrier
	s_waitcnt lgkmcnt(0)
	v_mfma_f32_16x16x32_bf16 v[96:99], v[128:131], v[200:203], v[152:155]
	v_mfma_f32_16x16x32_bf16 v[116:119], v[188:191], v[204:207], v[96:99]
	v_mfma_f32_16x16x32_bf16 v[96:99], v[132:135], v[200:203], v[156:159]
	v_mfma_f32_16x16x32_bf16 v[84:87], v[128:131], v[44:47], v[84:87]
	v_mfma_f32_16x16x32_bf16 v[44:47], v[132:135], v[44:47], v[80:83]
	v_mfma_f32_16x16x32_bf16 v[112:115], v[184:187], v[204:207], v[96:99]
	v_mfma_f32_16x16x32_bf16 v[96:99], v[184:187], v[192:195], v[44:47]
	v_mfma_f32_16x16x32_bf16 v[44:47], v[128:131], v[40:43], v[160:163]
	v_mfma_f32_16x16x32_bf16 v[40:43], v[132:135], v[40:43], v[164:167]
	v_mfma_f32_16x16x32_bf16 v[80:83], v[184:187], v[196:199], v[40:43]
	v_mfma_f32_16x16x32_bf16 v[40:43], v[128:131], v[24:27], v[68:71]
	v_mfma_f32_16x16x32_bf16 v[24:27], v[132:135], v[24:27], v[64:67]
	v_mfma_f32_16x16x32_bf16 v[100:103], v[188:191], v[192:195], v[84:87]
	v_mfma_f32_16x16x32_bf16 v[84:87], v[188:191], v[196:199], v[44:47]
	v_mfma_f32_16x16x32_bf16 v[68:71], v[188:191], v[28:31], v[40:43]
	v_mfma_f32_16x16x32_bf16 v[64:67], v[184:187], v[28:31], v[24:27]
	s_barrier
	ds_read_b128 v[200:203], v221 offset:49152
	ds_read_b128 v[164:167], v221 offset:51200
	ds_read_b128 v[204:207], v222 offset:49152
	ds_read_b128 v[192:195], v222 offset:51200
	ds_read_b128 v[160:163], v221 offset:53248
	ds_read_b128 v[152:155], v221 offset:55296
	ds_read_b128 v[196:199], v222 offset:53248
	ds_read_b128 v[156:159], v222 offset:55296
	s_and_b64 vcc, exec, s[4:5]
	s_cbranch_vccnz .LBB0_145
	s_mov_b32 m0, s45
	v_lshl_add_u64 v[26:27], v[214:215], 0, s[14:15]
	v_lshl_add_u64 v[24:25], v[214:215], 0, s[16:17]
	global_load_lds_dwordx4 v[26:27], off
	s_mov_b32 m0, s48
	s_nop 0
	global_load_lds_dwordx4 v[24:25], off
.LBB0_145:
	s_barrier
	s_waitcnt lgkmcnt(0)
	v_mfma_f32_16x16x32_bf16 v[24:27], v[8:11], v[200:203], v[60:63]
	v_mfma_f32_16x16x32_bf16 v[60:63], v[12:15], v[204:207], v[24:27]
	v_mfma_f32_16x16x32_bf16 v[24:27], v[176:179], v[200:203], v[56:59]
	v_mfma_f32_16x16x32_bf16 v[56:59], v[180:183], v[204:207], v[24:27]
	v_mfma_f32_16x16x32_bf16 v[24:27], v[8:11], v[164:167], v[52:55]
	v_mfma_f32_16x16x32_bf16 v[44:47], v[12:15], v[192:195], v[24:27]
	v_mfma_f32_16x16x32_bf16 v[24:27], v[176:179], v[164:167], v[48:51]
	v_mfma_f32_16x16x32_bf16 v[40:43], v[180:183], v[192:195], v[24:27]
	v_mfma_f32_16x16x32_bf16 v[24:27], v[8:11], v[160:163], v[168:171]
	v_mfma_f32_16x16x32_bf16 v[8:11], v[8:11], v[152:155], v[36:39]
	v_mfma_f32_16x16x32_bf16 v[28:31], v[12:15], v[196:199], v[24:27]
	v_mfma_f32_16x16x32_bf16 v[24:27], v[176:179], v[160:163], v[172:175]
	v_mfma_f32_16x16x32_bf16 v[12:15], v[12:15], v[156:159], v[8:11]
	v_mfma_f32_16x16x32_bf16 v[8:11], v[176:179], v[152:155], v[32:35]
	v_mfma_f32_16x16x32_bf16 v[24:27], v[180:183], v[196:199], v[24:27]
	v_mfma_f32_16x16x32_bf16 v[8:11], v[180:183], v[156:159], v[8:11]
	s_barrier
	s_and_b64 vcc, exec, s[4:5]
	s_mov_b64 s[46:47], s[24:25]
	s_cbranch_vccnz .LBB0_147
	s_mov_b32 m0, s49
	v_lshl_add_u64 v[34:35], v[212:213], 0, s[14:15]
	v_lshl_add_u64 v[32:33], v[212:213], 0, s[16:17]
	global_load_lds_dwordx4 v[34:35], off
	s_mov_b32 m0, s50
	s_mov_b64 s[46:47], 0
	global_load_lds_dwordx4 v[32:33], off
	s_waitcnt vmcnt(6)
.LBB0_147:
	s_barrier
	v_mfma_f32_16x16x32_bf16 v[32:35], v[128:131], v[200:203], v[136:139]
	v_mfma_f32_16x16x32_bf16 v[52:55], v[188:191], v[204:207], v[32:35]
	v_mfma_f32_16x16x32_bf16 v[32:35], v[132:135], v[200:203], v[140:143]
	v_mfma_f32_16x16x32_bf16 v[16:19], v[132:135], v[164:167], v[16:19]
	v_mfma_f32_16x16x32_bf16 v[48:51], v[184:187], v[204:207], v[32:35]
	v_mfma_f32_16x16x32_bf16 v[20:23], v[128:131], v[164:167], v[20:23]
	v_mfma_f32_16x16x32_bf16 v[32:35], v[184:187], v[192:195], v[16:19]
	v_mfma_f32_16x16x32_bf16 v[16:19], v[128:131], v[160:163], v[144:147]
	v_mfma_f32_16x16x32_bf16 v[36:39], v[188:191], v[192:195], v[20:23]
	v_mfma_f32_16x16x32_bf16 v[20:23], v[188:191], v[196:199], v[16:19]
	v_mfma_f32_16x16x32_bf16 v[16:19], v[132:135], v[160:163], v[148:151]
	v_mfma_f32_16x16x32_bf16 v[4:7], v[128:131], v[152:155], v[4:7]
	v_mfma_f32_16x16x32_bf16 v[0:3], v[132:135], v[152:155], v[0:3]
	v_mfma_f32_16x16x32_bf16 v[16:19], v[184:187], v[196:199], v[16:19]
	v_mfma_f32_16x16x32_bf16 v[4:7], v[188:191], v[156:159], v[4:7]
	v_mfma_f32_16x16x32_bf16 v[0:3], v[184:187], v[156:159], v[0:3]
	s_or_b64 vcc, s[4:5], s[24:25]
	s_cbranch_scc0 .Llate_p2_defer
	s_barrier

.Llate_p3_done:
.LBB0_183:
	ds_read_b128 v[128:131], v220
	s_waitcnt lgkmcnt(0)
	ds_read_b128 v[132:135], v220 offset:2048
	ds_read_b128 v[136:139], v221
	ds_read_b128 v[140:143], v221 offset:2048
	v_lshl_add_u64 v[192:193], s[6:7], 0, v[210:211]
	s_mov_b32 m0, s28
	v_lshl_add_u64 v[176:177], v[192:193], 0, s[72:73]
	ds_read_b128 v[144:147], v222
	ds_read_b128 v[148:151], v222 offset:2048
	ds_read_b128 v[152:155], v223
	ds_read_b128 v[156:159], v223 offset:2048
	ds_read_b128 v[160:163], v222 offset:4096
	ds_read_b128 v[164:167], v222 offset:6144
	ds_read_b128 v[168:171], v223 offset:4096
	ds_read_b128 v[172:175], v223 offset:6144
	global_load_lds_dwordx4 v[176:177], off
	v_lshl_add_u64 v[176:177], v[192:193], 0, s[70:71]
	s_mov_b32 m0, s22
	s_nop 0
	global_load_lds_dwordx4 v[176:177], off
	s_waitcnt lgkmcnt(8)
	s_barrier
	s_waitcnt lgkmcnt(0)
	v_mfma_f32_16x16x32_bf16 v[124:127], v[128:131], v[144:147], v[124:127]
	v_mfma_f32_16x16x32_bf16 v[120:123], v[132:135], v[144:147], v[120:123]
	v_mfma_f32_16x16x32_bf16 v[116:119], v[128:131], v[148:151], v[116:119]
	v_mfma_f32_16x16x32_bf16 v[112:115], v[132:135], v[148:151], v[112:115]
	v_mfma_f32_16x16x32_bf16 v[108:111], v[128:131], v[160:163], v[108:111]
	v_mfma_f32_16x16x32_bf16 v[104:107], v[132:135], v[160:163], v[104:107]
	v_mfma_f32_16x16x32_bf16 v[100:103], v[128:131], v[164:167], v[100:103]
	v_mfma_f32_16x16x32_bf16 v[96:99], v[132:135], v[164:167], v[96:99]
	v_mfma_f32_16x16x32_bf16 v[124:127], v[136:139], v[152:155], v[124:127]
	v_mfma_f32_16x16x32_bf16 v[120:123], v[140:143], v[152:155], v[120:123]
	v_mfma_f32_16x16x32_bf16 v[116:119], v[136:139], v[156:159], v[116:119]
	v_mfma_f32_16x16x32_bf16 v[112:115], v[140:143], v[156:159], v[112:115]
	v_mfma_f32_16x16x32_bf16 v[108:111], v[136:139], v[168:171], v[108:111]
	v_mfma_f32_16x16x32_bf16 v[104:107], v[140:143], v[168:171], v[104:107]
	v_mfma_f32_16x16x32_bf16 v[100:103], v[136:139], v[172:175], v[100:103]
	v_mfma_f32_16x16x32_bf16 v[96:99], v[140:143], v[172:175], v[96:99]
	s_barrier
	v_lshl_add_u64 v[194:195], s[8:9], 0, v[210:211]
	s_mov_b32 m0, s37
	v_lshl_add_u64 v[196:197], v[194:195], 0, s[78:79]
	ds_read_b128 v[176:179], v224
	ds_read_b128 v[180:183], v224 offset:2048
	ds_read_b128 v[184:187], v225
	ds_read_b128 v[188:191], v225 offset:2048
	global_load_lds_dwordx4 v[196:197], off
	v_lshl_add_u64 v[196:197], v[194:195], 0, s[80:81]
	s_mov_b32 m0, s39
	s_nop 0
	global_load_lds_dwordx4 v[196:197], off
	s_barrier
	s_waitcnt lgkmcnt(0)
	v_mfma_f32_16x16x32_bf16 v[56:59], v[176:179], v[144:147], v[56:59]
	v_mfma_f32_16x16x32_bf16 v[64:67], v[180:183], v[144:147], v[64:67]
	v_mfma_f32_16x16x32_bf16 v[72:75], v[176:179], v[148:151], v[72:75]
	v_mfma_f32_16x16x32_bf16 v[76:79], v[180:183], v[148:151], v[76:79]
	v_mfma_f32_16x16x32_bf16 v[80:83], v[176:179], v[160:163], v[80:83]
	v_mfma_f32_16x16x32_bf16 v[84:87], v[180:183], v[160:163], v[84:87]
	v_mfma_f32_16x16x32_bf16 v[88:91], v[176:179], v[164:167], v[88:91]
	v_mfma_f32_16x16x32_bf16 v[92:95], v[180:183], v[164:167], v[92:95]
	v_mfma_f32_16x16x32_bf16 v[56:59], v[184:187], v[152:155], v[56:59]
	v_mfma_f32_16x16x32_bf16 v[64:67], v[188:191], v[152:155], v[64:67]
	v_mfma_f32_16x16x32_bf16 v[72:75], v[184:187], v[156:159], v[72:75]
	v_mfma_f32_16x16x32_bf16 v[76:79], v[188:191], v[156:159], v[76:79]
	v_mfma_f32_16x16x32_bf16 v[80:83], v[184:187], v[168:171], v[80:83]
	v_mfma_f32_16x16x32_bf16 v[84:87], v[188:191], v[168:171], v[84:87]
	v_mfma_f32_16x16x32_bf16 v[88:91], v[184:187], v[172:175], v[88:91]
	v_mfma_f32_16x16x32_bf16 v[92:95], v[188:191], v[172:175], v[92:95]
	s_barrier
	s_mov_b32 m0, s76
	v_lshl_add_u64 v[196:197], v[192:193], 0, s[78:79]
	ds_read_b128 v[144:147], v222 offset:16384
	ds_read_b128 v[148:151], v222 offset:18432
	ds_read_b128 v[152:155], v223 offset:16384
	ds_read_b128 v[156:159], v223 offset:18432
	ds_read_b128 v[160:163], v222 offset:20480
	ds_read_b128 v[164:167], v222 offset:22528
	ds_read_b128 v[168:171], v223 offset:20480
	ds_read_b128 v[172:175], v223 offset:22528
	global_load_lds_dwordx4 v[196:197], off
	v_lshl_add_u64 v[196:197], v[192:193], 0, s[80:81]
	s_mov_b32 m0, s77
	s_nop 0
	global_load_lds_dwordx4 v[196:197], off
	s_barrier
	s_waitcnt lgkmcnt(0)
	v_mfma_f32_16x16x32_bf16 v[32:35], v[128:131], v[144:147], v[32:35]
	v_mfma_f32_16x16x32_bf16 v[36:39], v[132:135], v[144:147], v[36:39]
	v_mfma_f32_16x16x32_bf16 v[40:43], v[128:131], v[148:151], v[40:43]
	v_mfma_f32_16x16x32_bf16 v[44:47], v[132:135], v[148:151], v[44:47]
	v_mfma_f32_16x16x32_bf16 v[48:51], v[128:131], v[160:163], v[48:51]
	v_mfma_f32_16x16x32_bf16 v[52:55], v[132:135], v[160:163], v[52:55]
	v_mfma_f32_16x16x32_bf16 v[60:63], v[128:131], v[164:167], v[60:63]
	v_mfma_f32_16x16x32_bf16 v[68:71], v[132:135], v[164:167], v[68:71]
	v_mfma_f32_16x16x32_bf16 v[32:35], v[136:139], v[152:155], v[32:35]
	v_mfma_f32_16x16x32_bf16 v[36:39], v[140:143], v[152:155], v[36:39]
	v_mfma_f32_16x16x32_bf16 v[40:43], v[136:139], v[156:159], v[40:43]
	v_mfma_f32_16x16x32_bf16 v[44:47], v[140:143], v[156:159], v[44:47]
	v_mfma_f32_16x16x32_bf16 v[48:51], v[136:139], v[168:171], v[48:51]
	v_mfma_f32_16x16x32_bf16 v[52:55], v[140:143], v[168:171], v[52:55]
	v_mfma_f32_16x16x32_bf16 v[60:63], v[136:139], v[172:175], v[60:63]
	v_mfma_f32_16x16x32_bf16 v[68:71], v[140:143], v[172:175], v[68:71]
	s_barrier
	v_lshl_add_u64 v[196:197], s[4:5], 0, v[210:211]
	s_mov_b32 m0, s23
	v_lshl_add_u64 v[128:129], v[196:197], 0, s[78:79]
	global_load_lds_dwordx4 v[128:129], off
	v_lshl_add_u64 v[128:129], v[196:197], 0, s[80:81]
	s_mov_b32 m0, s33
	s_nop 0
	global_load_lds_dwordx4 v[128:129], off
	s_waitcnt vmcnt(6)
	s_barrier
	v_mfma_f32_16x16x32_bf16 v[0:3], v[176:179], v[144:147], v[0:3]
	v_mfma_f32_16x16x32_bf16 v[4:7], v[180:183], v[144:147], v[4:7]
	v_mfma_f32_16x16x32_bf16 v[8:11], v[176:179], v[148:151], v[8:11]
	v_mfma_f32_16x16x32_bf16 v[12:15], v[180:183], v[148:151], v[12:15]
	v_mfma_f32_16x16x32_bf16 v[16:19], v[176:179], v[160:163], v[16:19]
	v_mfma_f32_16x16x32_bf16 v[20:23], v[180:183], v[160:163], v[20:23]
	v_mfma_f32_16x16x32_bf16 v[24:27], v[176:179], v[164:167], v[24:27]
	v_mfma_f32_16x16x32_bf16 v[28:31], v[180:183], v[164:167], v[28:31]
	v_mfma_f32_16x16x32_bf16 v[0:3], v[184:187], v[152:155], v[0:3]
	v_mfma_f32_16x16x32_bf16 v[4:7], v[188:191], v[152:155], v[4:7]
	v_mfma_f32_16x16x32_bf16 v[8:11], v[184:187], v[156:159], v[8:11]
	v_mfma_f32_16x16x32_bf16 v[12:15], v[188:191], v[156:159], v[12:15]
	v_mfma_f32_16x16x32_bf16 v[16:19], v[184:187], v[168:171], v[16:19]
	v_mfma_f32_16x16x32_bf16 v[20:23], v[188:191], v[168:171], v[20:23]
	v_mfma_f32_16x16x32_bf16 v[24:27], v[184:187], v[172:175], v[24:27]
	v_mfma_f32_16x16x32_bf16 v[28:31], v[188:191], v[172:175], v[28:31]
	s_barrier
	ds_read_b128 v[128:131], v226
	ds_read_b128 v[132:135], v226 offset:2048
	ds_read_b128 v[136:139], v227
	ds_read_b128 v[140:143], v227 offset:2048
	s_mov_b64 s[10:11], 0x80100
	s_mov_b32 m0, s26
	v_lshl_add_u64 v[176:177], v[192:193], 0, s[10:11]
	s_mov_b64 s[10:11], 0xc0100
	ds_read_b128 v[144:147], v222 offset:32768
	ds_read_b128 v[148:151], v222 offset:34816
	ds_read_b128 v[152:155], v223 offset:32768
	ds_read_b128 v[156:159], v223 offset:34816
	ds_read_b128 v[160:163], v222 offset:36864
	ds_read_b128 v[164:167], v222 offset:38912
	ds_read_b128 v[168:171], v223 offset:36864
	ds_read_b128 v[172:175], v223 offset:38912
	global_load_lds_dwordx4 v[176:177], off
	v_lshl_add_u64 v[176:177], v[192:193], 0, s[10:11]
	s_mov_b32 m0, s35
	s_nop 0
	global_load_lds_dwordx4 v[176:177], off
	s_waitcnt lgkmcnt(8)
	s_barrier
	s_waitcnt lgkmcnt(0)
	v_mfma_f32_16x16x32_bf16 v[124:127], v[128:131], v[144:147], v[124:127]
	v_mfma_f32_16x16x32_bf16 v[120:123], v[132:135], v[144:147], v[120:123]
	v_mfma_f32_16x16x32_bf16 v[116:119], v[128:131], v[148:151], v[116:119]
	v_mfma_f32_16x16x32_bf16 v[112:115], v[132:135], v[148:151], v[112:115]
	v_mfma_f32_16x16x32_bf16 v[108:111], v[128:131], v[160:163], v[108:111]
	v_mfma_f32_16x16x32_bf16 v[104:107], v[132:135], v[160:163], v[104:107]
	v_mfma_f32_16x16x32_bf16 v[100:103], v[128:131], v[164:167], v[100:103]
	v_mfma_f32_16x16x32_bf16 v[96:99], v[132:135], v[164:167], v[96:99]
	v_mfma_f32_16x16x32_bf16 v[124:127], v[136:139], v[152:155], v[124:127]
	v_mfma_f32_16x16x32_bf16 v[120:123], v[140:143], v[152:155], v[120:123]
	v_mfma_f32_16x16x32_bf16 v[116:119], v[136:139], v[156:159], v[116:119]
	v_mfma_f32_16x16x32_bf16 v[112:115], v[140:143], v[156:159], v[112:115]
	v_mfma_f32_16x16x32_bf16 v[108:111], v[136:139], v[168:171], v[108:111]
	v_mfma_f32_16x16x32_bf16 v[104:107], v[140:143], v[168:171], v[104:107]
	v_mfma_f32_16x16x32_bf16 v[100:103], v[136:139], v[172:175], v[100:103]
	v_mfma_f32_16x16x32_bf16 v[96:99], v[140:143], v[172:175], v[96:99]
	s_barrier
	s_mov_b32 m0, s27
	v_lshl_add_u64 v[198:199], v[194:195], 0, s[82:83]
	ds_read_b128 v[176:179], v228
	ds_read_b128 v[180:183], v228 offset:2048
	ds_read_b128 v[184:187], v229
	ds_read_b128 v[188:191], v229 offset:2048
	global_load_lds_dwordx4 v[198:199], off
	v_lshl_add_u64 v[194:195], v[194:195], 0, s[96:97]
	s_mov_b32 m0, s31
	s_nop 0
	global_load_lds_dwordx4 v[194:195], off
	s_barrier
	s_waitcnt lgkmcnt(0)
	v_mfma_f32_16x16x32_bf16 v[56:59], v[176:179], v[144:147], v[56:59]
	v_mfma_f32_16x16x32_bf16 v[64:67], v[180:183], v[144:147], v[64:67]
	v_mfma_f32_16x16x32_bf16 v[72:75], v[176:179], v[148:151], v[72:75]
	v_mfma_f32_16x16x32_bf16 v[76:79], v[180:183], v[148:151], v[76:79]
	v_mfma_f32_16x16x32_bf16 v[80:83], v[176:179], v[160:163], v[80:83]
	v_mfma_f32_16x16x32_bf16 v[84:87], v[180:183], v[160:163], v[84:87]
	v_mfma_f32_16x16x32_bf16 v[88:91], v[176:179], v[164:167], v[88:91]
	v_mfma_f32_16x16x32_bf16 v[92:95], v[180:183], v[164:167], v[92:95]
	v_mfma_f32_16x16x32_bf16 v[56:59], v[184:187], v[152:155], v[56:59]
	v_mfma_f32_16x16x32_bf16 v[64:67], v[188:191], v[152:155], v[64:67]
	v_mfma_f32_16x16x32_bf16 v[72:75], v[184:187], v[156:159], v[72:75]
	v_mfma_f32_16x16x32_bf16 v[76:79], v[188:191], v[156:159], v[76:79]
	v_mfma_f32_16x16x32_bf16 v[80:83], v[184:187], v[168:171], v[80:83]
	v_mfma_f32_16x16x32_bf16 v[84:87], v[188:191], v[168:171], v[84:87]
	v_mfma_f32_16x16x32_bf16 v[88:91], v[184:187], v[172:175], v[88:91]
	v_mfma_f32_16x16x32_bf16 v[92:95], v[188:191], v[172:175], v[92:95]
	s_barrier
	s_mov_b32 m0, s1
	v_lshl_add_u64 v[194:195], v[192:193], 0, s[82:83]
	ds_read_b128 v[144:147], v222 offset:49152
	ds_read_b128 v[148:151], v222 offset:51200
	ds_read_b128 v[152:155], v223 offset:49152
	ds_read_b128 v[156:159], v223 offset:51200
	ds_read_b128 v[160:163], v222 offset:53248
	ds_read_b128 v[164:167], v222 offset:55296
	ds_read_b128 v[168:171], v223 offset:53248
	ds_read_b128 v[172:175], v223 offset:55296
	global_load_lds_dwordx4 v[194:195], off
	v_lshl_add_u64 v[192:193], v[192:193], 0, s[96:97]
	s_mov_b32 m0, s34
	s_nop 0
	global_load_lds_dwordx4 v[192:193], off
	s_barrier
; template <int K, int EPI, bool MIX = false>
; __device__ __forceinline__ void gemm_phase(const Params& p, const u16* __restrict__ A, const u16* __restrict__ Bt,
;                            const float* __restrict__ rs_in, float* __restrict__ ssq_out, float alpha, bool rev = false) {
;     ...
;     if constexpr (MIX) {
;       for (int t = 0; t < nt / 2; t += 2) KBODY(t);
	s_waitcnt lgkmcnt(0)
	v_mfma_f32_16x16x32_bf16 v[32:35], v[128:131], v[144:147], v[32:35]
	v_mfma_f32_16x16x32_bf16 v[36:39], v[132:135], v[144:147], v[36:39]
	v_mfma_f32_16x16x32_bf16 v[40:43], v[128:131], v[148:151], v[40:43]
	v_mfma_f32_16x16x32_bf16 v[44:47], v[132:135], v[148:151], v[44:47]
	v_mfma_f32_16x16x32_bf16 v[48:51], v[128:131], v[160:163], v[48:51]
	v_mfma_f32_16x16x32_bf16 v[52:55], v[132:135], v[160:163], v[52:55]
	v_mfma_f32_16x16x32_bf16 v[60:63], v[128:131], v[164:167], v[60:63]
	v_mfma_f32_16x16x32_bf16 v[68:71], v[132:135], v[164:167], v[68:71]
	v_mfma_f32_16x16x32_bf16 v[32:35], v[136:139], v[152:155], v[32:35]
	v_mfma_f32_16x16x32_bf16 v[36:39], v[140:143], v[152:155], v[36:39]
	v_mfma_f32_16x16x32_bf16 v[40:43], v[136:139], v[156:159], v[40:43]
	v_mfma_f32_16x16x32_bf16 v[44:47], v[140:143], v[156:159], v[44:47]
	v_mfma_f32_16x16x32_bf16 v[48:51], v[136:139], v[168:171], v[48:51]
	v_mfma_f32_16x16x32_bf16 v[52:55], v[140:143], v[168:171], v[52:55]
	v_mfma_f32_16x16x32_bf16 v[60:63], v[136:139], v[172:175], v[60:63]
	v_mfma_f32_16x16x32_bf16 v[68:71], v[140:143], v[172:175], v[68:71]
	s_barrier
	s_mov_b32 m0, s19
	v_lshl_add_u64 v[128:129], v[196:197], 0, s[82:83]
	global_load_lds_dwordx4 v[128:129], off
	v_lshl_add_u64 v[128:129], v[196:197], 0, s[96:97]
	s_mov_b32 m0, s18
	s_nop 0
	global_load_lds_dwordx4 v[128:129], off
	s_waitcnt vmcnt(6)
	s_barrier
	v_mfma_f32_16x16x32_bf16 v[0:3], v[176:179], v[144:147], v[0:3]
	v_mfma_f32_16x16x32_bf16 v[4:7], v[180:183], v[144:147], v[4:7]
	v_mfma_f32_16x16x32_bf16 v[8:11], v[176:179], v[148:151], v[8:11]
	v_mfma_f32_16x16x32_bf16 v[12:15], v[180:183], v[148:151], v[12:15]
	v_mfma_f32_16x16x32_bf16 v[16:19], v[176:179], v[160:163], v[16:19]
	v_mfma_f32_16x16x32_bf16 v[20:23], v[180:183], v[160:163], v[20:23]
	v_mfma_f32_16x16x32_bf16 v[24:27], v[176:179], v[164:167], v[24:27]
	v_mfma_f32_16x16x32_bf16 v[28:31], v[180:183], v[164:167], v[28:31]
	v_mfma_f32_16x16x32_bf16 v[0:3], v[184:187], v[152:155], v[0:3]
	v_mfma_f32_16x16x32_bf16 v[4:7], v[188:191], v[152:155], v[4:7]
	v_mfma_f32_16x16x32_bf16 v[8:11], v[184:187], v[156:159], v[8:11]
	v_mfma_f32_16x16x32_bf16 v[12:15], v[188:191], v[156:159], v[12:15]
	v_mfma_f32_16x16x32_bf16 v[16:19], v[184:187], v[168:171], v[16:19]
	v_mfma_f32_16x16x32_bf16 v[20:23], v[188:191], v[168:171], v[20:23]
	v_mfma_f32_16x16x32_bf16 v[24:27], v[184:187], v[172:175], v[24:27]
	v_mfma_f32_16x16x32_bf16 v[28:31], v[188:191], v[172:175], v[28:31]
	s_barrier
	s_add_i32 s2, s2, 2
	s_add_u32 s8, s8, 0x100
	s_addc_u32 s9, s9, 0
	s_add_u32 s6, s6, 0x100
	s_addc_u32 s7, s7, 0
	s_add_u32 s4, s4, 0x100
	s_addc_u32 s5, s5, 0
	s_cmp_lt_u32 s2, 28
	s_cbranch_scc1 .LBB0_183
; #define LDA(dst,b,h) _Pragma("unroll") for(int m=0;m<4;++m) _Pragma("unroll") for(int k=0;k<2;++k) \
;     dst[m][k]=*reinterpret_cast<const bf16x8*>(SA(b,h)+(wr*64+m*16)*128+koff[k])
; #define LDB(dst,b,h) _Pragma("unroll") for(int n=0;n<2;++n) _Pragma("unroll") for(int k=0;k<2;++k) \
;     dst[n][k]=*reinterpret_cast<const bf16x8*>(SB(b,h)+(wc*32+n*16)*128+koff[k])
; #define MMA(ai,bj,Af,Bf) do{__builtin_amdgcn_s_setprio(1); \
;     _Pragma("unroll") for(int m=0;m<4;++m) _Pragma("unroll") for(int n=0;n<2;++n) _Pragma("unroll") for(int k=0;k<2;++k) \
;       acc[ai][bj][m][n]=__builtin_amdgcn_mfma_f32_16x16x32_bf16(Bf[n][k],Af[m][k],acc[ai][bj][m][n],0,0,0); \
;     __builtin_amdgcn_s_setprio(0);}while(0)
; #define WAIT_L(n) asm volatile("s_waitcnt lgkmcnt(" #n ")":::"memory")
; #define BAR __builtin_amdgcn_s_barrier()
; #define SCHED __builtin_amdgcn_sched_barrier(0)
; #define STAGE_A(b,h,kt) do{ unsigned char* _d = SA(b,h) + wbase; \
;     if constexpr (BLK) { const char* _s = baseA + ((size_t)(h)*(K/64) + (kt)) * 16384; GLDS(_s + voa, _d); GLDS(_s + 8192 + voa, _d + 8192); } \
;     else { const char* _s = baseA + ((size_t)(h)*128*K + (kt)*64) * 2; GLDS(_s + voa, _d); GLDS(_s + (size_t)128*K + voa, _d + 8192); } }while(0)
; template <int K, int EPI, bool MIX = false>
; __device__ __forceinline__ void gemm_phase(const Params& p, const u16* __restrict__ A, const u16* __restrict__ Bt,
;                            const float* __restrict__ rs_in, float* __restrict__ ssq_out, float alpha, bool rev = false) {
;     ...
;     const int cpm = pm, cpn = pn;
;     float rsq[2][4];
;     if constexpr (EPI == EPI_SWIGLU || EPI == EPI_Z || MIX) {
;       const float* rsrc = MIX ? p.ssqb : rs_in;
;       int fr_p = fr;
;       asm volatile("" : "+v"(fr_p));
; #pragma unroll
;       for (int ai = 0; ai < 2; ++ai)
; #pragma unroll
;         for (int m = 0; m < 4; ++m) rsq[ai][m] = rsrc[cpm * 256 + ai * 128 + wr * 64 + m * 16 + fr_p];
;     }
;     ++it;
;     id = item_id(it);
;     const bool more = id < ntiles;
;     if (rev) id = ntiles - 1 - id;
;     {
;       LDB(B0,0,0); SCHED; LDA(At,0,0); STAGE_A(1,1,nt-1);
;       WAIT_L(8); BAR; WAIT_L(0); MMA(0,0,At,B0); BAR; SCHED;
;       if (more) SETUP_TILE();
	v_mov_b32_e32 v128, v219
	s_lshl_b32 s15, s12, 8
	s_add_i32 s15, s15, s13
	v_add_u32_e32 v128, s15, v128
	v_readlane_b32 s52, v254, 32
	v_ashrrev_i32_e32 v129, 31, v128
	v_readlane_b32 s64, v254, 44
	v_readlane_b32 s65, v254, 45
	s_add_i32 s74, s74, 1
	v_readlane_b32 s2, v255, 6
	v_lshl_add_u64 v[128:129], v[128:129], 2, s[64:65]
	global_load_dword v242, v[128:129], off
	global_load_dword v241, v[128:129], off offset:64
	global_load_dword v240, v[128:129], off offset:128
	global_load_dword v239, v[128:129], off offset:192
	global_load_dword v238, v[128:129], off offset:512
	global_load_dword v237, v[128:129], off offset:576
	global_load_dword v236, v[128:129], off offset:640
	global_load_dword v235, v[128:129], off offset:704
	ds_read_b128 v[136:139], v220
	ds_read_b128 v[140:143], v220 offset:2048
	ds_read_b128 v[148:151], v221
	ds_read_b128 v[144:147], v221 offset:2048
	s_mul_i32 s2, s74, s2
	v_readlane_b32 s4, v255, 17
	s_add_i32 s2, s2, s4
	v_readlane_b32 s53, v254, 33
	v_readlane_b32 s54, v254, 34
	v_readlane_b32 s55, v254, 35
	v_readlane_b32 s56, v254, 36
	v_readlane_b32 s57, v254, 37
	v_readlane_b32 s58, v254, 38
	v_readlane_b32 s59, v254, 39
	v_readlane_b32 s60, v254, 40
	v_readlane_b32 s61, v254, 41
	v_readlane_b32 s62, v254, 42
	v_readlane_b32 s63, v254, 43
	v_readlane_b32 s66, v254, 46
	v_readlane_b32 s67, v254, 47
	v_lshl_add_u64 v[128:129], s[16:17], 0, v[208:209]
	s_mov_b64 s[4:5], 0x80f80
	s_mov_b32 m0, s28
	v_lshl_add_u64 v[130:131], v[128:129], 0, s[4:5]
	s_mov_b64 s[4:5], 0xc0f80
	ds_read_b128 v[152:155], v222
	ds_read_b128 v[156:159], v222 offset:2048
	ds_read_b128 v[180:183], v223
	ds_read_b128 v[164:167], v223 offset:2048
	ds_read_b128 v[160:163], v222 offset:4096
	ds_read_b128 v[168:171], v222 offset:6144
	ds_read_b128 v[176:179], v223 offset:4096
	ds_read_b128 v[172:175], v223 offset:6144
	global_load_lds_dwordx4 v[130:131], off
	v_lshl_add_u64 v[128:129], v[128:129], 0, s[4:5]
	s_mov_b32 m0, s22
	s_nop 0
	global_load_lds_dwordx4 v[128:129], off
	s_waitcnt lgkmcnt(8)
	s_barrier
	s_waitcnt lgkmcnt(0)
	v_mfma_f32_16x16x32_bf16 v[124:127], v[136:139], v[152:155], v[124:127]
	s_cmpk_lt_i32 s2, 0xf00
	s_cselect_b64 s[4:5], -1, 0
	s_cmpk_gt_i32 s2, 0xeff
	v_mfma_f32_16x16x32_bf16 v[120:123], v[140:143], v[152:155], v[120:123]
	v_mfma_f32_16x16x32_bf16 v[116:119], v[136:139], v[156:159], v[116:119]
	v_mfma_f32_16x16x32_bf16 v[112:115], v[140:143], v[156:159], v[112:115]
	v_mfma_f32_16x16x32_bf16 v[108:111], v[136:139], v[160:163], v[108:111]
	v_mfma_f32_16x16x32_bf16 v[104:107], v[140:143], v[160:163], v[104:107]
	v_mfma_f32_16x16x32_bf16 v[100:103], v[136:139], v[168:171], v[100:103]
	v_mfma_f32_16x16x32_bf16 v[96:99], v[140:143], v[168:171], v[96:99]
	v_mfma_f32_16x16x32_bf16 v[124:127], v[148:151], v[180:183], v[124:127]
	v_mfma_f32_16x16x32_bf16 v[120:123], v[144:147], v[180:183], v[120:123]
	v_mfma_f32_16x16x32_bf16 v[116:119], v[148:151], v[164:167], v[116:119]
	v_mfma_f32_16x16x32_bf16 v[112:115], v[144:147], v[164:167], v[112:115]
	v_mfma_f32_16x16x32_bf16 v[108:111], v[148:151], v[176:179], v[108:111]
	v_mfma_f32_16x16x32_bf16 v[104:107], v[144:147], v[176:179], v[104:107]
	v_mfma_f32_16x16x32_bf16 v[128:131], v[148:151], v[172:175], v[100:103]
	v_mfma_f32_16x16x32_bf16 v[132:135], v[144:147], v[172:175], v[96:99]
	s_barrier
	s_mov_b32 s75, s25
	s_cbranch_scc1 .LBB0_186
	s_mul_hi_i32 s6, s2, 0x66666667
	s_lshr_b32 s7, s6, 31
	s_ashr_i32 s6, s6, 6
	s_add_i32 s6, s6, s7
	s_lshl_b32 s7, s6, 3
	s_mulk_i32 s6, 0xff60
	s_add_i32 s6, s6, s2
	s_and_b32 s2, s2, 7
	s_or_b32 s12, s7, s2
	s_ashr_i32 s75, s6, 3
	s_lshl_b32 s6, s12, 8
	s_ashr_i32 s7, s6, 31
	s_lshl_b64 s[6:7], s[6:7], 12
	s_add_u32 s16, s90, s6
	s_addc_u32 s17, s91, s7
	s_lshl_b32 s6, s75, 8
	s_ashr_i32 s7, s6, 31
	v_readlane_b32 s52, v254, 16
	s_lshl_b64 s[6:7], s[6:7], 12
	v_readlane_b32 s66, v254, 30
	v_readlane_b32 s67, v254, 31
	s_add_u32 s20, s66, s6
	s_addc_u32 s21, s67, s7
	s_add_u32 s44, s20, 0x80000
	s_addc_u32 s45, s21, 0
	v_readlane_b32 s53, v254, 17
	v_readlane_b32 s54, v254, 18
	v_readlane_b32 s55, v254, 19
	v_readlane_b32 s56, v254, 20
	v_readlane_b32 s57, v254, 21
	v_readlane_b32 s58, v254, 22
	v_readlane_b32 s59, v254, 23
	v_readlane_b32 s60, v254, 24
	v_readlane_b32 s61, v254, 25
	v_readlane_b32 s62, v254, 26
	v_readlane_b32 s63, v254, 27
	v_readlane_b32 s64, v254, 28
	v_readlane_b32 s65, v254, 29

; #define LDA(dst,b,h) _Pragma("unroll") for(int m=0;m<4;++m) _Pragma("unroll") for(int k=0;k<2;++k) \
;     dst[m][k]=*reinterpret_cast<const bf16x8*>(SA(b,h)+(wr*64+m*16)*128+koff[k])
; #define LDB(dst,b,h) _Pragma("unroll") for(int n=0;n<2;++n) _Pragma("unroll") for(int k=0;k<2;++k) \
;     dst[n][k]=*reinterpret_cast<const bf16x8*>(SB(b,h)+(wc*32+n*16)*128+koff[k])
; #define MMA(ai,bj,Af,Bf) do{__builtin_amdgcn_s_setprio(1); \
;     _Pragma("unroll") for(int m=0;m<4;++m) _Pragma("unroll") for(int n=0;n<2;++n) _Pragma("unroll") for(int k=0;k<2;++k) \
;       acc[ai][bj][m][n]=__builtin_amdgcn_mfma_f32_16x16x32_bf16(Bf[n][k],Af[m][k],acc[ai][bj][m][n],0,0,0); \
;     __builtin_amdgcn_s_setprio(0);}while(0)
; #define WAIT_V(n) asm volatile("s_waitcnt vmcnt(" #n ")":::"memory")
; #define WAIT_L(n) asm volatile("s_waitcnt lgkmcnt(" #n ")":::"memory")
; #define BAR __builtin_amdgcn_s_barrier()
; #define SCHED __builtin_amdgcn_sched_barrier(0)
; #define STAGE_A(b,h,kt) do{ unsigned char* _d = SA(b,h) + wbase; \
;     if constexpr (BLK) { const char* _s = baseA + ((size_t)(h)*(K/64) + (kt)) * 16384; GLDS(_s + voa, _d); GLDS(_s + 8192 + voa, _d + 8192); } \
;     else { const char* _s = baseA + ((size_t)(h)*128*K + (kt)*64) * 2; GLDS(_s + voa, _d); GLDS(_s + (size_t)128*K + voa, _d + 8192); } }while(0)
; #define STAGE_B(b,h,kt) do{ unsigned char* _d = SB(b,h) + wbase; \
;     if constexpr (BLK) { const char* _s = ((h)?baseB1:baseB0) + (size_t)(kt) * 16384; GLDS(_s + voa, _d); GLDS(_s + 8192 + voa, _d + 8192); } \
;     else { const char* _s = ((h)?baseB1:baseB0) + (kt)*128; GLDS(_s + voa, _d); GLDS(_s + (size_t)128*K + voa, _d + 8192); } }while(0)
; template <int K, int EPI, bool MIX = false>
; __device__ __forceinline__ void gemm_phase(const Params& p, const u16* __restrict__ A, const u16* __restrict__ Bt,
;                            const float* __restrict__ rs_in, float* __restrict__ ssq_out, float alpha, bool rev = false) {
;     ...
;       LDB(B1,0,1); if (more) STAGE_B(0,0,0);
;       BAR; WAIT_L(0); MMA(0,1,At,B1); BAR;
;       LDA(At,0,1); if (more) STAGE_A(0,0,0);
;       BAR; WAIT_L(0); MMA(1,0,At,B0); BAR; SCHED;
;       if (more) { STAGE_B(0,1,0); WAIT_V(6); } else { WAIT_V(0); }
.LBB0_188:
	s_barrier
	s_waitcnt lgkmcnt(0)
	v_mfma_f32_16x16x32_bf16 v[64:67], v[100:103], v[152:155], v[64:67]
	v_mfma_f32_16x16x32_bf16 v[56:59], v[96:99], v[152:155], v[56:59]
	v_mfma_f32_16x16x32_bf16 v[152:155], v[188:191], v[180:183], v[64:67]
	v_mfma_f32_16x16x32_bf16 v[64:67], v[96:99], v[156:159], v[72:75]
	v_mfma_f32_16x16x32_bf16 v[72:75], v[184:187], v[164:167], v[64:67]
	v_mfma_f32_16x16x32_bf16 v[64:67], v[100:103], v[156:159], v[76:79]
	v_mfma_f32_16x16x32_bf16 v[76:79], v[188:191], v[164:167], v[64:67]
	v_mfma_f32_16x16x32_bf16 v[64:67], v[96:99], v[160:163], v[80:83]
	v_mfma_f32_16x16x32_bf16 v[156:159], v[184:187], v[176:179], v[64:67]
	v_mfma_f32_16x16x32_bf16 v[64:67], v[100:103], v[160:163], v[84:87]
	v_mfma_f32_16x16x32_bf16 v[160:163], v[188:191], v[176:179], v[64:67]
	v_mfma_f32_16x16x32_bf16 v[64:67], v[96:99], v[168:171], v[88:91]
	v_mfma_f32_16x16x32_bf16 v[164:167], v[184:187], v[172:175], v[64:67]
	v_mfma_f32_16x16x32_bf16 v[64:67], v[100:103], v[168:171], v[92:95]
	v_mfma_f32_16x16x32_bf16 v[56:59], v[184:187], v[180:183], v[56:59]
	v_mfma_f32_16x16x32_bf16 v[168:171], v[188:191], v[172:175], v[64:67]
	s_barrier
	ds_read_b128 v[192:195], v222 offset:16384
	ds_read_b128 v[88:91], v222 offset:18432
	ds_read_b128 v[196:199], v223 offset:16384
	ds_read_b128 v[92:95], v223 offset:18432
	ds_read_b128 v[84:87], v222 offset:20480
	ds_read_b128 v[64:67], v222 offset:22528
	ds_read_b128 v[180:183], v223 offset:20480
	ds_read_b128 v[80:83], v223 offset:22528
	s_and_b64 vcc, exec, s[10:11]
	v_lshl_add_u64 v[214:215], s[16:17], 0, v[208:209]
	s_cbranch_vccnz .LBB0_190
	s_mov_b32 m0, s76
	v_lshl_add_u64 v[172:173], v[214:215], 0, s[42:43]
	global_load_lds_dwordx4 v[214:215], off
	s_mov_b32 m0, s77
	s_nop 0
	global_load_lds_dwordx4 v[172:173], off
.LBB0_190:
	s_barrier
	s_waitcnt lgkmcnt(0)
	v_mfma_f32_16x16x32_bf16 v[48:51], v[136:139], v[84:87], v[48:51]
	v_mfma_f32_16x16x32_bf16 v[172:175], v[148:151], v[180:183], v[48:51]
	v_mfma_f32_16x16x32_bf16 v[48:51], v[140:143], v[84:87], v[52:55]
	v_mfma_f32_16x16x32_bf16 v[176:179], v[144:147], v[180:183], v[48:51]
	v_mfma_f32_16x16x32_bf16 v[48:51], v[136:139], v[64:67], v[60:63]
	v_mfma_f32_16x16x32_bf16 v[32:35], v[136:139], v[192:195], v[32:35]
	v_mfma_f32_16x16x32_bf16 v[36:39], v[140:143], v[192:195], v[36:39]
	v_mfma_f32_16x16x32_bf16 v[40:43], v[136:139], v[88:91], v[40:43]
	v_mfma_f32_16x16x32_bf16 v[44:47], v[140:143], v[88:91], v[44:47]
	v_mfma_f32_16x16x32_bf16 v[60:63], v[148:151], v[80:83], v[48:51]
	v_mfma_f32_16x16x32_bf16 v[48:51], v[140:143], v[64:67], v[68:71]
	v_mfma_f32_16x16x32_bf16 v[32:35], v[148:151], v[196:199], v[32:35]
	v_mfma_f32_16x16x32_bf16 v[36:39], v[144:147], v[196:199], v[36:39]
	v_mfma_f32_16x16x32_bf16 v[40:43], v[148:151], v[92:95], v[40:43]
	v_mfma_f32_16x16x32_bf16 v[44:47], v[144:147], v[92:95], v[44:47]
	v_mfma_f32_16x16x32_bf16 v[136:139], v[144:147], v[80:83], v[48:51]
	s_barrier
	s_mov_b64 s[4:5], -1
	s_and_b64 vcc, exec, s[10:11]
	v_lshl_add_u64 v[212:213], s[44:45], 0, v[208:209]
	s_cbranch_vccnz .LBB0_192
	s_mov_b32 m0, s23
	v_lshl_add_u64 v[48:49], v[212:213], 0, s[42:43]
	global_load_lds_dwordx4 v[212:213], off
	s_mov_b32 m0, s33
	s_mov_b64 s[4:5], 0
	global_load_lds_dwordx4 v[48:49], off
	s_waitcnt vmcnt(6)

; #define LDA(dst,b,h) _Pragma("unroll") for(int m=0;m<4;++m) _Pragma("unroll") for(int k=0;k<2;++k) \
;     dst[m][k]=*reinterpret_cast<const bf16x8*>(SA(b,h)+(wr*64+m*16)*128+koff[k])
; #define LDB(dst,b,h) _Pragma("unroll") for(int n=0;n<2;++n) _Pragma("unroll") for(int k=0;k<2;++k) \
;     dst[n][k]=*reinterpret_cast<const bf16x8*>(SB(b,h)+(wc*32+n*16)*128+koff[k])
; #define MMA(ai,bj,Af,Bf) do{__builtin_amdgcn_s_setprio(1); \
;     _Pragma("unroll") for(int m=0;m<4;++m) _Pragma("unroll") for(int n=0;n<2;++n) _Pragma("unroll") for(int k=0;k<2;++k) \
;       acc[ai][bj][m][n]=__builtin_amdgcn_mfma_f32_16x16x32_bf16(Bf[n][k],Af[m][k],acc[ai][bj][m][n],0,0,0); \
;     __builtin_amdgcn_s_setprio(0);}while(0)
; #define WAIT_L(n) asm volatile("s_waitcnt lgkmcnt(" #n ")":::"memory")
; #define BAR __builtin_amdgcn_s_barrier()
; #define SCHED __builtin_amdgcn_sched_barrier(0)
; #define STAGE_A(b,h,kt) do{ unsigned char* _d = SA(b,h) + wbase; \
;     if constexpr (BLK) { const char* _s = baseA + ((size_t)(h)*(K/64) + (kt)) * 16384; GLDS(_s + voa, _d); GLDS(_s + 8192 + voa, _d + 8192); } \
;     else { const char* _s = baseA + ((size_t)(h)*128*K + (kt)*64) * 2; GLDS(_s + voa, _d); GLDS(_s + (size_t)128*K + voa, _d + 8192); } }while(0)
; #define STAGE_B(b,h,kt) do{ unsigned char* _d = SB(b,h) + wbase; \
;     if constexpr (BLK) { const char* _s = ((h)?baseB1:baseB0) + (size_t)(kt) * 16384; GLDS(_s + voa, _d); GLDS(_s + 8192 + voa, _d + 8192); } \
;     else { const char* _s = ((h)?baseB1:baseB0) + (kt)*128; GLDS(_s + voa, _d); GLDS(_s + (size_t)128*K + voa, _d + 8192); } }while(0)
; template <int K, int EPI, bool MIX = false>
; __device__ __forceinline__ void gemm_phase(const Params& p, const u16* __restrict__ A, const u16* __restrict__ Bt,
;                            const float* __restrict__ rs_in, float* __restrict__ ssq_out, float alpha, bool rev = false) {
;     ...
;       BAR; MMA(1,1,At,B1); BAR;
;       LDB(B0,1,0); SCHED; LDA(At,1,0); if (more) STAGE_A(0,1,0);
;       WAIT_L(8); BAR; WAIT_L(0); MMA(0,0,At,B0); BAR; SCHED;
;       LDB(B1,1,1); if (more) STAGE_B(1,0,1);
.LBB0_194:
	s_barrier
	v_mfma_f32_16x16x32_bf16 v[0:3], v[96:99], v[192:195], v[0:3]
	v_mfma_f32_16x16x32_bf16 v[140:143], v[184:187], v[196:199], v[0:3]
	v_mfma_f32_16x16x32_bf16 v[0:3], v[100:103], v[192:195], v[4:7]
	v_mfma_f32_16x16x32_bf16 v[144:147], v[188:191], v[196:199], v[0:3]
	v_mfma_f32_16x16x32_bf16 v[0:3], v[96:99], v[88:91], v[8:11]
	v_mfma_f32_16x16x32_bf16 v[8:11], v[184:187], v[92:95], v[0:3]
	v_mfma_f32_16x16x32_bf16 v[0:3], v[100:103], v[88:91], v[12:15]
	v_mfma_f32_16x16x32_bf16 v[12:15], v[188:191], v[92:95], v[0:3]
	v_mfma_f32_16x16x32_bf16 v[0:3], v[96:99], v[84:87], v[16:19]
	v_mfma_f32_16x16x32_bf16 v[148:151], v[184:187], v[180:183], v[0:3]
	v_mfma_f32_16x16x32_bf16 v[0:3], v[100:103], v[84:87], v[20:23]
	v_mfma_f32_16x16x32_bf16 v[180:183], v[188:191], v[180:183], v[0:3]
	v_mfma_f32_16x16x32_bf16 v[0:3], v[96:99], v[64:67], v[24:27]
	v_mfma_f32_16x16x32_bf16 v[184:187], v[184:187], v[80:83], v[0:3]
	v_mfma_f32_16x16x32_bf16 v[0:3], v[100:103], v[64:67], v[28:31]
	v_mfma_f32_16x16x32_bf16 v[188:191], v[188:191], v[80:83], v[0:3]
	s_barrier
	s_nop 4
	ds_read_b128 v[0:3], v226
	ds_read_b128 v[24:27], v226 offset:2048
	ds_read_b128 v[4:7], v227
	ds_read_b128 v[28:31], v227 offset:2048
	ds_read_b128 v[92:95], v222 offset:32768
	ds_read_b128 v[52:55], v222 offset:34816
	ds_read_b128 v[204:207], v223 offset:32768
	ds_read_b128 v[88:91], v223 offset:34816
	ds_read_b128 v[48:51], v222 offset:36864
	ds_read_b128 v[16:19], v222 offset:38912
	ds_read_b128 v[200:203], v223 offset:36864
	ds_read_b128 v[20:23], v223 offset:38912
	s_and_b64 vcc, exec, s[10:11]
	s_cbranch_vccnz .LBB0_196
	s_mov_b64 s[4:5], 0xc0000
	v_lshl_add_u64 v[64:65], v[214:215], 0, s[4:5]
	s_mov_b64 s[4:5], 0x80000
	s_mov_b32 m0, s26
	v_lshl_add_u64 v[66:67], v[214:215], 0, s[4:5]
	global_load_lds_dwordx4 v[66:67], off
	s_mov_b32 m0, s35
	s_nop 0
	global_load_lds_dwordx4 v[64:65], off
.LBB0_196:
	s_waitcnt lgkmcnt(8)
	s_barrier
	s_waitcnt lgkmcnt(0)
	v_mfma_f32_16x16x32_bf16 v[64:67], v[0:3], v[92:95], v[124:127]
	v_mfma_f32_16x16x32_bf16 v[124:127], v[4:7], v[204:207], v[64:67]
	v_mfma_f32_16x16x32_bf16 v[64:67], v[24:27], v[92:95], v[120:123]
	v_mfma_f32_16x16x32_bf16 v[120:123], v[28:31], v[204:207], v[64:67]
	v_mfma_f32_16x16x32_bf16 v[64:67], v[0:3], v[52:55], v[116:119]
	v_mfma_f32_16x16x32_bf16 v[100:103], v[4:7], v[88:91], v[64:67]
	v_mfma_f32_16x16x32_bf16 v[64:67], v[24:27], v[52:55], v[112:115]
	v_mfma_f32_16x16x32_bf16 v[96:99], v[28:31], v[88:91], v[64:67]
	v_mfma_f32_16x16x32_bf16 v[64:67], v[0:3], v[48:51], v[108:111]
	v_mfma_f32_16x16x32_bf16 v[84:87], v[4:7], v[200:203], v[64:67]
	v_mfma_f32_16x16x32_bf16 v[64:67], v[24:27], v[48:51], v[104:107]
	v_mfma_f32_16x16x32_bf16 v[80:83], v[28:31], v[200:203], v[64:67]
	v_mfma_f32_16x16x32_bf16 v[64:67], v[0:3], v[16:19], v[128:131]
	v_mfma_f32_16x16x32_bf16 v[68:71], v[4:7], v[20:23], v[64:67]
	v_mfma_f32_16x16x32_bf16 v[64:67], v[24:27], v[16:19], v[132:135]
	v_mfma_f32_16x16x32_bf16 v[64:67], v[28:31], v[20:23], v[64:67]
	s_barrier
	ds_read_b128 v[128:131], v228
	ds_read_b128 v[132:135], v228 offset:2048
	ds_read_b128 v[196:199], v229
	ds_read_b128 v[192:195], v229 offset:2048
	s_and_b64 vcc, exec, s[10:11]
	s_cbranch_vccnz .LBB0_198
	s_mov_b32 m0, s27
	v_lshl_add_u64 v[106:107], v[216:217], 0, s[46:47]
	v_lshl_add_u64 v[104:105], v[216:217], 0, s[48:49]
	global_load_lds_dwordx4 v[106:107], off
	s_mov_b32 m0, s31
	s_nop 0
	global_load_lds_dwordx4 v[104:105], off
; #define LDA(dst,b,h) _Pragma("unroll") for(int m=0;m<4;++m) _Pragma("unroll") for(int k=0;k<2;++k) \
;     dst[m][k]=*reinterpret_cast<const bf16x8*>(SA(b,h)+(wr*64+m*16)*128+koff[k])
; #define MMA(ai,bj,Af,Bf) do{__builtin_amdgcn_s_setprio(1); \
;     _Pragma("unroll") for(int m=0;m<4;++m) _Pragma("unroll") for(int n=0;n<2;++n) _Pragma("unroll") for(int k=0;k<2;++k) \
;       acc[ai][bj][m][n]=__builtin_amdgcn_mfma_f32_16x16x32_bf16(Bf[n][k],Af[m][k],acc[ai][bj][m][n],0,0,0); \
;     __builtin_amdgcn_s_setprio(0);}while(0)
; #define WAIT_V(n) asm volatile("s_waitcnt vmcnt(" #n ")":::"memory")
; #define WAIT_L(n) asm volatile("s_waitcnt lgkmcnt(" #n ")":::"memory")
; #define BAR __builtin_amdgcn_s_barrier()
; #define SCHED __builtin_amdgcn_sched_barrier(0)
; #define STAGE_A(b,h,kt) do{ unsigned char* _d = SA(b,h) + wbase; \
;     if constexpr (BLK) { const char* _s = baseA + ((size_t)(h)*(K/64) + (kt)) * 16384; GLDS(_s + voa, _d); GLDS(_s + 8192 + voa, _d + 8192); } \
;     else { const char* _s = baseA + ((size_t)(h)*128*K + (kt)*64) * 2; GLDS(_s + voa, _d); GLDS(_s + (size_t)128*K + voa, _d + 8192); } }while(0)
; #define STAGE_B(b,h,kt) do{ unsigned char* _d = SB(b,h) + wbase; \
;     if constexpr (BLK) { const char* _s = ((h)?baseB1:baseB0) + (size_t)(kt) * 16384; GLDS(_s + voa, _d); GLDS(_s + 8192 + voa, _d + 8192); } \
;     else { const char* _s = ((h)?baseB1:baseB0) + (kt)*128; GLDS(_s + voa, _d); GLDS(_s + (size_t)128*K + voa, _d + 8192); } }while(0)
; template <int K, int EPI, bool MIX = false>
; __device__ __forceinline__ void gemm_phase(const Params& p, const u16* __restrict__ A, const u16* __restrict__ Bt,
;                            const float* __restrict__ rs_in, float* __restrict__ ssq_out, float alpha, bool rev = false) {
;     ...
;       BAR; WAIT_L(0); MMA(0,1,At,B1); BAR;
;       LDA(At,1,1); if (more) STAGE_A(1,0,1);
;       BAR; WAIT_L(0); MMA(1,0,At,B0); BAR; SCHED;
;       if (more) { STAGE_B(1,1,1); WAIT_V(6); }
;       BAR; MMA(1,1,At,B1); BAR;
;       if (!more && wr == 0) BAR;
.LBB0_198:
	s_barrier
	s_waitcnt lgkmcnt(0)
	v_mfma_f32_16x16x32_bf16 v[56:59], v[128:131], v[92:95], v[56:59]
	v_mfma_f32_16x16x32_bf16 v[116:119], v[196:199], v[204:207], v[56:59]
	v_mfma_f32_16x16x32_bf16 v[56:59], v[132:135], v[92:95], v[152:155]
	v_mfma_f32_16x16x32_bf16 v[112:115], v[192:195], v[204:207], v[56:59]
	v_mfma_f32_16x16x32_bf16 v[56:59], v[128:131], v[52:55], v[72:75]
	v_mfma_f32_16x16x32_bf16 v[52:55], v[132:135], v[52:55], v[76:79]
	v_mfma_f32_16x16x32_bf16 v[104:107], v[192:195], v[88:91], v[52:55]
	v_mfma_f32_16x16x32_bf16 v[52:55], v[128:131], v[48:51], v[156:159]
	v_mfma_f32_16x16x32_bf16 v[48:51], v[132:135], v[48:51], v[160:163]
	v_mfma_f32_16x16x32_bf16 v[108:111], v[196:199], v[88:91], v[56:59]
	v_mfma_f32_16x16x32_bf16 v[88:91], v[192:195], v[200:203], v[48:51]
	v_mfma_f32_16x16x32_bf16 v[48:51], v[128:131], v[16:19], v[164:167]
	v_mfma_f32_16x16x32_bf16 v[16:19], v[132:135], v[16:19], v[168:171]
	v_mfma_f32_16x16x32_bf16 v[92:95], v[196:199], v[200:203], v[52:55]
	v_mfma_f32_16x16x32_bf16 v[76:79], v[196:199], v[20:23], v[48:51]
	v_mfma_f32_16x16x32_bf16 v[72:75], v[192:195], v[20:23], v[16:19]
	s_barrier
	ds_read_b128 v[56:59], v222 offset:49152
	ds_read_b128 v[164:167], v222 offset:51200
	ds_read_b128 v[204:207], v223 offset:49152
	ds_read_b128 v[168:171], v223 offset:51200
	ds_read_b128 v[160:163], v222 offset:53248
	ds_read_b128 v[152:155], v222 offset:55296
	ds_read_b128 v[200:203], v223 offset:53248
	ds_read_b128 v[156:159], v223 offset:55296
	s_and_b64 vcc, exec, s[10:11]
	s_cbranch_vccnz .LBB0_200
	s_mov_b32 m0, s1
	v_lshl_add_u64 v[18:19], v[214:215], 0, s[46:47]
	v_lshl_add_u64 v[16:17], v[214:215], 0, s[48:49]
	global_load_lds_dwordx4 v[18:19], off
	s_mov_b32 m0, s34
	s_nop 0
	global_load_lds_dwordx4 v[16:17], off
.LBB0_200:
	s_barrier
	s_waitcnt lgkmcnt(0)
	v_mfma_f32_16x16x32_bf16 v[16:19], v[0:3], v[56:59], v[32:35]
	v_mfma_f32_16x16x32_bf16 v[52:55], v[4:7], v[204:207], v[16:19]
	v_mfma_f32_16x16x32_bf16 v[16:19], v[24:27], v[56:59], v[36:39]
	v_mfma_f32_16x16x32_bf16 v[48:51], v[28:31], v[204:207], v[16:19]
	v_mfma_f32_16x16x32_bf16 v[16:19], v[0:3], v[164:167], v[40:43]
	v_mfma_f32_16x16x32_bf16 v[36:39], v[4:7], v[168:171], v[16:19]
	v_mfma_f32_16x16x32_bf16 v[16:19], v[24:27], v[164:167], v[44:47]
	v_mfma_f32_16x16x32_bf16 v[32:35], v[28:31], v[168:171], v[16:19]
	v_mfma_f32_16x16x32_bf16 v[16:19], v[0:3], v[160:163], v[172:175]
	v_mfma_f32_16x16x32_bf16 v[0:3], v[0:3], v[152:155], v[60:63]
	v_mfma_f32_16x16x32_bf16 v[20:23], v[4:7], v[200:203], v[16:19]
	v_mfma_f32_16x16x32_bf16 v[16:19], v[24:27], v[160:163], v[176:179]
	v_mfma_f32_16x16x32_bf16 v[4:7], v[4:7], v[156:159], v[0:3]
	v_mfma_f32_16x16x32_bf16 v[0:3], v[24:27], v[152:155], v[136:139]
	v_mfma_f32_16x16x32_bf16 v[16:19], v[28:31], v[200:203], v[16:19]
	v_mfma_f32_16x16x32_bf16 v[0:3], v[28:31], v[156:159], v[0:3]
	s_barrier
	v_readlane_b32 s4, v255, 18
	s_and_b64 vcc, exec, s[10:11]
	v_readlane_b32 s5, v255, 19
	s_cbranch_vccnz .LBB0_202
	s_mov_b32 m0, s19
	v_lshl_add_u64 v[26:27], v[212:213], 0, s[46:47]
	v_lshl_add_u64 v[24:25], v[212:213], 0, s[48:49]
	global_load_lds_dwordx4 v[26:27], off
	s_mov_b32 m0, s18
	s_mov_b64 s[4:5], 0
	global_load_lds_dwordx4 v[24:25], off
	s_waitcnt vmcnt(6)
.LBB0_202:
	s_barrier
	v_mfma_f32_16x16x32_bf16 v[8:11], v[128:131], v[164:167], v[8:11]
	v_mfma_f32_16x16x32_bf16 v[44:47], v[196:199], v[168:171], v[8:11]
	v_mfma_f32_16x16x32_bf16 v[8:11], v[132:135], v[164:167], v[12:15]
	v_mfma_f32_16x16x32_bf16 v[24:27], v[128:131], v[56:59], v[140:143]
	v_mfma_f32_16x16x32_bf16 v[40:43], v[192:195], v[168:171], v[8:11]
	v_mfma_f32_16x16x32_bf16 v[8:11], v[128:131], v[160:163], v[148:151]
	v_mfma_f32_16x16x32_bf16 v[60:63], v[196:199], v[204:207], v[24:27]
	v_mfma_f32_16x16x32_bf16 v[24:27], v[132:135], v[56:59], v[144:147]
	v_mfma_f32_16x16x32_bf16 v[28:31], v[196:199], v[200:203], v[8:11]
	v_mfma_f32_16x16x32_bf16 v[8:11], v[132:135], v[160:163], v[180:183]
	v_mfma_f32_16x16x32_bf16 v[56:59], v[192:195], v[204:207], v[24:27]
	v_mfma_f32_16x16x32_bf16 v[24:27], v[192:195], v[200:203], v[8:11]
	v_mfma_f32_16x16x32_bf16 v[8:11], v[128:131], v[152:155], v[184:187]
	v_mfma_f32_16x16x32_bf16 v[12:15], v[196:199], v[156:159], v[8:11]
	v_mfma_f32_16x16x32_bf16 v[8:11], v[132:135], v[152:155], v[188:191]
	v_mfma_f32_16x16x32_bf16 v[8:11], v[192:195], v[156:159], v[8:11]
	v_readlane_b32 vcc_lo, v255, 18
	v_readlane_b32 vcc_hi, v255, 19
	s_nop 3
	s_or_b64 vcc, vcc, s[10:11]
	s_cbranch_scc0 .Llate_p3_defer
	s_barrier

.Llate_p5_done:
.LBB0_365:
	ds_read_b128 v[112:115], v234
	ds_read_b128 v[116:119], v234 offset:2048
	ds_read_b128 v[136:139], v235
	ds_read_b128 v[140:143], v235 offset:2048
	v_lshl_add_u64 v[192:193], s[6:7], 0, v[222:223]
	s_mov_b32 m0, s74
	v_lshl_add_u64 v[176:177], v[192:193], 0, s[22:23]
	ds_read_b128 v[144:147], v236
	ds_read_b128 v[148:151], v236 offset:2048
	ds_read_b128 v[152:155], v237
	ds_read_b128 v[156:159], v237 offset:2048
	ds_read_b128 v[160:163], v236 offset:4096
	ds_read_b128 v[164:167], v236 offset:6144
	ds_read_b128 v[168:171], v237 offset:4096
	ds_read_b128 v[172:175], v237 offset:6144
	global_load_lds_dwordx4 v[176:177], off
	v_lshl_add_u64 v[176:177], v[192:193], 0, s[24:25]
	s_mov_b32 m0, s75
	s_nop 0
	global_load_lds_dwordx4 v[176:177], off
	s_waitcnt lgkmcnt(8)
	s_barrier
	s_waitcnt lgkmcnt(0)
	v_mfma_f32_16x16x32_bf16 v[28:31], v[112:115], v[144:147], v[28:31]
	v_mfma_f32_16x16x32_bf16 v[24:27], v[116:119], v[144:147], v[24:27]
	v_mfma_f32_16x16x32_bf16 v[44:47], v[112:115], v[148:151], v[44:47]
	v_mfma_f32_16x16x32_bf16 v[40:43], v[116:119], v[148:151], v[40:43]
	v_mfma_f32_16x16x32_bf16 v[68:71], v[112:115], v[160:163], v[68:71]
	v_mfma_f32_16x16x32_bf16 v[64:67], v[116:119], v[160:163], v[64:67]
	v_mfma_f32_16x16x32_bf16 v[100:103], v[112:115], v[164:167], v[100:103]
	v_mfma_f32_16x16x32_bf16 v[96:99], v[116:119], v[164:167], v[96:99]
	v_mfma_f32_16x16x32_bf16 v[28:31], v[136:139], v[152:155], v[28:31]
	v_mfma_f32_16x16x32_bf16 v[24:27], v[140:143], v[152:155], v[24:27]
	v_mfma_f32_16x16x32_bf16 v[44:47], v[136:139], v[156:159], v[44:47]
	v_mfma_f32_16x16x32_bf16 v[40:43], v[140:143], v[156:159], v[40:43]
	v_mfma_f32_16x16x32_bf16 v[68:71], v[136:139], v[168:171], v[68:71]
	v_mfma_f32_16x16x32_bf16 v[64:67], v[140:143], v[168:171], v[64:67]
	v_mfma_f32_16x16x32_bf16 v[100:103], v[136:139], v[172:175], v[100:103]
	v_mfma_f32_16x16x32_bf16 v[96:99], v[140:143], v[172:175], v[96:99]
	s_barrier
	v_lshl_add_u64 v[194:195], s[60:61], 0, v[222:223]
	s_mov_b32 m0, s42
	v_lshl_add_u64 v[196:197], v[194:195], 0, s[30:31]
	ds_read_b128 v[176:179], v238
	ds_read_b128 v[180:183], v238 offset:2048
	ds_read_b128 v[184:187], v239
	ds_read_b128 v[188:191], v239 offset:2048
	global_load_lds_dwordx4 v[196:197], off
	v_lshl_add_u64 v[196:197], v[194:195], 0, s[36:37]
	s_mov_b32 m0, s43
	s_nop 0
	global_load_lds_dwordx4 v[196:197], off
	s_barrier
	s_waitcnt lgkmcnt(0)
	v_mfma_f32_16x16x32_bf16 v[20:23], v[176:179], v[144:147], v[20:23]
	v_mfma_f32_16x16x32_bf16 v[16:19], v[180:183], v[144:147], v[16:19]
	v_mfma_f32_16x16x32_bf16 v[36:39], v[176:179], v[148:151], v[36:39]
	v_mfma_f32_16x16x32_bf16 v[32:35], v[180:183], v[148:151], v[32:35]
	v_mfma_f32_16x16x32_bf16 v[52:55], v[176:179], v[160:163], v[52:55]
	v_mfma_f32_16x16x32_bf16 v[48:51], v[180:183], v[160:163], v[48:51]
	v_mfma_f32_16x16x32_bf16 v[76:79], v[176:179], v[164:167], v[76:79]
	v_mfma_f32_16x16x32_bf16 v[72:75], v[180:183], v[164:167], v[72:75]
	v_mfma_f32_16x16x32_bf16 v[20:23], v[184:187], v[152:155], v[20:23]
	v_mfma_f32_16x16x32_bf16 v[16:19], v[188:191], v[152:155], v[16:19]
	v_mfma_f32_16x16x32_bf16 v[36:39], v[184:187], v[156:159], v[36:39]
	v_mfma_f32_16x16x32_bf16 v[32:35], v[188:191], v[156:159], v[32:35]
	v_mfma_f32_16x16x32_bf16 v[52:55], v[184:187], v[168:171], v[52:55]
	v_mfma_f32_16x16x32_bf16 v[48:51], v[188:191], v[168:171], v[48:51]
	v_mfma_f32_16x16x32_bf16 v[76:79], v[184:187], v[172:175], v[76:79]
	v_mfma_f32_16x16x32_bf16 v[72:75], v[188:191], v[172:175], v[72:75]
	s_barrier
	s_mov_b32 m0, s34
	v_lshl_add_u64 v[196:197], v[192:193], 0, s[30:31]
	ds_read_b128 v[144:147], v236 offset:16384
	ds_read_b128 v[148:151], v236 offset:18432
	ds_read_b128 v[152:155], v237 offset:16384
	ds_read_b128 v[156:159], v237 offset:18432
	ds_read_b128 v[160:163], v236 offset:20480
	ds_read_b128 v[164:167], v236 offset:22528
	ds_read_b128 v[168:171], v237 offset:20480
	ds_read_b128 v[172:175], v237 offset:22528
	global_load_lds_dwordx4 v[196:197], off
	v_lshl_add_u64 v[196:197], v[192:193], 0, s[36:37]
	s_mov_b32 m0, s44
	s_nop 0
	global_load_lds_dwordx4 v[196:197], off
	s_barrier
	s_waitcnt lgkmcnt(0)
	v_mfma_f32_16x16x32_bf16 v[84:87], v[112:115], v[144:147], v[84:87]
	v_mfma_f32_16x16x32_bf16 v[80:83], v[116:119], v[144:147], v[80:83]
	v_mfma_f32_16x16x32_bf16 v[108:111], v[112:115], v[148:151], v[108:111]
	v_mfma_f32_16x16x32_bf16 v[104:107], v[116:119], v[148:151], v[104:107]
	v_mfma_f32_16x16x32_bf16 v[60:63], v[112:115], v[160:163], v[60:63]
	v_mfma_f32_16x16x32_bf16 v[56:59], v[116:119], v[160:163], v[56:59]
	v_mfma_f32_16x16x32_bf16 v[4:7], v[112:115], v[164:167], v[4:7]
	v_mfma_f32_16x16x32_bf16 v[0:3], v[116:119], v[164:167], v[0:3]
	v_mfma_f32_16x16x32_bf16 v[84:87], v[136:139], v[152:155], v[84:87]
	v_mfma_f32_16x16x32_bf16 v[80:83], v[140:143], v[152:155], v[80:83]
	v_mfma_f32_16x16x32_bf16 v[108:111], v[136:139], v[156:159], v[108:111]
	v_mfma_f32_16x16x32_bf16 v[104:107], v[140:143], v[156:159], v[104:107]
	v_mfma_f32_16x16x32_bf16 v[60:63], v[136:139], v[168:171], v[60:63]
	v_mfma_f32_16x16x32_bf16 v[56:59], v[140:143], v[168:171], v[56:59]
	v_mfma_f32_16x16x32_bf16 v[4:7], v[136:139], v[172:175], v[4:7]
	v_mfma_f32_16x16x32_bf16 v[0:3], v[140:143], v[172:175], v[0:3]
	s_barrier
	v_lshl_add_u64 v[196:197], s[4:5], 0, v[222:223]
	s_mov_b32 m0, s45
	v_lshl_add_u64 v[112:113], v[196:197], 0, s[30:31]
	global_load_lds_dwordx4 v[112:113], off
	v_lshl_add_u64 v[112:113], v[196:197], 0, s[36:37]
	s_mov_b32 m0, s62
	s_nop 0
	global_load_lds_dwordx4 v[112:113], off
	s_waitcnt vmcnt(6)
	s_barrier
	v_mfma_f32_16x16x32_bf16 v[120:123], v[176:179], v[148:151], v[120:123]
	v_mfma_f32_16x16x32_bf16 v[124:127], v[180:183], v[148:151], v[124:127]
	v_mfma_f32_16x16x32_bf16 v[88:91], v[176:179], v[160:163], v[88:91]
	v_mfma_f32_16x16x32_bf16 v[92:95], v[180:183], v[160:163], v[92:95]
	v_mfma_f32_16x16x32_bf16 v[12:15], v[176:179], v[164:167], v[12:15]
	v_mfma_f32_16x16x32_bf16 v[8:11], v[180:183], v[164:167], v[8:11]
	v_mfma_f32_16x16x32_bf16 v[112:115], v[176:179], v[144:147], v[128:131]
	v_mfma_f32_16x16x32_bf16 v[116:119], v[180:183], v[144:147], v[132:135]
	v_mfma_f32_16x16x32_bf16 v[120:123], v[184:187], v[156:159], v[120:123]
	v_mfma_f32_16x16x32_bf16 v[124:127], v[188:191], v[156:159], v[124:127]
	v_mfma_f32_16x16x32_bf16 v[88:91], v[184:187], v[168:171], v[88:91]
	v_mfma_f32_16x16x32_bf16 v[92:95], v[188:191], v[168:171], v[92:95]
	v_mfma_f32_16x16x32_bf16 v[12:15], v[184:187], v[172:175], v[12:15]
	v_mfma_f32_16x16x32_bf16 v[8:11], v[188:191], v[172:175], v[8:11]
	v_mfma_f32_16x16x32_bf16 v[112:115], v[184:187], v[152:155], v[112:115]
	v_mfma_f32_16x16x32_bf16 v[116:119], v[188:191], v[152:155], v[116:119]
	s_barrier
	ds_read_b128 v[128:131], v240
	ds_read_b128 v[132:135], v240 offset:2048
	ds_read_b128 v[136:139], v241
	ds_read_b128 v[140:143], v241 offset:2048
	s_mov_b64 s[80:81], 0x80100
	s_mov_b32 m0, s63
	v_lshl_add_u64 v[176:177], v[192:193], 0, s[80:81]
	s_mov_b64 s[80:81], 0xc0100
	ds_read_b128 v[144:147], v236 offset:32768
	ds_read_b128 v[148:151], v236 offset:34816
	ds_read_b128 v[152:155], v237 offset:32768
	ds_read_b128 v[156:159], v237 offset:34816
	ds_read_b128 v[160:163], v236 offset:36864
	ds_read_b128 v[164:167], v236 offset:38912
	ds_read_b128 v[168:171], v237 offset:36864
	ds_read_b128 v[172:175], v237 offset:38912
	global_load_lds_dwordx4 v[176:177], off
	v_lshl_add_u64 v[176:177], v[192:193], 0, s[80:81]
	s_mov_b32 m0, s64
	s_nop 0
	global_load_lds_dwordx4 v[176:177], off
	s_waitcnt lgkmcnt(8)
	s_barrier
	s_waitcnt lgkmcnt(0)
	v_mfma_f32_16x16x32_bf16 v[28:31], v[128:131], v[144:147], v[28:31]
	v_mfma_f32_16x16x32_bf16 v[24:27], v[132:135], v[144:147], v[24:27]
	v_mfma_f32_16x16x32_bf16 v[44:47], v[128:131], v[148:151], v[44:47]
	v_mfma_f32_16x16x32_bf16 v[40:43], v[132:135], v[148:151], v[40:43]
	v_mfma_f32_16x16x32_bf16 v[68:71], v[128:131], v[160:163], v[68:71]
	v_mfma_f32_16x16x32_bf16 v[64:67], v[132:135], v[160:163], v[64:67]
	v_mfma_f32_16x16x32_bf16 v[100:103], v[128:131], v[164:167], v[100:103]
	v_mfma_f32_16x16x32_bf16 v[96:99], v[132:135], v[164:167], v[96:99]
	v_mfma_f32_16x16x32_bf16 v[28:31], v[136:139], v[152:155], v[28:31]
	v_mfma_f32_16x16x32_bf16 v[24:27], v[140:143], v[152:155], v[24:27]
	v_mfma_f32_16x16x32_bf16 v[44:47], v[136:139], v[156:159], v[44:47]
	v_mfma_f32_16x16x32_bf16 v[40:43], v[140:143], v[156:159], v[40:43]
	v_mfma_f32_16x16x32_bf16 v[68:71], v[136:139], v[168:171], v[68:71]
	v_mfma_f32_16x16x32_bf16 v[64:67], v[140:143], v[168:171], v[64:67]
	v_mfma_f32_16x16x32_bf16 v[100:103], v[136:139], v[172:175], v[100:103]
	v_mfma_f32_16x16x32_bf16 v[96:99], v[140:143], v[172:175], v[96:99]
	s_barrier
	s_mov_b32 m0, s65
	v_lshl_add_u64 v[198:199], v[194:195], 0, s[38:39]
	ds_read_b128 v[176:179], v242
	ds_read_b128 v[180:183], v242 offset:2048
	ds_read_b128 v[184:187], v243
	ds_read_b128 v[188:191], v243 offset:2048
	global_load_lds_dwordx4 v[198:199], off
	v_lshl_add_u64 v[194:195], v[194:195], 0, s[40:41]
	s_mov_b32 m0, s68
	s_nop 0
	global_load_lds_dwordx4 v[194:195], off
	s_barrier
	s_waitcnt lgkmcnt(0)
	v_mfma_f32_16x16x32_bf16 v[20:23], v[176:179], v[144:147], v[20:23]
	v_mfma_f32_16x16x32_bf16 v[16:19], v[180:183], v[144:147], v[16:19]
	v_mfma_f32_16x16x32_bf16 v[36:39], v[176:179], v[148:151], v[36:39]
	v_mfma_f32_16x16x32_bf16 v[32:35], v[180:183], v[148:151], v[32:35]
	v_mfma_f32_16x16x32_bf16 v[52:55], v[176:179], v[160:163], v[52:55]
	v_mfma_f32_16x16x32_bf16 v[48:51], v[180:183], v[160:163], v[48:51]
	v_mfma_f32_16x16x32_bf16 v[76:79], v[176:179], v[164:167], v[76:79]
	v_mfma_f32_16x16x32_bf16 v[72:75], v[180:183], v[164:167], v[72:75]
	v_mfma_f32_16x16x32_bf16 v[20:23], v[184:187], v[152:155], v[20:23]
	v_mfma_f32_16x16x32_bf16 v[16:19], v[188:191], v[152:155], v[16:19]
	v_mfma_f32_16x16x32_bf16 v[36:39], v[184:187], v[156:159], v[36:39]
	v_mfma_f32_16x16x32_bf16 v[32:35], v[188:191], v[156:159], v[32:35]
	v_mfma_f32_16x16x32_bf16 v[52:55], v[184:187], v[168:171], v[52:55]
	v_mfma_f32_16x16x32_bf16 v[48:51], v[188:191], v[168:171], v[48:51]
	v_mfma_f32_16x16x32_bf16 v[76:79], v[184:187], v[172:175], v[76:79]
	v_mfma_f32_16x16x32_bf16 v[72:75], v[188:191], v[172:175], v[72:75]
	s_barrier
	s_mov_b32 m0, s69
	v_lshl_add_u64 v[194:195], v[192:193], 0, s[38:39]
	ds_read_b128 v[144:147], v236 offset:49152
	ds_read_b128 v[148:151], v236 offset:51200
	ds_read_b128 v[152:155], v237 offset:49152
	ds_read_b128 v[156:159], v237 offset:51200
	ds_read_b128 v[160:163], v236 offset:53248
	ds_read_b128 v[164:167], v236 offset:55296
	ds_read_b128 v[168:171], v237 offset:53248
	ds_read_b128 v[172:175], v237 offset:55296
	global_load_lds_dwordx4 v[194:195], off
	v_lshl_add_u64 v[192:193], v[192:193], 0, s[40:41]
	s_mov_b32 m0, s70
	s_nop 0
	global_load_lds_dwordx4 v[192:193], off
	s_barrier
; template <int K, int EPI, bool MIX = false>
; __device__ __forceinline__ void gemm_phase(const Params& p, const u16* __restrict__ A, const u16* __restrict__ Bt,
;                            const float* __restrict__ rs_in, float* __restrict__ ssq_out, float alpha, bool rev = false) {
;     ...
;           int fr_m = fr;
;           asm volatile("" : "+v"(fr_m));
; #pragma unroll
;           for (int ai = 0; ai < 2; ++ai)
; #pragma unroll
;             for (int m = 0; m < 4; ++m) {
;               const int row = pm * 256 + ai * 128 + wr * 64 + m * 16 + fr_m;
;               const float ra = rsqrtf(p.ssqa[row] * (1.f / 1024.f) + 1e-6f);
;               const float rb = rsqrtf(p.ssqb[row] * (1.f / 1024.f) + 1e-6f);
;               const float f = ra * __builtin_amdgcn_rcpf(rb);
; #pragma unroll
;               for (int bj = 0; bj < 2; ++bj)
; #pragma unroll
;                 for (int n = 0; n < 2; ++n) acc[ai][bj][m][n] *= f;
;             }
	s_waitcnt lgkmcnt(0)
	v_mfma_f32_16x16x32_bf16 v[84:87], v[128:131], v[144:147], v[84:87]
	v_mfma_f32_16x16x32_bf16 v[80:83], v[132:135], v[144:147], v[80:83]
	v_mfma_f32_16x16x32_bf16 v[108:111], v[128:131], v[148:151], v[108:111]
	v_mfma_f32_16x16x32_bf16 v[104:107], v[132:135], v[148:151], v[104:107]
	v_mfma_f32_16x16x32_bf16 v[60:63], v[128:131], v[160:163], v[60:63]
	v_mfma_f32_16x16x32_bf16 v[56:59], v[132:135], v[160:163], v[56:59]
	v_mfma_f32_16x16x32_bf16 v[4:7], v[128:131], v[164:167], v[4:7]
	v_mfma_f32_16x16x32_bf16 v[0:3], v[132:135], v[164:167], v[0:3]
	v_mfma_f32_16x16x32_bf16 v[84:87], v[136:139], v[152:155], v[84:87]
	v_mfma_f32_16x16x32_bf16 v[80:83], v[140:143], v[152:155], v[80:83]
	v_mfma_f32_16x16x32_bf16 v[108:111], v[136:139], v[156:159], v[108:111]
	v_mfma_f32_16x16x32_bf16 v[104:107], v[140:143], v[156:159], v[104:107]
	v_mfma_f32_16x16x32_bf16 v[60:63], v[136:139], v[168:171], v[60:63]
	v_mfma_f32_16x16x32_bf16 v[56:59], v[140:143], v[168:171], v[56:59]
	v_mfma_f32_16x16x32_bf16 v[4:7], v[136:139], v[172:175], v[4:7]
	v_mfma_f32_16x16x32_bf16 v[0:3], v[140:143], v[172:175], v[0:3]
	s_barrier
	s_mov_b32 m0, s71
	v_lshl_add_u64 v[128:129], v[196:197], 0, s[38:39]
	global_load_lds_dwordx4 v[128:129], off
	v_lshl_add_u64 v[128:129], v[196:197], 0, s[40:41]
	s_mov_b32 m0, s72
	s_nop 0
	global_load_lds_dwordx4 v[128:129], off
	s_waitcnt vmcnt(6)
	s_barrier
	v_mfma_f32_16x16x32_bf16 v[112:115], v[176:179], v[144:147], v[112:115]
	v_mfma_f32_16x16x32_bf16 v[128:131], v[184:187], v[152:155], v[112:115]
	v_mfma_f32_16x16x32_bf16 v[112:115], v[180:183], v[144:147], v[116:119]
	v_mfma_f32_16x16x32_bf16 v[132:135], v[188:191], v[152:155], v[112:115]
	v_mfma_f32_16x16x32_bf16 v[112:115], v[176:179], v[148:151], v[120:123]
	v_mfma_f32_16x16x32_bf16 v[120:123], v[184:187], v[156:159], v[112:115]
	v_mfma_f32_16x16x32_bf16 v[112:115], v[180:183], v[148:151], v[124:127]
	v_mfma_f32_16x16x32_bf16 v[88:91], v[176:179], v[160:163], v[88:91]
	v_mfma_f32_16x16x32_bf16 v[92:95], v[180:183], v[160:163], v[92:95]
	v_mfma_f32_16x16x32_bf16 v[12:15], v[176:179], v[164:167], v[12:15]
	v_mfma_f32_16x16x32_bf16 v[8:11], v[180:183], v[164:167], v[8:11]
	v_mfma_f32_16x16x32_bf16 v[124:127], v[188:191], v[156:159], v[112:115]
	v_mfma_f32_16x16x32_bf16 v[88:91], v[184:187], v[168:171], v[88:91]
	v_mfma_f32_16x16x32_bf16 v[92:95], v[188:191], v[168:171], v[92:95]
	v_mfma_f32_16x16x32_bf16 v[12:15], v[184:187], v[172:175], v[12:15]
	v_mfma_f32_16x16x32_bf16 v[8:11], v[188:191], v[172:175], v[8:11]
	s_barrier
	s_add_i32 s33, s33, 2
	s_add_u32 s60, s60, 0x100
	s_addc_u32 s61, s61, 0
	s_add_u32 s6, s6, 0x100
	s_addc_u32 s7, s7, 0
	s_add_u32 s4, s4, 0x100
	s_addc_u32 s5, s5, 0
	s_cmp_lt_u32 s33, 14
	s_cbranch_scc1 .LBB0_365
	v_mov_b32_e32 v112, v233
	s_lshl_b32 s79, s35, 8
	s_add_i32 s79, s79, s73
	v_add_u32_e32 v112, s79, v112
	v_ashrrev_i32_e32 v113, 31, v112
	v_lshlrev_b64 v[112:113], 2, v[112:113]
	v_lshl_add_u64 v[138:139], s[86:87], 0, v[112:113]
	global_load_dword v114, v[138:139], off
	v_lshl_add_u64 v[136:137], s[88:89], 0, v[112:113]
	global_load_dword v112, v[136:137], off
	s_mov_b32 s33, 14
	s_mov_b64 s[4:5], s[16:17]
	s_mov_b64 s[6:7], s[8:9]
	s_mov_b64 s[60:61], s[12:13]
	s_waitcnt vmcnt(0)
	v_fmamk_f32 v114, v114, 0x3a800000, v244
	v_cmp_gt_f32_e32 vcc, s76, v114
	v_mul_f32_e32 v115, 0x4b800000, v114
	v_fmamk_f32 v112, v112, 0x3a800000, v244
	v_cndmask_b32_e32 v114, v114, v115, vcc
	v_rsq_f32_e32 v114, v114
	v_mul_f32_e32 v113, 0x4b800000, v112
	v_mul_f32_e32 v115, 0x45800000, v114
	v_cndmask_b32_e32 v114, v114, v115, vcc
	v_cmp_gt_f32_e32 vcc, s76, v112
	s_nop 1
	v_cndmask_b32_e32 v112, v112, v113, vcc
	v_rsq_f32_e32 v112, v112
	s_nop 0
	v_mul_f32_e32 v113, 0x45800000, v112
	v_cndmask_b32_e32 v112, v112, v113, vcc
	v_rcp_f32_e32 v112, v112
	s_nop 0
	v_mul_f32_e32 v112, v114, v112
	v_pk_mul_f32 v[30:31], v[30:31], v[112:113] op_sel_hi:[1,0]
	v_pk_mul_f32 v[28:29], v[28:29], v[112:113] op_sel_hi:[1,0]
	v_pk_mul_f32 v[26:27], v[26:27], v[112:113] op_sel_hi:[1,0]
	v_pk_mul_f32 v[24:25], v[24:25], v[112:113] op_sel_hi:[1,0]
	v_pk_mul_f32 v[22:23], v[22:23], v[112:113] op_sel_hi:[1,0]
	v_pk_mul_f32 v[20:21], v[20:21], v[112:113] op_sel_hi:[1,0]
	v_pk_mul_f32 v[18:19], v[18:19], v[112:113] op_sel_hi:[1,0]
	v_pk_mul_f32 v[16:17], v[16:17], v[112:113] op_sel_hi:[1,0]
	global_load_dword v112, v[138:139], off offset:64
	s_waitcnt vmcnt(0)
	v_fmamk_f32 v112, v112, 0x3a800000, v244
	v_cmp_gt_f32_e32 vcc, s76, v112
	v_mul_f32_e32 v113, 0x4b800000, v112
	s_nop 0
	v_cndmask_b32_e32 v112, v112, v113, vcc
	v_rsq_f32_e32 v112, v112
	s_nop 0
	v_mul_f32_e32 v113, 0x45800000, v112
	v_cndmask_b32_e32 v112, v112, v113, vcc
	global_load_dword v113, v[136:137], off offset:64
	s_waitcnt vmcnt(0)
	v_fmamk_f32 v113, v113, 0x3a800000, v244
	v_cmp_gt_f32_e32 vcc, s76, v113
	v_mul_f32_e32 v114, 0x4b800000, v113
	s_nop 0
	v_cndmask_b32_e32 v113, v113, v114, vcc
	v_rsq_f32_e32 v113, v113
	s_nop 0
	v_mul_f32_e32 v114, 0x45800000, v113
	v_cndmask_b32_e32 v113, v113, v114, vcc
	v_rcp_f32_e32 v113, v113
	s_nop 0
	v_mul_f32_e32 v112, v112, v113
	v_pk_mul_f32 v[46:47], v[46:47], v[112:113] op_sel_hi:[1,0]
	v_pk_mul_f32 v[44:45], v[44:45], v[112:113] op_sel_hi:[1,0]
	v_pk_mul_f32 v[42:43], v[42:43], v[112:113] op_sel_hi:[1,0]
	v_pk_mul_f32 v[40:41], v[40:41], v[112:113] op_sel_hi:[1,0]
	v_pk_mul_f32 v[38:39], v[38:39], v[112:113] op_sel_hi:[1,0]
	v_pk_mul_f32 v[36:37], v[36:37], v[112:113] op_sel_hi:[1,0]
	v_pk_mul_f32 v[34:35], v[34:35], v[112:113] op_sel_hi:[1,0]
	v_pk_mul_f32 v[32:33], v[32:33], v[112:113] op_sel_hi:[1,0]
	global_load_dword v112, v[138:139], off offset:128
	s_waitcnt vmcnt(0)
; template <int K, int EPI, bool MIX = false>
; __device__ __forceinline__ void gemm_phase(const Params& p, const u16* __restrict__ A, const u16* __restrict__ Bt,
;                            const float* __restrict__ rs_in, float* __restrict__ ssq_out, float alpha, bool rev = false) {
;     ...
;           int fr_m = fr;
;           asm volatile("" : "+v"(fr_m));
; #pragma unroll
;           for (int ai = 0; ai < 2; ++ai)
; #pragma unroll
;             for (int m = 0; m < 4; ++m) {
;               const int row = pm * 256 + ai * 128 + wr * 64 + m * 16 + fr_m;
;               const float ra = rsqrtf(p.ssqa[row] * (1.f / 1024.f) + 1e-6f);
;               const float rb = rsqrtf(p.ssqb[row] * (1.f / 1024.f) + 1e-6f);
;               const float f = ra * __builtin_amdgcn_rcpf(rb);
; #pragma unroll
;               for (int bj = 0; bj < 2; ++bj)
; #pragma unroll
;                 for (int n = 0; n < 2; ++n) acc[ai][bj][m][n] *= f;
;             }
	v_fmamk_f32 v112, v112, 0x3a800000, v244
	v_cmp_gt_f32_e32 vcc, s76, v112
	v_mul_f32_e32 v113, 0x4b800000, v112
	s_nop 0
	v_cndmask_b32_e32 v112, v112, v113, vcc
	v_rsq_f32_e32 v112, v112
	s_nop 0
	v_mul_f32_e32 v113, 0x45800000, v112
	v_cndmask_b32_e32 v112, v112, v113, vcc
	global_load_dword v113, v[136:137], off offset:128
	s_waitcnt vmcnt(0)
	v_fmamk_f32 v113, v113, 0x3a800000, v244
	v_cmp_gt_f32_e32 vcc, s76, v113
	v_mul_f32_e32 v114, 0x4b800000, v113
	s_nop 0
	v_cndmask_b32_e32 v113, v113, v114, vcc
	v_rsq_f32_e32 v113, v113
	s_nop 0
	v_mul_f32_e32 v114, 0x45800000, v113
	v_cndmask_b32_e32 v113, v113, v114, vcc
	v_rcp_f32_e32 v113, v113
	s_nop 0
	v_mul_f32_e32 v112, v112, v113
	v_pk_mul_f32 v[70:71], v[70:71], v[112:113] op_sel_hi:[1,0]
	v_pk_mul_f32 v[68:69], v[68:69], v[112:113] op_sel_hi:[1,0]
	v_pk_mul_f32 v[66:67], v[66:67], v[112:113] op_sel_hi:[1,0]
	v_pk_mul_f32 v[64:65], v[64:65], v[112:113] op_sel_hi:[1,0]
	v_pk_mul_f32 v[54:55], v[54:55], v[112:113] op_sel_hi:[1,0]
	v_pk_mul_f32 v[52:53], v[52:53], v[112:113] op_sel_hi:[1,0]
	v_pk_mul_f32 v[50:51], v[50:51], v[112:113] op_sel_hi:[1,0]
	v_pk_mul_f32 v[48:49], v[48:49], v[112:113] op_sel_hi:[1,0]
	global_load_dword v112, v[138:139], off offset:192
	s_waitcnt vmcnt(0)
	v_fmamk_f32 v112, v112, 0x3a800000, v244
	v_cmp_gt_f32_e32 vcc, s76, v112
	v_mul_f32_e32 v113, 0x4b800000, v112
	s_nop 0
	v_cndmask_b32_e32 v112, v112, v113, vcc
	v_rsq_f32_e32 v112, v112
	s_nop 0
	v_mul_f32_e32 v113, 0x45800000, v112
	v_cndmask_b32_e32 v112, v112, v113, vcc
	global_load_dword v113, v[136:137], off offset:192
	s_waitcnt vmcnt(0)
	v_fmamk_f32 v113, v113, 0x3a800000, v244
	v_cmp_gt_f32_e32 vcc, s76, v113
	v_mul_f32_e32 v114, 0x4b800000, v113
	s_nop 0
	v_cndmask_b32_e32 v113, v113, v114, vcc
	v_rsq_f32_e32 v113, v113
	s_nop 0
	v_mul_f32_e32 v114, 0x45800000, v113
	v_cndmask_b32_e32 v113, v113, v114, vcc
	v_rcp_f32_e32 v113, v113
	s_nop 0
	v_mul_f32_e32 v140, v112, v113
	v_pk_mul_f32 v[112:113], v[96:97], v[140:141] op_sel_hi:[1,0]
	global_load_dword v96, v[138:139], off offset:512
	v_pk_mul_f32 v[114:115], v[98:99], v[140:141] op_sel_hi:[1,0]
	v_pk_mul_f32 v[118:119], v[102:103], v[140:141] op_sel_hi:[1,0]
	v_pk_mul_f32 v[116:117], v[100:101], v[140:141] op_sel_hi:[1,0]
	v_pk_mul_f32 v[78:79], v[78:79], v[140:141] op_sel_hi:[1,0]
	v_pk_mul_f32 v[76:77], v[76:77], v[140:141] op_sel_hi:[1,0]
	v_pk_mul_f32 v[74:75], v[74:75], v[140:141] op_sel_hi:[1,0]
	v_pk_mul_f32 v[72:73], v[72:73], v[140:141] op_sel_hi:[1,0]
	s_waitcnt vmcnt(0)
	v_fmamk_f32 v96, v96, 0x3a800000, v244
	v_cmp_gt_f32_e32 vcc, s76, v96
	v_mul_f32_e32 v97, 0x4b800000, v96
	s_nop 0
	v_cndmask_b32_e32 v96, v96, v97, vcc
	v_rsq_f32_e32 v96, v96
	s_nop 0
	v_mul_f32_e32 v97, 0x45800000, v96
	v_cndmask_b32_e32 v96, v96, v97, vcc
	global_load_dword v97, v[136:137], off offset:512
	s_waitcnt vmcnt(0)
	v_fmamk_f32 v97, v97, 0x3a800000, v244
	v_cmp_gt_f32_e32 vcc, s76, v97
	v_mul_f32_e32 v98, 0x4b800000, v97
	s_nop 0
	v_cndmask_b32_e32 v97, v97, v98, vcc
	v_rsq_f32_e32 v97, v97
	s_nop 0
	v_mul_f32_e32 v98, 0x45800000, v97
	v_cndmask_b32_e32 v97, v97, v98, vcc
	v_rcp_f32_e32 v97, v97
	s_nop 0
	v_mul_f32_e32 v140, v96, v97
	v_pk_mul_f32 v[96:97], v[80:81], v[140:141] op_sel_hi:[1,0]
	v_pk_mul_f32 v[80:81], v[128:129], v[140:141] op_sel_hi:[1,0]
	global_load_dword v128, v[138:139], off offset:576
	v_pk_mul_f32 v[98:99], v[82:83], v[140:141] op_sel_hi:[1,0]
	v_pk_mul_f32 v[82:83], v[130:131], v[140:141] op_sel_hi:[1,0]
	v_pk_mul_f32 v[102:103], v[86:87], v[140:141] op_sel_hi:[1,0]
	v_pk_mul_f32 v[100:101], v[84:85], v[140:141] op_sel_hi:[1,0]
	v_pk_mul_f32 v[86:87], v[134:135], v[140:141] op_sel_hi:[1,0]
	v_pk_mul_f32 v[84:85], v[132:133], v[140:141] op_sel_hi:[1,0]
	s_waitcnt vmcnt(0)
	v_fmamk_f32 v128, v128, 0x3a800000, v244
	v_cmp_gt_f32_e32 vcc, s76, v128
	v_mul_f32_e32 v129, 0x4b800000, v128
	s_nop 0
	v_cndmask_b32_e32 v128, v128, v129, vcc
	v_rsq_f32_e32 v128, v128
	s_nop 0
	v_mul_f32_e32 v129, 0x45800000, v128
	v_cndmask_b32_e32 v128, v128, v129, vcc
	global_load_dword v129, v[136:137], off offset:576
	s_waitcnt vmcnt(0)
	v_fmamk_f32 v129, v129, 0x3a800000, v244
	v_cmp_gt_f32_e32 vcc, s76, v129
	v_mul_f32_e32 v130, 0x4b800000, v129
	s_nop 0
	v_cndmask_b32_e32 v129, v129, v130, vcc
	v_rsq_f32_e32 v129, v129
	s_nop 0
	v_mul_f32_e32 v130, 0x45800000, v129
	v_cndmask_b32_e32 v129, v129, v130, vcc
	v_rcp_f32_e32 v129, v129
	s_nop 0
	v_mul_f32_e32 v140, v128, v129
	v_pk_mul_f32 v[128:129], v[104:105], v[140:141] op_sel_hi:[1,0]
	v_pk_mul_f32 v[104:105], v[120:121], v[140:141] op_sel_hi:[1,0]
	global_load_dword v120, v[138:139], off offset:640
	v_pk_mul_f32 v[130:131], v[106:107], v[140:141] op_sel_hi:[1,0]
	v_pk_mul_f32 v[106:107], v[122:123], v[140:141] op_sel_hi:[1,0]
	v_pk_mul_f32 v[134:135], v[110:111], v[140:141] op_sel_hi:[1,0]
	v_pk_mul_f32 v[132:133], v[108:109], v[140:141] op_sel_hi:[1,0]
	v_pk_mul_f32 v[110:111], v[126:127], v[140:141] op_sel_hi:[1,0]
	v_pk_mul_f32 v[108:109], v[124:125], v[140:141] op_sel_hi:[1,0]
	s_waitcnt vmcnt(0)
	v_fmamk_f32 v120, v120, 0x3a800000, v244
	v_cmp_gt_f32_e32 vcc, s76, v120
	v_mul_f32_e32 v121, 0x4b800000, v120
	s_nop 0
	v_cndmask_b32_e32 v120, v120, v121, vcc
	v_rsq_f32_e32 v120, v120
	s_nop 0
	v_mul_f32_e32 v121, 0x45800000, v120
	v_cndmask_b32_e32 v120, v120, v121, vcc
	global_load_dword v121, v[136:137], off offset:640
	s_waitcnt vmcnt(0)
; template <int K, int EPI, bool MIX = false>
; __device__ __forceinline__ void gemm_phase(const Params& p, const u16* __restrict__ A, const u16* __restrict__ Bt,
;                            const float* __restrict__ rs_in, float* __restrict__ ssq_out, float alpha, bool rev = false) {
;     ...
;           int fr_m = fr;
;           asm volatile("" : "+v"(fr_m));
; #pragma unroll
;           for (int ai = 0; ai < 2; ++ai)
; #pragma unroll
;             for (int m = 0; m < 4; ++m) {
;               const int row = pm * 256 + ai * 128 + wr * 64 + m * 16 + fr_m;
;               const float ra = rsqrtf(p.ssqa[row] * (1.f / 1024.f) + 1e-6f);
;               const float rb = rsqrtf(p.ssqb[row] * (1.f / 1024.f) + 1e-6f);
;               const float f = ra * __builtin_amdgcn_rcpf(rb);
; #pragma unroll
;               for (int bj = 0; bj < 2; ++bj)
; #pragma unroll
;                 for (int n = 0; n < 2; ++n) acc[ai][bj][m][n] *= f;
;             }
	v_fmamk_f32 v121, v121, 0x3a800000, v244
	v_cmp_gt_f32_e32 vcc, s76, v121
	v_mul_f32_e32 v122, 0x4b800000, v121
	s_nop 0
	v_cndmask_b32_e32 v121, v121, v122, vcc
	v_rsq_f32_e32 v121, v121
	s_nop 0
	v_mul_f32_e32 v122, 0x45800000, v121
	v_cndmask_b32_e32 v121, v121, v122, vcc
	v_rcp_f32_e32 v121, v121
	s_nop 0
	v_mul_f32_e32 v140, v120, v121
	v_pk_mul_f32 v[120:121], v[56:57], v[140:141] op_sel_hi:[1,0]
	v_pk_mul_f32 v[56:57], v[88:89], v[140:141] op_sel_hi:[1,0]
	global_load_dword v88, v[138:139], off offset:704
	v_pk_mul_f32 v[122:123], v[58:59], v[140:141] op_sel_hi:[1,0]
	v_pk_mul_f32 v[58:59], v[90:91], v[140:141] op_sel_hi:[1,0]
	v_pk_mul_f32 v[126:127], v[62:63], v[140:141] op_sel_hi:[1,0]
	v_pk_mul_f32 v[124:125], v[60:61], v[140:141] op_sel_hi:[1,0]
	v_pk_mul_f32 v[62:63], v[94:95], v[140:141] op_sel_hi:[1,0]
	v_pk_mul_f32 v[60:61], v[92:93], v[140:141] op_sel_hi:[1,0]
	s_waitcnt vmcnt(0)
	v_fmamk_f32 v88, v88, 0x3a800000, v244
	v_cmp_gt_f32_e32 vcc, s76, v88
	v_mul_f32_e32 v89, 0x4b800000, v88
	s_nop 0
	v_cndmask_b32_e32 v88, v88, v89, vcc
	v_rsq_f32_e32 v88, v88
	s_nop 0
	v_mul_f32_e32 v89, 0x45800000, v88
	v_cndmask_b32_e32 v88, v88, v89, vcc
	global_load_dword v89, v[136:137], off offset:704
	s_waitcnt vmcnt(0)
	v_fmamk_f32 v89, v89, 0x3a800000, v244
	v_cmp_gt_f32_e32 vcc, s76, v89
	v_mul_f32_e32 v90, 0x4b800000, v89
	s_nop 0
	v_cndmask_b32_e32 v89, v89, v90, vcc
	v_rsq_f32_e32 v89, v89
	s_nop 0
	v_mul_f32_e32 v90, 0x45800000, v89
	v_cndmask_b32_e32 v89, v89, v90, vcc
	v_rcp_f32_e32 v89, v89
	s_nop 0
	v_mul_f32_e32 v136, v88, v89
	v_pk_mul_f32 v[90:91], v[6:7], v[136:137] op_sel_hi:[1,0]
	v_pk_mul_f32 v[88:89], v[4:5], v[136:137] op_sel_hi:[1,0]
	v_pk_mul_f32 v[94:95], v[2:3], v[136:137] op_sel_hi:[1,0]
	v_pk_mul_f32 v[92:93], v[0:1], v[136:137] op_sel_hi:[1,0]
	v_pk_mul_f32 v[2:3], v[14:15], v[136:137] op_sel_hi:[1,0]
	v_pk_mul_f32 v[0:1], v[12:13], v[136:137] op_sel_hi:[1,0]
	v_pk_mul_f32 v[6:7], v[10:11], v[136:137] op_sel_hi:[1,0]
	v_pk_mul_f32 v[4:5], v[8:9], v[136:137] op_sel_hi:[1,0]
.LBB0_367:
	ds_read_b128 v[8:11], v234
	ds_read_b128 v[12:15], v234 offset:2048
	ds_read_b128 v[136:139], v235
	ds_read_b128 v[140:143], v235 offset:2048
	v_lshl_add_u64 v[192:193], s[6:7], 0, v[222:223]
	s_mov_b64 s[80:81], 0x80880
	s_mov_b32 m0, s74
	v_lshl_add_u64 v[176:177], v[192:193], 0, s[80:81]
	s_mov_b64 s[80:81], 0xc0880
	ds_read_b128 v[144:147], v236
	ds_read_b128 v[148:151], v236 offset:2048
	ds_read_b128 v[152:155], v237
	ds_read_b128 v[156:159], v237 offset:2048
	ds_read_b128 v[160:163], v236 offset:4096
	ds_read_b128 v[164:167], v236 offset:6144
	ds_read_b128 v[168:171], v237 offset:4096
	ds_read_b128 v[172:175], v237 offset:6144
	global_load_lds_dwordx4 v[176:177], off
	v_lshl_add_u64 v[176:177], v[192:193], 0, s[80:81]
	s_mov_b32 m0, s75
	s_nop 0
	global_load_lds_dwordx4 v[176:177], off
	s_waitcnt lgkmcnt(8)
	s_barrier
	s_waitcnt lgkmcnt(0)
	v_mfma_f32_16x16x32_bf16 v[28:31], v[8:11], v[144:147], v[28:31]
	v_mfma_f32_16x16x32_bf16 v[24:27], v[12:15], v[144:147], v[24:27]
	v_mfma_f32_16x16x32_bf16 v[44:47], v[8:11], v[148:151], v[44:47]
	v_mfma_f32_16x16x32_bf16 v[40:43], v[12:15], v[148:151], v[40:43]
	v_mfma_f32_16x16x32_bf16 v[68:71], v[8:11], v[160:163], v[68:71]
	v_mfma_f32_16x16x32_bf16 v[64:67], v[12:15], v[160:163], v[64:67]
	v_mfma_f32_16x16x32_bf16 v[116:119], v[8:11], v[164:167], v[116:119]
	v_mfma_f32_16x16x32_bf16 v[112:115], v[12:15], v[164:167], v[112:115]
	v_mfma_f32_16x16x32_bf16 v[28:31], v[136:139], v[152:155], v[28:31]
	v_mfma_f32_16x16x32_bf16 v[24:27], v[140:143], v[152:155], v[24:27]
	v_mfma_f32_16x16x32_bf16 v[44:47], v[136:139], v[156:159], v[44:47]
	v_mfma_f32_16x16x32_bf16 v[40:43], v[140:143], v[156:159], v[40:43]
	v_mfma_f32_16x16x32_bf16 v[68:71], v[136:139], v[168:171], v[68:71]
	v_mfma_f32_16x16x32_bf16 v[64:67], v[140:143], v[168:171], v[64:67]
	v_mfma_f32_16x16x32_bf16 v[116:119], v[136:139], v[172:175], v[116:119]
	v_mfma_f32_16x16x32_bf16 v[112:115], v[140:143], v[172:175], v[112:115]
	s_barrier
	v_lshl_add_u64 v[194:195], s[60:61], 0, v[222:223]
	s_mov_b32 m0, s42
	v_lshl_add_u64 v[196:197], v[194:195], 0, s[46:47]
	ds_read_b128 v[176:179], v238
	ds_read_b128 v[180:183], v238 offset:2048
	ds_read_b128 v[184:187], v239
	ds_read_b128 v[188:191], v239 offset:2048
	global_load_lds_dwordx4 v[196:197], off
	v_lshl_add_u64 v[196:197], v[194:195], 0, s[48:49]
	s_mov_b32 m0, s43
	s_nop 0
	global_load_lds_dwordx4 v[196:197], off
	s_barrier
	s_waitcnt lgkmcnt(0)
	v_mfma_f32_16x16x32_bf16 v[20:23], v[176:179], v[144:147], v[20:23]
	v_mfma_f32_16x16x32_bf16 v[16:19], v[180:183], v[144:147], v[16:19]
	v_mfma_f32_16x16x32_bf16 v[36:39], v[176:179], v[148:151], v[36:39]
	v_mfma_f32_16x16x32_bf16 v[32:35], v[180:183], v[148:151], v[32:35]
	v_mfma_f32_16x16x32_bf16 v[52:55], v[176:179], v[160:163], v[52:55]
	v_mfma_f32_16x16x32_bf16 v[48:51], v[180:183], v[160:163], v[48:51]
	v_mfma_f32_16x16x32_bf16 v[76:79], v[176:179], v[164:167], v[76:79]
	v_mfma_f32_16x16x32_bf16 v[72:75], v[180:183], v[164:167], v[72:75]
	v_mfma_f32_16x16x32_bf16 v[20:23], v[184:187], v[152:155], v[20:23]
	v_mfma_f32_16x16x32_bf16 v[16:19], v[188:191], v[152:155], v[16:19]
	v_mfma_f32_16x16x32_bf16 v[36:39], v[184:187], v[156:159], v[36:39]
	v_mfma_f32_16x16x32_bf16 v[32:35], v[188:191], v[156:159], v[32:35]
	v_mfma_f32_16x16x32_bf16 v[52:55], v[184:187], v[168:171], v[52:55]
	v_mfma_f32_16x16x32_bf16 v[48:51], v[188:191], v[168:171], v[48:51]
	v_mfma_f32_16x16x32_bf16 v[76:79], v[184:187], v[172:175], v[76:79]
	v_mfma_f32_16x16x32_bf16 v[72:75], v[188:191], v[172:175], v[72:75]
	s_barrier
	s_mov_b32 m0, s34
	v_lshl_add_u64 v[196:197], v[192:193], 0, s[46:47]
	ds_read_b128 v[144:147], v236 offset:16384
	ds_read_b128 v[148:151], v236 offset:18432
	ds_read_b128 v[152:155], v237 offset:16384
	ds_read_b128 v[156:159], v237 offset:18432
	ds_read_b128 v[160:163], v236 offset:20480
	ds_read_b128 v[164:167], v236 offset:22528
	ds_read_b128 v[168:171], v237 offset:20480
	ds_read_b128 v[172:175], v237 offset:22528
	global_load_lds_dwordx4 v[196:197], off
	v_lshl_add_u64 v[196:197], v[192:193], 0, s[48:49]
	s_mov_b32 m0, s44
	s_nop 0
	global_load_lds_dwordx4 v[196:197], off
	s_barrier
	s_waitcnt lgkmcnt(0)
	v_mfma_f32_16x16x32_bf16 v[100:103], v[8:11], v[144:147], v[100:103]
	v_mfma_f32_16x16x32_bf16 v[96:99], v[12:15], v[144:147], v[96:99]
	v_mfma_f32_16x16x32_bf16 v[132:135], v[8:11], v[148:151], v[132:135]
	v_mfma_f32_16x16x32_bf16 v[128:131], v[12:15], v[148:151], v[128:131]
	v_mfma_f32_16x16x32_bf16 v[124:127], v[8:11], v[160:163], v[124:127]
	v_mfma_f32_16x16x32_bf16 v[120:123], v[12:15], v[160:163], v[120:123]
	v_mfma_f32_16x16x32_bf16 v[100:103], v[136:139], v[152:155], v[100:103]
	v_mfma_f32_16x16x32_bf16 v[96:99], v[140:143], v[152:155], v[96:99]
	v_mfma_f32_16x16x32_bf16 v[132:135], v[136:139], v[156:159], v[132:135]
	v_mfma_f32_16x16x32_bf16 v[128:131], v[140:143], v[156:159], v[128:131]
	v_mfma_f32_16x16x32_bf16 v[124:127], v[136:139], v[168:171], v[124:127]
	v_mfma_f32_16x16x32_bf16 v[120:123], v[140:143], v[168:171], v[120:123]
	v_mfma_f32_16x16x32_bf16 v[8:11], v[8:11], v[164:167], v[88:91]
	v_mfma_f32_16x16x32_bf16 v[12:15], v[12:15], v[164:167], v[92:95]
	v_mfma_f32_16x16x32_bf16 v[8:11], v[136:139], v[172:175], v[8:11]
	v_mfma_f32_16x16x32_bf16 v[12:15], v[140:143], v[172:175], v[12:15]
	s_barrier
	v_lshl_add_u64 v[196:197], s[4:5], 0, v[222:223]
	s_mov_b32 m0, s45
	v_lshl_add_u64 v[88:89], v[196:197], 0, s[46:47]
	global_load_lds_dwordx4 v[88:89], off
	v_lshl_add_u64 v[88:89], v[196:197], 0, s[48:49]
	s_mov_b32 m0, s62
	s_nop 0
	global_load_lds_dwordx4 v[88:89], off
	s_waitcnt vmcnt(6)
	s_barrier
	v_mfma_f32_16x16x32_bf16 v[88:91], v[176:179], v[148:151], v[104:107]
	v_mfma_f32_16x16x32_bf16 v[80:83], v[176:179], v[144:147], v[80:83]
	v_mfma_f32_16x16x32_bf16 v[84:87], v[180:183], v[144:147], v[84:87]
	v_mfma_f32_16x16x32_bf16 v[104:107], v[184:187], v[156:159], v[88:91]
	v_mfma_f32_16x16x32_bf16 v[88:91], v[180:183], v[148:151], v[108:111]
	v_mfma_f32_16x16x32_bf16 v[56:59], v[176:179], v[160:163], v[56:59]
	v_mfma_f32_16x16x32_bf16 v[60:63], v[180:183], v[160:163], v[60:63]
	v_mfma_f32_16x16x32_bf16 v[0:3], v[176:179], v[164:167], v[0:3]
	v_mfma_f32_16x16x32_bf16 v[4:7], v[180:183], v[164:167], v[4:7]
	v_mfma_f32_16x16x32_bf16 v[80:83], v[184:187], v[152:155], v[80:83]
	v_mfma_f32_16x16x32_bf16 v[84:87], v[188:191], v[152:155], v[84:87]
	v_mfma_f32_16x16x32_bf16 v[108:111], v[188:191], v[156:159], v[88:91]
	v_mfma_f32_16x16x32_bf16 v[56:59], v[184:187], v[168:171], v[56:59]
	v_mfma_f32_16x16x32_bf16 v[60:63], v[188:191], v[168:171], v[60:63]
	v_mfma_f32_16x16x32_bf16 v[0:3], v[184:187], v[172:175], v[0:3]
	v_mfma_f32_16x16x32_bf16 v[4:7], v[188:191], v[172:175], v[4:7]
	s_barrier
	ds_read_b128 v[88:91], v240
	ds_read_b128 v[92:95], v240 offset:2048
	ds_read_b128 v[136:139], v241
	ds_read_b128 v[140:143], v241 offset:2048
	s_mov_b64 s[80:81], 0x80900
	s_mov_b32 m0, s63
	v_lshl_add_u64 v[176:177], v[192:193], 0, s[80:81]
	s_mov_b64 s[80:81], 0xc0900
	ds_read_b128 v[144:147], v236 offset:32768
	ds_read_b128 v[148:151], v236 offset:34816
	ds_read_b128 v[152:155], v237 offset:32768
	ds_read_b128 v[156:159], v237 offset:34816
	ds_read_b128 v[160:163], v236 offset:36864
	ds_read_b128 v[164:167], v236 offset:38912
	ds_read_b128 v[168:171], v237 offset:36864
	ds_read_b128 v[172:175], v237 offset:38912
	global_load_lds_dwordx4 v[176:177], off
	v_lshl_add_u64 v[176:177], v[192:193], 0, s[80:81]
	s_mov_b32 m0, s64
	s_nop 0
	global_load_lds_dwordx4 v[176:177], off
	s_waitcnt lgkmcnt(8)
	s_barrier
	s_waitcnt lgkmcnt(0)
	v_mfma_f32_16x16x32_bf16 v[28:31], v[88:91], v[144:147], v[28:31]
	v_mfma_f32_16x16x32_bf16 v[24:27], v[92:95], v[144:147], v[24:27]
	v_mfma_f32_16x16x32_bf16 v[44:47], v[88:91], v[148:151], v[44:47]
	v_mfma_f32_16x16x32_bf16 v[40:43], v[92:95], v[148:151], v[40:43]
	v_mfma_f32_16x16x32_bf16 v[68:71], v[88:91], v[160:163], v[68:71]
	v_mfma_f32_16x16x32_bf16 v[64:67], v[92:95], v[160:163], v[64:67]
	v_mfma_f32_16x16x32_bf16 v[116:119], v[88:91], v[164:167], v[116:119]
	v_mfma_f32_16x16x32_bf16 v[112:115], v[92:95], v[164:167], v[112:115]
	v_mfma_f32_16x16x32_bf16 v[28:31], v[136:139], v[152:155], v[28:31]
	v_mfma_f32_16x16x32_bf16 v[24:27], v[140:143], v[152:155], v[24:27]
	v_mfma_f32_16x16x32_bf16 v[44:47], v[136:139], v[156:159], v[44:47]
	v_mfma_f32_16x16x32_bf16 v[40:43], v[140:143], v[156:159], v[40:43]
	v_mfma_f32_16x16x32_bf16 v[68:71], v[136:139], v[168:171], v[68:71]
	v_mfma_f32_16x16x32_bf16 v[64:67], v[140:143], v[168:171], v[64:67]
	v_mfma_f32_16x16x32_bf16 v[116:119], v[136:139], v[172:175], v[116:119]
	v_mfma_f32_16x16x32_bf16 v[112:115], v[140:143], v[172:175], v[112:115]
	s_barrier
	s_mov_b32 m0, s65
	v_lshl_add_u64 v[198:199], v[194:195], 0, s[50:51]
	ds_read_b128 v[176:179], v242
	ds_read_b128 v[180:183], v242 offset:2048
	ds_read_b128 v[184:187], v243
	ds_read_b128 v[188:191], v243 offset:2048
	global_load_lds_dwordx4 v[198:199], off
	v_lshl_add_u64 v[194:195], v[194:195], 0, s[58:59]
	s_mov_b32 m0, s68
	s_nop 0
	global_load_lds_dwordx4 v[194:195], off
	s_barrier
	s_waitcnt lgkmcnt(0)
	v_mfma_f32_16x16x32_bf16 v[20:23], v[176:179], v[144:147], v[20:23]
	v_mfma_f32_16x16x32_bf16 v[16:19], v[180:183], v[144:147], v[16:19]
	v_mfma_f32_16x16x32_bf16 v[36:39], v[176:179], v[148:151], v[36:39]
	v_mfma_f32_16x16x32_bf16 v[32:35], v[180:183], v[148:151], v[32:35]
	v_mfma_f32_16x16x32_bf16 v[52:55], v[176:179], v[160:163], v[52:55]
	v_mfma_f32_16x16x32_bf16 v[48:51], v[180:183], v[160:163], v[48:51]
	v_mfma_f32_16x16x32_bf16 v[76:79], v[176:179], v[164:167], v[76:79]
	v_mfma_f32_16x16x32_bf16 v[72:75], v[180:183], v[164:167], v[72:75]
	v_mfma_f32_16x16x32_bf16 v[20:23], v[184:187], v[152:155], v[20:23]
	v_mfma_f32_16x16x32_bf16 v[16:19], v[188:191], v[152:155], v[16:19]
	v_mfma_f32_16x16x32_bf16 v[36:39], v[184:187], v[156:159], v[36:39]
	v_mfma_f32_16x16x32_bf16 v[32:35], v[188:191], v[156:159], v[32:35]
	v_mfma_f32_16x16x32_bf16 v[52:55], v[184:187], v[168:171], v[52:55]
	v_mfma_f32_16x16x32_bf16 v[48:51], v[188:191], v[168:171], v[48:51]
	v_mfma_f32_16x16x32_bf16 v[76:79], v[184:187], v[172:175], v[76:79]
	v_mfma_f32_16x16x32_bf16 v[72:75], v[188:191], v[172:175], v[72:75]
	s_barrier
	s_mov_b32 m0, s69
	v_lshl_add_u64 v[194:195], v[192:193], 0, s[50:51]
	ds_read_b128 v[144:147], v236 offset:49152
	ds_read_b128 v[148:151], v236 offset:51200
	ds_read_b128 v[152:155], v237 offset:49152
	ds_read_b128 v[156:159], v237 offset:51200
	ds_read_b128 v[160:163], v236 offset:53248
	ds_read_b128 v[164:167], v236 offset:55296
	ds_read_b128 v[168:171], v237 offset:53248
	ds_read_b128 v[172:175], v237 offset:55296
	global_load_lds_dwordx4 v[194:195], off
	v_lshl_add_u64 v[192:193], v[192:193], 0, s[58:59]
	s_mov_b32 m0, s70
	s_nop 0
	global_load_lds_dwordx4 v[192:193], off
	s_barrier
	s_waitcnt lgkmcnt(0)
	v_mfma_f32_16x16x32_bf16 v[8:11], v[88:91], v[164:167], v[8:11]
	v_mfma_f32_16x16x32_bf16 v[100:103], v[88:91], v[144:147], v[100:103]
	v_mfma_f32_16x16x32_bf16 v[96:99], v[92:95], v[144:147], v[96:99]
	v_mfma_f32_16x16x32_bf16 v[132:135], v[88:91], v[148:151], v[132:135]
	v_mfma_f32_16x16x32_bf16 v[128:131], v[92:95], v[148:151], v[128:131]
	v_mfma_f32_16x16x32_bf16 v[124:127], v[88:91], v[160:163], v[124:127]
	v_mfma_f32_16x16x32_bf16 v[120:123], v[92:95], v[160:163], v[120:123]
	v_mfma_f32_16x16x32_bf16 v[88:91], v[136:139], v[172:175], v[8:11]
	v_mfma_f32_16x16x32_bf16 v[8:11], v[92:95], v[164:167], v[12:15]
	v_mfma_f32_16x16x32_bf16 v[100:103], v[136:139], v[152:155], v[100:103]
	v_mfma_f32_16x16x32_bf16 v[96:99], v[140:143], v[152:155], v[96:99]
	v_mfma_f32_16x16x32_bf16 v[132:135], v[136:139], v[156:159], v[132:135]
	v_mfma_f32_16x16x32_bf16 v[128:131], v[140:143], v[156:159], v[128:131]
	v_mfma_f32_16x16x32_bf16 v[124:127], v[136:139], v[168:171], v[124:127]
	v_mfma_f32_16x16x32_bf16 v[120:123], v[140:143], v[168:171], v[120:123]
	v_mfma_f32_16x16x32_bf16 v[92:95], v[140:143], v[172:175], v[8:11]
	s_barrier
	s_mov_b32 m0, s71
	v_lshl_add_u64 v[8:9], v[196:197], 0, s[50:51]
	global_load_lds_dwordx4 v[8:9], off
	v_lshl_add_u64 v[8:9], v[196:197], 0, s[58:59]
	s_mov_b32 m0, s72
	s_nop 0
	global_load_lds_dwordx4 v[8:9], off
	s_waitcnt vmcnt(6)
	s_barrier
	v_mfma_f32_16x16x32_bf16 v[8:11], v[176:179], v[144:147], v[80:83]
	v_mfma_f32_16x16x32_bf16 v[80:83], v[184:187], v[152:155], v[8:11]
	v_mfma_f32_16x16x32_bf16 v[8:11], v[180:183], v[144:147], v[84:87]
	v_mfma_f32_16x16x32_bf16 v[84:87], v[188:191], v[152:155], v[8:11]
	v_mfma_f32_16x16x32_bf16 v[8:11], v[176:179], v[148:151], v[104:107]
	v_mfma_f32_16x16x32_bf16 v[104:107], v[184:187], v[156:159], v[8:11]
	v_mfma_f32_16x16x32_bf16 v[8:11], v[180:183], v[148:151], v[108:111]
	v_mfma_f32_16x16x32_bf16 v[108:111], v[188:191], v[156:159], v[8:11]
	v_mfma_f32_16x16x32_bf16 v[8:11], v[176:179], v[160:163], v[56:59]
	v_mfma_f32_16x16x32_bf16 v[56:59], v[184:187], v[168:171], v[8:11]
	v_mfma_f32_16x16x32_bf16 v[8:11], v[180:183], v[160:163], v[60:63]
	v_mfma_f32_16x16x32_bf16 v[0:3], v[176:179], v[164:167], v[0:3]
	v_mfma_f32_16x16x32_bf16 v[4:7], v[180:183], v[164:167], v[4:7]
	v_mfma_f32_16x16x32_bf16 v[60:63], v[188:191], v[168:171], v[8:11]
	v_mfma_f32_16x16x32_bf16 v[0:3], v[184:187], v[172:175], v[0:3]
	v_mfma_f32_16x16x32_bf16 v[4:7], v[188:191], v[172:175], v[4:7]
	s_barrier
; #define LDA(dst,b,h) _Pragma("unroll") for(int m=0;m<4;++m) _Pragma("unroll") for(int k=0;k<2;++k) \
;     dst[m][k]=*reinterpret_cast<const bf16x8*>(SA(b,h)+(wr*64+m*16)*128+koff[k])
; #define LDB(dst,b,h) _Pragma("unroll") for(int n=0;n<2;++n) _Pragma("unroll") for(int k=0;k<2;++k) \
;     dst[n][k]=*reinterpret_cast<const bf16x8*>(SB(b,h)+(wc*32+n*16)*128+koff[k])
; #define MMA(ai,bj,Af,Bf) do{__builtin_amdgcn_s_setprio(1); \
;     _Pragma("unroll") for(int m=0;m<4;++m) _Pragma("unroll") for(int n=0;n<2;++n) _Pragma("unroll") for(int k=0;k<2;++k) \
;       acc[ai][bj][m][n]=__builtin_amdgcn_mfma_f32_16x16x32_bf16(Bf[n][k],Af[m][k],acc[ai][bj][m][n],0,0,0); \
;     __builtin_amdgcn_s_setprio(0);}while(0)
; #define WAIT_L(n) asm volatile("s_waitcnt lgkmcnt(" #n ")":::"memory")
; #define BAR __builtin_amdgcn_s_barrier()
; #define SCHED __builtin_amdgcn_sched_barrier(0)
; #define STAGE_A(b,h,kt) do{ unsigned char* _d = SA(b,h) + wbase; \
;     if constexpr (BLK) { const char* _s = baseA + ((size_t)(h)*(K/64) + (kt)) * 16384; GLDS(_s + voa, _d); GLDS(_s + 8192 + voa, _d + 8192); } \
;     else { const char* _s = baseA + ((size_t)(h)*128*K + (kt)*64) * 2; GLDS(_s + voa, _d); GLDS(_s + (size_t)128*K + voa, _d + 8192); } }while(0)
; template <int K, int EPI, bool MIX = false>
; __device__ __forceinline__ void gemm_phase(const Params& p, const u16* __restrict__ A, const u16* __restrict__ Bt,
;                            const float* __restrict__ rs_in, float* __restrict__ ssq_out, float alpha, bool rev = false) {
;     ...
;     float rsq[2][4];
;     if constexpr (EPI == EPI_SWIGLU || EPI == EPI_Z || MIX) {
;       const float* rsrc = MIX ? p.ssqb : rs_in;
;       int fr_p = fr;
;       asm volatile("" : "+v"(fr_p));
; #pragma unroll
;       for (int ai = 0; ai < 2; ++ai)
; #pragma unroll
;         for (int m = 0; m < 4; ++m) rsq[ai][m] = rsrc[cpm * 256 + ai * 128 + wr * 64 + m * 16 + fr_p];
;     }
;     ++it;
;     id = item_id(it);
;     const bool more = id < ntiles;
;     if (rev) id = ntiles - 1 - id;
;     {
;       LDB(B0,0,0); SCHED; LDA(At,0,0); STAGE_A(1,1,nt-1);
;       WAIT_L(8); BAR; WAIT_L(0); MMA(0,0,At,B0); BAR; SCHED;
;       if (more) SETUP_TILE();
	s_add_i32 s33, s33, 2
	s_add_u32 s60, s60, 0x100
	s_addc_u32 s61, s61, 0
	s_add_u32 s6, s6, 0x100
	s_addc_u32 s7, s7, 0
	s_add_u32 s4, s4, 0x100
	s_addc_u32 s5, s5, 0
	s_cmp_lt_u32 s33, 28
	s_cbranch_scc1 .LBB0_367
	v_mov_b32_e32 v8, v233
	s_add_i32 s77, s77, 1
	v_add_u32_e32 v8, s79, v8
	v_ashrrev_i32_e32 v9, 31, v8
	v_lshl_add_u64 v[8:9], v[8:9], 2, s[88:89]
	global_load_dword v253, v[8:9], off
	global_load_dword v252, v[8:9], off offset:64
	global_load_dword v251, v[8:9], off offset:128
	global_load_dword v250, v[8:9], off offset:192
	global_load_dword v249, v[8:9], off offset:512
	global_load_dword v248, v[8:9], off offset:576
	global_load_dword v247, v[8:9], off offset:640
	global_load_dword v246, v[8:9], off offset:704
	ds_read_b128 v[136:139], v234
	ds_read_b128 v[140:143], v234 offset:2048
	ds_read_b128 v[148:151], v235
	ds_read_b128 v[144:147], v235 offset:2048
	s_mul_i32 s4, s77, s57
	s_add_i32 s4, s4, s56
	v_lshl_add_u64 v[8:9], s[8:9], 0, v[220:221]
	s_mov_b64 s[6:7], 0x80f80
	s_mov_b32 m0, s74
	v_lshl_add_u64 v[10:11], v[8:9], 0, s[6:7]
	s_mov_b64 s[6:7], 0xc0f80
	ds_read_b128 v[176:179], v236
	ds_read_b128 v[164:167], v236 offset:2048
	ds_read_b128 v[180:183], v237
	ds_read_b128 v[168:171], v237 offset:2048
	ds_read_b128 v[152:155], v236 offset:4096
	ds_read_b128 v[156:159], v236 offset:6144
	ds_read_b128 v[172:175], v237 offset:4096
	ds_read_b128 v[160:163], v237 offset:6144
	global_load_lds_dwordx4 v[10:11], off
	v_lshl_add_u64 v[8:9], v[8:9], 0, s[6:7]
	s_mov_b32 m0, s75
	s_nop 0
	global_load_lds_dwordx4 v[8:9], off
	s_waitcnt lgkmcnt(8)
	s_barrier
	s_waitcnt lgkmcnt(0)
	v_mfma_f32_16x16x32_bf16 v[8:11], v[136:139], v[176:179], v[28:31]
	s_cmpk_lt_i32 s4, 0x600
	s_cselect_b64 s[6:7], -1, 0
	s_cmpk_gt_i32 s4, 0x5ff
	v_mfma_f32_16x16x32_bf16 v[12:15], v[140:143], v[176:179], v[24:27]
	v_mfma_f32_16x16x32_bf16 v[24:27], v[136:139], v[164:167], v[44:47]
	v_mfma_f32_16x16x32_bf16 v[28:31], v[140:143], v[164:167], v[40:43]
	v_mfma_f32_16x16x32_bf16 v[40:43], v[136:139], v[152:155], v[68:71]
	v_mfma_f32_16x16x32_bf16 v[44:47], v[140:143], v[152:155], v[64:67]
	v_mfma_f32_16x16x32_bf16 v[64:67], v[136:139], v[156:159], v[116:119]
	v_mfma_f32_16x16x32_bf16 v[68:71], v[140:143], v[156:159], v[112:115]
	v_mfma_f32_16x16x32_bf16 v[8:11], v[148:151], v[180:183], v[8:11]
	v_mfma_f32_16x16x32_bf16 v[12:15], v[144:147], v[180:183], v[12:15]
	v_mfma_f32_16x16x32_bf16 v[24:27], v[148:151], v[168:171], v[24:27]
	v_mfma_f32_16x16x32_bf16 v[28:31], v[144:147], v[168:171], v[28:31]
	v_mfma_f32_16x16x32_bf16 v[40:43], v[148:151], v[172:175], v[40:43]
	v_mfma_f32_16x16x32_bf16 v[44:47], v[144:147], v[172:175], v[44:47]
	v_mfma_f32_16x16x32_bf16 v[64:67], v[148:151], v[160:163], v[64:67]
	v_mfma_f32_16x16x32_bf16 v[68:71], v[144:147], v[160:163], v[68:71]
	s_barrier
	s_mov_b32 s33, s78
	s_cbranch_scc1 .LBB0_370
	s_ashr_i32 s5, s4, 31
	s_lshr_b32 s5, s5, 26
	s_add_i32 s5, s4, s5
	s_ashr_i32 s8, s5, 6
	s_andn2_b32 s5, s5, 63
	s_lshl_b32 s8, s8, 3
	s_sub_i32 s5, s4, s5
	s_and_b32 s4, s4, 7
	s_or_b32 s35, s8, s4
	s_lshl_b32 s4, s35, 8
	s_ashr_i32 s33, s5, 3
	s_ashr_i32 s5, s4, 31
	s_lshl_b64 s[4:5], s[4:5], 12
	s_add_u32 s8, s94, s4
	s_addc_u32 s9, s95, s5
	s_lshl_b32 s4, s33, 8
	s_ashr_i32 s5, s4, 31
	s_lshl_b64 s[4:5], s[4:5], 12
	v_readlane_b32 s80, v254, 32
	v_readlane_b32 s81, v254, 33
	s_add_u32 s12, s80, s4
	v_readlane_b32 s84, v254, 36
	v_readlane_b32 s85, v254, 37
	v_readlane_b32 s86, v254, 38
	v_readlane_b32 s87, v254, 39
	v_readlane_b32 s88, v254, 40
	v_readlane_b32 s89, v254, 41
	v_readlane_b32 s90, v254, 42
	v_readlane_b32 s91, v254, 43
	s_addc_u32 s13, s81, s5
	v_readlane_b32 s84, v254, 0
	s_add_u32 s16, s12, 0x80000
	v_readlane_b32 s90, v254, 6
	v_readlane_b32 s91, v254, 7
	s_addc_u32 s17, s13, 0
	v_readlane_b32 s82, v254, 34
	v_readlane_b32 s83, v254, 35
	v_readlane_b32 s92, v254, 44
	v_readlane_b32 s93, v254, 45
	v_readlane_b32 s94, v254, 46
	v_readlane_b32 s95, v254, 47
	v_readlane_b32 s85, v254, 1
	v_readlane_b32 s86, v254, 2
	v_readlane_b32 s87, v254, 3
	v_readlane_b32 s88, v254, 4
	v_readlane_b32 s89, v254, 5

; #define LDA(dst,b,h) _Pragma("unroll") for(int m=0;m<4;++m) _Pragma("unroll") for(int k=0;k<2;++k) \
;     dst[m][k]=*reinterpret_cast<const bf16x8*>(SA(b,h)+(wr*64+m*16)*128+koff[k])
; #define LDB(dst,b,h) _Pragma("unroll") for(int n=0;n<2;++n) _Pragma("unroll") for(int k=0;k<2;++k) \
;     dst[n][k]=*reinterpret_cast<const bf16x8*>(SB(b,h)+(wc*32+n*16)*128+koff[k])
; #define MMA(ai,bj,Af,Bf) do{__builtin_amdgcn_s_setprio(1); \
;     _Pragma("unroll") for(int m=0;m<4;++m) _Pragma("unroll") for(int n=0;n<2;++n) _Pragma("unroll") for(int k=0;k<2;++k) \
;       acc[ai][bj][m][n]=__builtin_amdgcn_mfma_f32_16x16x32_bf16(Bf[n][k],Af[m][k],acc[ai][bj][m][n],0,0,0); \
;     __builtin_amdgcn_s_setprio(0);}while(0)
; #define WAIT_V(n) asm volatile("s_waitcnt vmcnt(" #n ")":::"memory")
; #define WAIT_L(n) asm volatile("s_waitcnt lgkmcnt(" #n ")":::"memory")
; #define BAR __builtin_amdgcn_s_barrier()
; #define SCHED __builtin_amdgcn_sched_barrier(0)
; template <int K, int EPI, bool MIX = false>
; __device__ __forceinline__ void gemm_phase(const Params& p, const u16* __restrict__ A, const u16* __restrict__ Bt,
;                            const float* __restrict__ rs_in, float* __restrict__ ssq_out, float alpha, bool rev = false) {
;     ...
;       LDB(B0,0,0); SCHED; LDA(At,0,0); STAGE_A(1,1,nt-1);
;       WAIT_L(8); BAR; WAIT_L(0); MMA(0,0,At,B0); BAR; SCHED;
;       if (more) SETUP_TILE();
;       LDB(B1,0,1); if (more) STAGE_B(0,0,0);
;       BAR; WAIT_L(0); MMA(0,1,At,B1); BAR;
;       LDA(At,0,1); if (more) STAGE_A(0,0,0);
;       BAR; WAIT_L(0); MMA(1,0,At,B0); BAR; SCHED;
;       if (more) { STAGE_B(0,1,0); WAIT_V(6); } else { WAIT_V(0); }
;       BAR; MMA(1,1,At,B1); BAR;
;       LDB(B0,1,0); SCHED; LDA(At,1,0); if (more) STAGE_A(0,1,0);
;       WAIT_L(8); BAR; WAIT_L(0); MMA(0,0,At,B0); BAR; SCHED;
;       LDB(B1,1,1); if (more) STAGE_B(1,0,1);
;       BAR; WAIT_L(0); MMA(0,1,At,B1); BAR;
;       LDA(At,1,1); if (more) STAGE_A(1,0,1);
;       BAR; WAIT_L(0); MMA(1,0,At,B0); BAR; SCHED;
;       if (more) { STAGE_B(1,1,1); WAIT_V(6); }
;       BAR; MMA(1,1,At,B1); BAR;
.LBB0_372:
	s_barrier
	s_waitcnt lgkmcnt(0)
	v_mfma_f32_16x16x32_bf16 v[20:23], v[112:115], v[176:179], v[20:23]
	v_mfma_f32_16x16x32_bf16 v[16:19], v[116:119], v[176:179], v[16:19]
	v_mfma_f32_16x16x32_bf16 v[36:39], v[112:115], v[164:167], v[36:39]
	v_mfma_f32_16x16x32_bf16 v[32:35], v[116:119], v[164:167], v[32:35]
	v_mfma_f32_16x16x32_bf16 v[52:55], v[112:115], v[152:155], v[52:55]
	v_mfma_f32_16x16x32_bf16 v[48:51], v[116:119], v[152:155], v[48:51]
	v_mfma_f32_16x16x32_bf16 v[76:79], v[112:115], v[156:159], v[76:79]
	v_mfma_f32_16x16x32_bf16 v[72:75], v[116:119], v[156:159], v[72:75]
	v_mfma_f32_16x16x32_bf16 v[20:23], v[192:195], v[180:183], v[20:23]
	v_mfma_f32_16x16x32_bf16 v[16:19], v[196:199], v[180:183], v[16:19]
	v_mfma_f32_16x16x32_bf16 v[36:39], v[192:195], v[168:171], v[36:39]
	v_mfma_f32_16x16x32_bf16 v[32:35], v[196:199], v[168:171], v[32:35]
	v_mfma_f32_16x16x32_bf16 v[52:55], v[192:195], v[172:175], v[52:55]
	v_mfma_f32_16x16x32_bf16 v[48:51], v[196:199], v[172:175], v[48:51]
	v_mfma_f32_16x16x32_bf16 v[152:155], v[192:195], v[160:163], v[76:79]
	v_mfma_f32_16x16x32_bf16 v[156:159], v[196:199], v[160:163], v[72:75]
	s_barrier
	ds_read_b128 v[176:179], v236 offset:16384
	ds_read_b128 v[180:183], v236 offset:18432
	ds_read_b128 v[204:207], v237 offset:16384
	ds_read_b128 v[184:187], v237 offset:18432
	ds_read_b128 v[188:191], v236 offset:20480
	ds_read_b128 v[72:75], v236 offset:22528
	ds_read_b128 v[200:203], v237 offset:20480
	ds_read_b128 v[76:79], v237 offset:22528
	s_and_b64 vcc, exec, s[4:5]
	v_lshl_add_u64 v[226:227], s[8:9], 0, v[220:221]
	s_cbranch_vccnz .LBB0_374
	s_mov_b32 m0, s34
	v_lshl_add_u64 v[160:161], v[226:227], 0, s[10:11]
	global_load_lds_dwordx4 v[226:227], off
	s_mov_b32 m0, s44
	s_nop 0
	global_load_lds_dwordx4 v[160:161], off
.LBB0_374:
	s_barrier
	s_waitcnt lgkmcnt(0)
	v_mfma_f32_16x16x32_bf16 v[96:99], v[140:143], v[176:179], v[96:99]
	v_mfma_f32_16x16x32_bf16 v[164:167], v[144:147], v[204:207], v[96:99]
	v_mfma_f32_16x16x32_bf16 v[96:99], v[136:139], v[180:183], v[132:135]
	v_mfma_f32_16x16x32_bf16 v[132:135], v[148:151], v[184:187], v[96:99]
	v_mfma_f32_16x16x32_bf16 v[96:99], v[140:143], v[180:183], v[128:131]
	v_mfma_f32_16x16x32_bf16 v[128:131], v[144:147], v[184:187], v[96:99]
	v_mfma_f32_16x16x32_bf16 v[96:99], v[136:139], v[188:191], v[124:127]
	v_mfma_f32_16x16x32_bf16 v[88:91], v[136:139], v[72:75], v[88:91]
	v_mfma_f32_16x16x32_bf16 v[100:103], v[136:139], v[176:179], v[100:103]
	v_mfma_f32_16x16x32_bf16 v[168:171], v[148:151], v[200:203], v[96:99]
	v_mfma_f32_16x16x32_bf16 v[96:99], v[140:143], v[188:191], v[120:123]
	v_mfma_f32_16x16x32_bf16 v[136:139], v[148:151], v[76:79], v[88:91]
	v_mfma_f32_16x16x32_bf16 v[88:91], v[140:143], v[72:75], v[92:95]
	v_mfma_f32_16x16x32_bf16 v[160:163], v[148:151], v[204:207], v[100:103]
	v_mfma_f32_16x16x32_bf16 v[172:175], v[144:147], v[200:203], v[96:99]
	v_mfma_f32_16x16x32_bf16 v[140:143], v[144:147], v[76:79], v[88:91]
	s_barrier
	s_mov_b64 s[6:7], -1
	s_and_b64 vcc, exec, s[4:5]
	v_lshl_add_u64 v[224:225], s[16:17], 0, v[220:221]
	s_cbranch_vccnz .LBB0_376
	s_mov_b32 m0, s45
	v_lshl_add_u64 v[88:89], v[224:225], 0, s[10:11]
	global_load_lds_dwordx4 v[224:225], off
	s_mov_b32 m0, s62
	s_mov_b64 s[6:7], 0
	global_load_lds_dwordx4 v[88:89], off
	s_waitcnt vmcnt(6)

; #define LDA(dst,b,h) _Pragma("unroll") for(int m=0;m<4;++m) _Pragma("unroll") for(int k=0;k<2;++k) \
;     dst[m][k]=*reinterpret_cast<const bf16x8*>(SA(b,h)+(wr*64+m*16)*128+koff[k])
; #define LDB(dst,b,h) _Pragma("unroll") for(int n=0;n<2;++n) _Pragma("unroll") for(int k=0;k<2;++k) \
;     dst[n][k]=*reinterpret_cast<const bf16x8*>(SB(b,h)+(wc*32+n*16)*128+koff[k])
; #define MMA(ai,bj,Af,Bf) do{__builtin_amdgcn_s_setprio(1); \
;     _Pragma("unroll") for(int m=0;m<4;++m) _Pragma("unroll") for(int n=0;n<2;++n) _Pragma("unroll") for(int k=0;k<2;++k) \
;       acc[ai][bj][m][n]=__builtin_amdgcn_mfma_f32_16x16x32_bf16(Bf[n][k],Af[m][k],acc[ai][bj][m][n],0,0,0); \
;     __builtin_amdgcn_s_setprio(0);}while(0)
; #define WAIT_V(n) asm volatile("s_waitcnt vmcnt(" #n ")":::"memory")
; #define WAIT_L(n) asm volatile("s_waitcnt lgkmcnt(" #n ")":::"memory")
; #define BAR __builtin_amdgcn_s_barrier()
; #define SCHED __builtin_amdgcn_sched_barrier(0)
; template <int K, int EPI, bool MIX = false>
; __device__ __forceinline__ void gemm_phase(const Params& p, const u16* __restrict__ A, const u16* __restrict__ Bt,
;                            const float* __restrict__ rs_in, float* __restrict__ ssq_out, float alpha, bool rev = false) {
;     ...
;       LDB(B0,0,0); SCHED; LDA(At,0,0); STAGE_A(1,1,nt-1);
;       WAIT_L(8); BAR; WAIT_L(0); MMA(0,0,At,B0); BAR; SCHED;
;       if (more) SETUP_TILE();
;       LDB(B1,0,1); if (more) STAGE_B(0,0,0);
;       BAR; WAIT_L(0); MMA(0,1,At,B1); BAR;
;       LDA(At,0,1); if (more) STAGE_A(0,0,0);
;       BAR; WAIT_L(0); MMA(1,0,At,B0); BAR; SCHED;
;       if (more) { STAGE_B(0,1,0); WAIT_V(6); } else { WAIT_V(0); }
;       BAR; MMA(1,1,At,B1); BAR;
;       LDB(B0,1,0); SCHED; LDA(At,1,0); if (more) STAGE_A(0,1,0);
;       WAIT_L(8); BAR; WAIT_L(0); MMA(0,0,At,B0); BAR; SCHED;
;       LDB(B1,1,1); if (more) STAGE_B(1,0,1);
;       BAR; WAIT_L(0); MMA(0,1,At,B1); BAR;
;       LDA(At,1,1); if (more) STAGE_A(1,0,1);
;       BAR; WAIT_L(0); MMA(1,0,At,B0); BAR; SCHED;
;       if (more) { STAGE_B(1,1,1); WAIT_V(6); }
;       BAR; MMA(1,1,At,B1); BAR;
.LBB0_378:
	s_barrier
	v_mfma_f32_16x16x32_bf16 v[80:83], v[112:115], v[176:179], v[80:83]
	v_mfma_f32_16x16x32_bf16 v[144:147], v[192:195], v[204:207], v[80:83]
	v_mfma_f32_16x16x32_bf16 v[80:83], v[116:119], v[176:179], v[84:87]
	v_mfma_f32_16x16x32_bf16 v[148:151], v[196:199], v[204:207], v[80:83]
	v_mfma_f32_16x16x32_bf16 v[80:83], v[112:115], v[180:183], v[104:107]
	v_mfma_f32_16x16x32_bf16 v[176:179], v[192:195], v[184:187], v[80:83]
	v_mfma_f32_16x16x32_bf16 v[80:83], v[116:119], v[180:183], v[108:111]
	v_mfma_f32_16x16x32_bf16 v[56:59], v[112:115], v[188:191], v[56:59]
	v_mfma_f32_16x16x32_bf16 v[0:3], v[112:115], v[72:75], v[0:3]
	v_mfma_f32_16x16x32_bf16 v[180:183], v[196:199], v[184:187], v[80:83]
	v_mfma_f32_16x16x32_bf16 v[184:187], v[192:195], v[200:203], v[56:59]
	v_mfma_f32_16x16x32_bf16 v[56:59], v[116:119], v[188:191], v[60:63]
	v_mfma_f32_16x16x32_bf16 v[192:195], v[192:195], v[76:79], v[0:3]
	v_mfma_f32_16x16x32_bf16 v[0:3], v[116:119], v[72:75], v[4:7]
	v_mfma_f32_16x16x32_bf16 v[188:191], v[196:199], v[200:203], v[56:59]
	v_mfma_f32_16x16x32_bf16 v[196:199], v[196:199], v[76:79], v[0:3]
	s_barrier
	s_nop 3
	ds_read_b128 v[0:3], v240
	ds_read_b128 v[4:7], v240 offset:2048
	ds_read_b128 v[204:207], v241
	ds_read_b128 v[200:203], v241 offset:2048
	ds_read_b128 v[100:103], v236 offset:32768
	ds_read_b128 v[84:87], v236 offset:34816
	ds_read_b128 v[112:115], v237 offset:32768
	ds_read_b128 v[96:99], v237 offset:34816
	ds_read_b128 v[80:83], v236 offset:36864
	ds_read_b128 v[56:59], v236 offset:38912
	ds_read_b128 v[216:219], v237 offset:36864
	ds_read_b128 v[60:63], v237 offset:38912
	s_and_b64 vcc, exec, s[4:5]
	s_cbranch_vccnz .LBB0_380
	s_mov_b32 m0, s63
	v_lshl_add_u64 v[74:75], v[226:227], 0, s[0:1]
	v_lshl_add_u64 v[72:73], v[226:227], 0, s[14:15]
	global_load_lds_dwordx4 v[74:75], off
	s_mov_b32 m0, s64
	s_nop 0
	global_load_lds_dwordx4 v[72:73], off
.LBB0_380:
	s_waitcnt lgkmcnt(8)
	s_barrier
	s_waitcnt lgkmcnt(0)
	v_mfma_f32_16x16x32_bf16 v[8:11], v[0:3], v[100:103], v[8:11]
	v_mfma_f32_16x16x32_bf16 v[124:127], v[204:207], v[112:115], v[8:11]
	v_mfma_f32_16x16x32_bf16 v[8:11], v[4:7], v[100:103], v[12:15]
	v_mfma_f32_16x16x32_bf16 v[120:123], v[200:203], v[112:115], v[8:11]
	v_mfma_f32_16x16x32_bf16 v[8:11], v[0:3], v[84:87], v[24:27]
	v_mfma_f32_16x16x32_bf16 v[108:111], v[204:207], v[96:99], v[8:11]
	v_mfma_f32_16x16x32_bf16 v[8:11], v[4:7], v[84:87], v[28:31]
	v_mfma_f32_16x16x32_bf16 v[104:107], v[200:203], v[96:99], v[8:11]
	v_mfma_f32_16x16x32_bf16 v[8:11], v[0:3], v[80:83], v[40:43]
	v_mfma_f32_16x16x32_bf16 v[92:95], v[204:207], v[216:219], v[8:11]
	v_mfma_f32_16x16x32_bf16 v[8:11], v[4:7], v[80:83], v[44:47]
	v_mfma_f32_16x16x32_bf16 v[88:91], v[200:203], v[216:219], v[8:11]
	v_mfma_f32_16x16x32_bf16 v[8:11], v[0:3], v[56:59], v[64:67]
	v_mfma_f32_16x16x32_bf16 v[76:79], v[204:207], v[60:63], v[8:11]
	v_mfma_f32_16x16x32_bf16 v[8:11], v[4:7], v[56:59], v[68:71]
	v_mfma_f32_16x16x32_bf16 v[72:75], v[200:203], v[60:63], v[8:11]
	s_barrier
	s_nop 4
	ds_read_b128 v[8:11], v242
	ds_read_b128 v[208:211], v242 offset:2048
	ds_read_b128 v[12:15], v243
	ds_read_b128 v[212:215], v243 offset:2048
	s_and_b64 vcc, exec, s[4:5]
	s_cbranch_vccnz .LBB0_382
	s_mov_b32 m0, s65
	v_lshl_add_u64 v[26:27], v[228:229], 0, s[18:19]
	v_lshl_add_u64 v[24:25], v[228:229], 0, s[20:21]
	global_load_lds_dwordx4 v[26:27], off
	s_mov_b32 m0, s68
	s_nop 0
	global_load_lds_dwordx4 v[24:25], off
; #define LDA(dst,b,h) _Pragma("unroll") for(int m=0;m<4;++m) _Pragma("unroll") for(int k=0;k<2;++k) \
;     dst[m][k]=*reinterpret_cast<const bf16x8*>(SA(b,h)+(wr*64+m*16)*128+koff[k])
; #define LDB(dst,b,h) _Pragma("unroll") for(int n=0;n<2;++n) _Pragma("unroll") for(int k=0;k<2;++k) \
;     dst[n][k]=*reinterpret_cast<const bf16x8*>(SB(b,h)+(wc*32+n*16)*128+koff[k])
; #define MMA(ai,bj,Af,Bf) do{__builtin_amdgcn_s_setprio(1); \
;     _Pragma("unroll") for(int m=0;m<4;++m) _Pragma("unroll") for(int n=0;n<2;++n) _Pragma("unroll") for(int k=0;k<2;++k) \
;       acc[ai][bj][m][n]=__builtin_amdgcn_mfma_f32_16x16x32_bf16(Bf[n][k],Af[m][k],acc[ai][bj][m][n],0,0,0); \
;     __builtin_amdgcn_s_setprio(0);}while(0)
; #define WAIT_V(n) asm volatile("s_waitcnt vmcnt(" #n ")":::"memory")
; #define WAIT_L(n) asm volatile("s_waitcnt lgkmcnt(" #n ")":::"memory")
; #define BAR __builtin_amdgcn_s_barrier()
; #define SCHED __builtin_amdgcn_sched_barrier(0)
; #define STAGE_A(b,h,kt) do{ unsigned char* _d = SA(b,h) + wbase; \
;     if constexpr (BLK) { const char* _s = baseA + ((size_t)(h)*(K/64) + (kt)) * 16384; GLDS(_s + voa, _d); GLDS(_s + 8192 + voa, _d + 8192); } \
;     else { const char* _s = baseA + ((size_t)(h)*128*K + (kt)*64) * 2; GLDS(_s + voa, _d); GLDS(_s + (size_t)128*K + voa, _d + 8192); } }while(0)
; template <int K, int EPI, bool MIX = false>
; __device__ __forceinline__ void gemm_phase(const Params& p, const u16* __restrict__ A, const u16* __restrict__ Bt,
;                            const float* __restrict__ rs_in, float* __restrict__ ssq_out, float alpha, bool rev = false) {
;     ...
;       BAR; WAIT_L(0); MMA(1,0,At,B0); BAR; SCHED;
;       if (more) { STAGE_B(0,1,0); WAIT_V(6); } else { WAIT_V(0); }
;       BAR; MMA(1,1,At,B1); BAR;
;       LDB(B0,1,0); SCHED; LDA(At,1,0); if (more) STAGE_A(0,1,0);
;       WAIT_L(8); BAR; WAIT_L(0); MMA(0,0,At,B0); BAR; SCHED;
;       LDB(B1,1,1); if (more) STAGE_B(1,0,1);
;       BAR; WAIT_L(0); MMA(0,1,At,B1); BAR;
;       LDA(At,1,1); if (more) STAGE_A(1,0,1);
;       BAR; WAIT_L(0); MMA(1,0,At,B0); BAR; SCHED;
;       if (more) { STAGE_B(1,1,1); WAIT_V(6); }
;       BAR; MMA(1,1,At,B1); BAR;
;       if (!more && wr == 0) BAR;
;     }
.LBB0_382:
	s_barrier
	s_waitcnt lgkmcnt(0)
	v_mfma_f32_16x16x32_bf16 v[20:23], v[8:11], v[100:103], v[20:23]
	v_mfma_f32_16x16x32_bf16 v[16:19], v[208:211], v[100:103], v[16:19]
	v_mfma_f32_16x16x32_bf16 v[116:119], v[12:15], v[112:115], v[20:23]
	v_mfma_f32_16x16x32_bf16 v[112:115], v[212:215], v[112:115], v[16:19]
	v_mfma_f32_16x16x32_bf16 v[16:19], v[8:11], v[84:87], v[36:39]
	v_mfma_f32_16x16x32_bf16 v[100:103], v[12:15], v[96:99], v[16:19]
	v_mfma_f32_16x16x32_bf16 v[16:19], v[208:211], v[84:87], v[32:35]
	v_mfma_f32_16x16x32_bf16 v[96:99], v[212:215], v[96:99], v[16:19]
	v_mfma_f32_16x16x32_bf16 v[16:19], v[8:11], v[80:83], v[52:55]
	v_mfma_f32_16x16x32_bf16 v[84:87], v[12:15], v[216:219], v[16:19]
	v_mfma_f32_16x16x32_bf16 v[16:19], v[208:211], v[80:83], v[48:51]
	v_mfma_f32_16x16x32_bf16 v[80:83], v[212:215], v[216:219], v[16:19]
	v_mfma_f32_16x16x32_bf16 v[16:19], v[8:11], v[56:59], v[152:155]
	v_mfma_f32_16x16x32_bf16 v[68:71], v[12:15], v[60:63], v[16:19]
	v_mfma_f32_16x16x32_bf16 v[16:19], v[208:211], v[56:59], v[156:159]
	v_mfma_f32_16x16x32_bf16 v[64:67], v[212:215], v[60:63], v[16:19]
	s_barrier
	ds_read_b128 v[36:39], v236 offset:49152
	ds_read_b128 v[20:23], v236 offset:51200
	ds_read_b128 v[48:51], v237 offset:49152
	ds_read_b128 v[32:35], v237 offset:51200
	s_nop 0
	ds_read_b128 v[16:19], v236 offset:53248
	ds_read_b128 v[152:155], v236 offset:55296
	ds_read_b128 v[216:219], v237 offset:53248
	ds_read_b128 v[156:159], v237 offset:55296
	s_and_b64 vcc, exec, s[4:5]
	s_cbranch_vccnz .LBB0_384
	s_mov_b32 m0, s69
	v_lshl_add_u64 v[26:27], v[226:227], 0, s[18:19]
	v_lshl_add_u64 v[24:25], v[226:227], 0, s[20:21]
	global_load_lds_dwordx4 v[26:27], off
	s_mov_b32 m0, s70
	s_nop 0
	global_load_lds_dwordx4 v[24:25], off
.LBB0_384:
	s_barrier
	s_waitcnt lgkmcnt(0)
	v_mfma_f32_16x16x32_bf16 v[24:27], v[0:3], v[36:39], v[160:163]
	v_mfma_f32_16x16x32_bf16 v[60:63], v[204:207], v[48:51], v[24:27]
	v_mfma_f32_16x16x32_bf16 v[24:27], v[4:7], v[36:39], v[164:167]
	v_mfma_f32_16x16x32_bf16 v[56:59], v[200:203], v[48:51], v[24:27]
	v_mfma_f32_16x16x32_bf16 v[24:27], v[0:3], v[20:23], v[132:135]
	v_mfma_f32_16x16x32_bf16 v[44:47], v[204:207], v[32:35], v[24:27]
	v_mfma_f32_16x16x32_bf16 v[24:27], v[4:7], v[20:23], v[128:131]
	v_mfma_f32_16x16x32_bf16 v[40:43], v[200:203], v[32:35], v[24:27]
	v_mfma_f32_16x16x32_bf16 v[24:27], v[0:3], v[16:19], v[168:171]
	v_mfma_f32_16x16x32_bf16 v[28:31], v[204:207], v[216:219], v[24:27]
	v_mfma_f32_16x16x32_bf16 v[24:27], v[4:7], v[16:19], v[172:175]
	v_mfma_f32_16x16x32_bf16 v[0:3], v[0:3], v[152:155], v[136:139]
	v_mfma_f32_16x16x32_bf16 v[4:7], v[4:7], v[152:155], v[140:143]
	v_mfma_f32_16x16x32_bf16 v[24:27], v[200:203], v[216:219], v[24:27]
	v_mfma_f32_16x16x32_bf16 v[0:3], v[204:207], v[156:159], v[0:3]
	v_mfma_f32_16x16x32_bf16 v[4:7], v[200:203], v[156:159], v[4:7]
	s_barrier
	s_and_b64 vcc, exec, s[4:5]
	s_mov_b64 s[6:7], s[26:27]
	s_cbranch_vccnz .LBB0_386
	s_mov_b32 m0, s71
	v_lshl_add_u64 v[54:55], v[224:225], 0, s[18:19]
	v_lshl_add_u64 v[52:53], v[224:225], 0, s[20:21]
	global_load_lds_dwordx4 v[54:55], off
	s_mov_b32 m0, s72
	s_mov_b64 s[6:7], 0
	global_load_lds_dwordx4 v[52:53], off
	s_waitcnt vmcnt(6)
.LBB0_386:
	s_barrier
	v_mfma_f32_16x16x32_bf16 v[52:55], v[8:11], v[36:39], v[144:147]
	v_mfma_f32_16x16x32_bf16 v[36:39], v[208:211], v[36:39], v[148:151]
	v_mfma_f32_16x16x32_bf16 v[52:55], v[12:15], v[48:51], v[52:55]
	v_mfma_f32_16x16x32_bf16 v[48:51], v[212:215], v[48:51], v[36:39]
	v_mfma_f32_16x16x32_bf16 v[36:39], v[8:11], v[20:23], v[176:179]
	v_mfma_f32_16x16x32_bf16 v[20:23], v[208:211], v[20:23], v[180:183]
	v_mfma_f32_16x16x32_bf16 v[36:39], v[12:15], v[32:35], v[36:39]
	v_mfma_f32_16x16x32_bf16 v[32:35], v[212:215], v[32:35], v[20:23]
	v_mfma_f32_16x16x32_bf16 v[20:23], v[8:11], v[16:19], v[184:187]
	v_mfma_f32_16x16x32_bf16 v[8:11], v[8:11], v[152:155], v[192:195]
	v_mfma_f32_16x16x32_bf16 v[20:23], v[12:15], v[216:219], v[20:23]
	v_mfma_f32_16x16x32_bf16 v[16:19], v[208:211], v[16:19], v[188:191]
	v_mfma_f32_16x16x32_bf16 v[12:15], v[12:15], v[156:159], v[8:11]
	v_mfma_f32_16x16x32_bf16 v[8:11], v[208:211], v[152:155], v[196:199]
	v_mfma_f32_16x16x32_bf16 v[16:19], v[212:215], v[216:219], v[16:19]
	v_mfma_f32_16x16x32_bf16 v[8:11], v[212:215], v[156:159], v[8:11]
	s_or_b64 vcc, s[4:5], s[26:27]
	s_cbranch_scc0 .Llate_p5_defer
	s_barrier

.Llate_p6_done:
.LBB0_423:
	ds_read_b128 v[128:131], v224
	ds_read_b128 v[132:135], v224 offset:2048
	ds_read_b128 v[136:139], v225
	ds_read_b128 v[140:143], v225 offset:2048
	v_lshl_add_u64 v[192:193], s[52:53], 0, v[216:217]
	s_mov_b32 m0, s72
	v_lshl_add_u64 v[176:177], v[192:193], 0, s[24:25]
	ds_read_b128 v[144:147], v226
	ds_read_b128 v[148:151], v226 offset:2048
	ds_read_b128 v[152:155], v227
	ds_read_b128 v[156:159], v227 offset:2048
	ds_read_b128 v[160:163], v226 offset:4096
	ds_read_b128 v[164:167], v226 offset:6144
	ds_read_b128 v[168:171], v227 offset:4096
	ds_read_b128 v[172:175], v227 offset:6144
	global_load_lds_dwordx4 v[176:177], off
	v_lshl_add_u64 v[176:177], v[192:193], 0, s[26:27]
	s_mov_b32 m0, s73
	s_nop 0
	global_load_lds_dwordx4 v[176:177], off
	s_waitcnt lgkmcnt(8)
	s_barrier
	s_waitcnt lgkmcnt(0)
	v_mfma_f32_16x16x32_bf16 v[124:127], v[128:131], v[144:147], v[124:127]
	v_mfma_f32_16x16x32_bf16 v[120:123], v[132:135], v[144:147], v[120:123]
	v_mfma_f32_16x16x32_bf16 v[116:119], v[128:131], v[148:151], v[116:119]
	v_mfma_f32_16x16x32_bf16 v[112:115], v[132:135], v[148:151], v[112:115]
	v_mfma_f32_16x16x32_bf16 v[108:111], v[128:131], v[160:163], v[108:111]
	v_mfma_f32_16x16x32_bf16 v[104:107], v[132:135], v[160:163], v[104:107]
	v_mfma_f32_16x16x32_bf16 v[100:103], v[128:131], v[164:167], v[100:103]
	v_mfma_f32_16x16x32_bf16 v[96:99], v[132:135], v[164:167], v[96:99]
	v_mfma_f32_16x16x32_bf16 v[124:127], v[136:139], v[152:155], v[124:127]
	v_mfma_f32_16x16x32_bf16 v[120:123], v[140:143], v[152:155], v[120:123]
	v_mfma_f32_16x16x32_bf16 v[116:119], v[136:139], v[156:159], v[116:119]
	v_mfma_f32_16x16x32_bf16 v[112:115], v[140:143], v[156:159], v[112:115]
	v_mfma_f32_16x16x32_bf16 v[108:111], v[136:139], v[168:171], v[108:111]
	v_mfma_f32_16x16x32_bf16 v[104:107], v[140:143], v[168:171], v[104:107]
	v_mfma_f32_16x16x32_bf16 v[100:103], v[136:139], v[172:175], v[100:103]
	v_mfma_f32_16x16x32_bf16 v[96:99], v[140:143], v[172:175], v[96:99]
	s_barrier
	v_lshl_add_u64 v[194:195], s[58:59], 0, v[216:217]
	s_mov_b32 m0, s35
	v_lshl_add_u64 v[196:197], v[194:195], 0, s[28:29]
	ds_read_b128 v[176:179], v228
	ds_read_b128 v[180:183], v228 offset:2048
	ds_read_b128 v[184:187], v229
	ds_read_b128 v[188:191], v229 offset:2048
	global_load_lds_dwordx4 v[196:197], off
	v_lshl_add_u64 v[196:197], v[194:195], 0, s[30:31]
	s_mov_b32 m0, s42
	s_nop 0
	global_load_lds_dwordx4 v[196:197], off
	s_barrier
	s_waitcnt lgkmcnt(0)
	v_mfma_f32_16x16x32_bf16 v[92:95], v[176:179], v[144:147], v[92:95]
	v_mfma_f32_16x16x32_bf16 v[88:91], v[180:183], v[144:147], v[88:91]
	v_mfma_f32_16x16x32_bf16 v[84:87], v[176:179], v[148:151], v[84:87]
	v_mfma_f32_16x16x32_bf16 v[80:83], v[180:183], v[148:151], v[80:83]
	v_mfma_f32_16x16x32_bf16 v[76:79], v[176:179], v[160:163], v[76:79]
	v_mfma_f32_16x16x32_bf16 v[72:75], v[180:183], v[160:163], v[72:75]
	v_mfma_f32_16x16x32_bf16 v[68:71], v[176:179], v[164:167], v[68:71]
	v_mfma_f32_16x16x32_bf16 v[64:67], v[180:183], v[164:167], v[64:67]
	v_mfma_f32_16x16x32_bf16 v[92:95], v[184:187], v[152:155], v[92:95]
	v_mfma_f32_16x16x32_bf16 v[88:91], v[188:191], v[152:155], v[88:91]
	v_mfma_f32_16x16x32_bf16 v[84:87], v[184:187], v[156:159], v[84:87]
	v_mfma_f32_16x16x32_bf16 v[80:83], v[188:191], v[156:159], v[80:83]
	v_mfma_f32_16x16x32_bf16 v[76:79], v[184:187], v[168:171], v[76:79]
	v_mfma_f32_16x16x32_bf16 v[72:75], v[188:191], v[168:171], v[72:75]
	v_mfma_f32_16x16x32_bf16 v[68:71], v[184:187], v[172:175], v[68:71]
	v_mfma_f32_16x16x32_bf16 v[64:67], v[188:191], v[172:175], v[64:67]
	s_barrier
	s_mov_b32 m0, s33
	v_lshl_add_u64 v[196:197], v[192:193], 0, s[28:29]
	ds_read_b128 v[144:147], v226 offset:16384
	ds_read_b128 v[148:151], v226 offset:18432
	ds_read_b128 v[152:155], v227 offset:16384
	ds_read_b128 v[156:159], v227 offset:18432
	ds_read_b128 v[160:163], v226 offset:20480
	ds_read_b128 v[164:167], v226 offset:22528
	ds_read_b128 v[168:171], v227 offset:20480
	ds_read_b128 v[172:175], v227 offset:22528
	global_load_lds_dwordx4 v[196:197], off
	v_lshl_add_u64 v[196:197], v[192:193], 0, s[30:31]
	s_mov_b32 m0, s43
	s_nop 0
	global_load_lds_dwordx4 v[196:197], off
	s_barrier
	s_waitcnt lgkmcnt(0)
	v_mfma_f32_16x16x32_bf16 v[28:31], v[128:131], v[144:147], v[28:31]
	v_mfma_f32_16x16x32_bf16 v[24:27], v[132:135], v[144:147], v[24:27]
	v_mfma_f32_16x16x32_bf16 v[20:23], v[128:131], v[148:151], v[20:23]
	v_mfma_f32_16x16x32_bf16 v[16:19], v[132:135], v[148:151], v[16:19]
	v_mfma_f32_16x16x32_bf16 v[12:15], v[128:131], v[160:163], v[12:15]
	v_mfma_f32_16x16x32_bf16 v[8:11], v[132:135], v[160:163], v[8:11]
	v_mfma_f32_16x16x32_bf16 v[4:7], v[128:131], v[164:167], v[4:7]
	v_mfma_f32_16x16x32_bf16 v[0:3], v[132:135], v[164:167], v[0:3]
	v_mfma_f32_16x16x32_bf16 v[28:31], v[136:139], v[152:155], v[28:31]
	v_mfma_f32_16x16x32_bf16 v[24:27], v[140:143], v[152:155], v[24:27]
	v_mfma_f32_16x16x32_bf16 v[20:23], v[136:139], v[156:159], v[20:23]
	v_mfma_f32_16x16x32_bf16 v[16:19], v[140:143], v[156:159], v[16:19]
	v_mfma_f32_16x16x32_bf16 v[12:15], v[136:139], v[168:171], v[12:15]
	v_mfma_f32_16x16x32_bf16 v[8:11], v[140:143], v[168:171], v[8:11]
	v_mfma_f32_16x16x32_bf16 v[4:7], v[136:139], v[172:175], v[4:7]
	v_mfma_f32_16x16x32_bf16 v[0:3], v[140:143], v[172:175], v[0:3]
	s_barrier
	v_lshl_add_u64 v[196:197], s[4:5], 0, v[216:217]
	s_mov_b32 m0, s44
	v_lshl_add_u64 v[128:129], v[196:197], 0, s[28:29]
	global_load_lds_dwordx4 v[128:129], off
	v_lshl_add_u64 v[128:129], v[196:197], 0, s[30:31]
	s_mov_b32 m0, s45
	s_nop 0
	global_load_lds_dwordx4 v[128:129], off
	s_waitcnt vmcnt(6)
	s_barrier
	v_mfma_f32_16x16x32_bf16 v[32:35], v[176:179], v[144:147], v[32:35]
	v_mfma_f32_16x16x32_bf16 v[36:39], v[180:183], v[144:147], v[36:39]
	v_mfma_f32_16x16x32_bf16 v[40:43], v[176:179], v[148:151], v[40:43]
	v_mfma_f32_16x16x32_bf16 v[44:47], v[180:183], v[148:151], v[44:47]
	v_mfma_f32_16x16x32_bf16 v[48:51], v[176:179], v[160:163], v[48:51]
	v_mfma_f32_16x16x32_bf16 v[52:55], v[180:183], v[160:163], v[52:55]
	v_mfma_f32_16x16x32_bf16 v[56:59], v[176:179], v[164:167], v[56:59]
	v_mfma_f32_16x16x32_bf16 v[60:63], v[180:183], v[164:167], v[60:63]
	v_mfma_f32_16x16x32_bf16 v[32:35], v[184:187], v[152:155], v[32:35]
	v_mfma_f32_16x16x32_bf16 v[36:39], v[188:191], v[152:155], v[36:39]
	v_mfma_f32_16x16x32_bf16 v[40:43], v[184:187], v[156:159], v[40:43]
	v_mfma_f32_16x16x32_bf16 v[44:47], v[188:191], v[156:159], v[44:47]
	v_mfma_f32_16x16x32_bf16 v[48:51], v[184:187], v[168:171], v[48:51]
	v_mfma_f32_16x16x32_bf16 v[52:55], v[188:191], v[168:171], v[52:55]
	v_mfma_f32_16x16x32_bf16 v[56:59], v[184:187], v[172:175], v[56:59]
	v_mfma_f32_16x16x32_bf16 v[60:63], v[188:191], v[172:175], v[60:63]
	s_barrier
	ds_read_b128 v[128:131], v232
	ds_read_b128 v[132:135], v232 offset:2048
	ds_read_b128 v[136:139], v233
	ds_read_b128 v[140:143], v233 offset:2048
	s_mov_b32 m0, s60
	v_lshl_add_u64 v[176:177], v[192:193], 0, s[36:37]
	ds_read_b128 v[144:147], v226 offset:32768
	ds_read_b128 v[148:151], v226 offset:34816
	ds_read_b128 v[152:155], v227 offset:32768
	ds_read_b128 v[156:159], v227 offset:34816
	ds_read_b128 v[160:163], v226 offset:36864
	ds_read_b128 v[164:167], v226 offset:38912
	ds_read_b128 v[168:171], v227 offset:36864
	ds_read_b128 v[172:175], v227 offset:38912
	global_load_lds_dwordx4 v[176:177], off
	v_lshl_add_u64 v[176:177], v[192:193], 0, s[38:39]
	s_mov_b32 m0, s61
	s_nop 0
	global_load_lds_dwordx4 v[176:177], off
	s_waitcnt lgkmcnt(8)
	s_barrier
	s_waitcnt lgkmcnt(0)
	v_mfma_f32_16x16x32_bf16 v[124:127], v[128:131], v[144:147], v[124:127]
	v_mfma_f32_16x16x32_bf16 v[120:123], v[132:135], v[144:147], v[120:123]
	v_mfma_f32_16x16x32_bf16 v[116:119], v[128:131], v[148:151], v[116:119]
	v_mfma_f32_16x16x32_bf16 v[112:115], v[132:135], v[148:151], v[112:115]
	v_mfma_f32_16x16x32_bf16 v[108:111], v[128:131], v[160:163], v[108:111]
	v_mfma_f32_16x16x32_bf16 v[104:107], v[132:135], v[160:163], v[104:107]
	v_mfma_f32_16x16x32_bf16 v[100:103], v[128:131], v[164:167], v[100:103]
	v_mfma_f32_16x16x32_bf16 v[96:99], v[132:135], v[164:167], v[96:99]
	v_mfma_f32_16x16x32_bf16 v[124:127], v[136:139], v[152:155], v[124:127]
	v_mfma_f32_16x16x32_bf16 v[120:123], v[140:143], v[152:155], v[120:123]
	v_mfma_f32_16x16x32_bf16 v[116:119], v[136:139], v[156:159], v[116:119]
	v_mfma_f32_16x16x32_bf16 v[112:115], v[140:143], v[156:159], v[112:115]
	v_mfma_f32_16x16x32_bf16 v[108:111], v[136:139], v[168:171], v[108:111]
	v_mfma_f32_16x16x32_bf16 v[104:107], v[140:143], v[168:171], v[104:107]
	v_mfma_f32_16x16x32_bf16 v[100:103], v[136:139], v[172:175], v[100:103]
	v_mfma_f32_16x16x32_bf16 v[96:99], v[140:143], v[172:175], v[96:99]
	s_barrier
	s_mov_b32 m0, s62
	v_lshl_add_u64 v[198:199], v[194:195], 0, s[40:41]
	ds_read_b128 v[176:179], v234
	ds_read_b128 v[180:183], v234 offset:2048
	ds_read_b128 v[184:187], v235
	ds_read_b128 v[188:191], v235 offset:2048
	global_load_lds_dwordx4 v[198:199], off
	v_lshl_add_u64 v[194:195], v[194:195], 0, s[46:47]
	s_mov_b32 m0, s63
	s_nop 0
	global_load_lds_dwordx4 v[194:195], off
	s_barrier
	s_waitcnt lgkmcnt(0)
	v_mfma_f32_16x16x32_bf16 v[92:95], v[176:179], v[144:147], v[92:95]
	v_mfma_f32_16x16x32_bf16 v[88:91], v[180:183], v[144:147], v[88:91]
	v_mfma_f32_16x16x32_bf16 v[84:87], v[176:179], v[148:151], v[84:87]
	v_mfma_f32_16x16x32_bf16 v[80:83], v[180:183], v[148:151], v[80:83]
	v_mfma_f32_16x16x32_bf16 v[76:79], v[176:179], v[160:163], v[76:79]
	v_mfma_f32_16x16x32_bf16 v[72:75], v[180:183], v[160:163], v[72:75]
	v_mfma_f32_16x16x32_bf16 v[68:71], v[176:179], v[164:167], v[68:71]
	v_mfma_f32_16x16x32_bf16 v[64:67], v[180:183], v[164:167], v[64:67]
	v_mfma_f32_16x16x32_bf16 v[92:95], v[184:187], v[152:155], v[92:95]
	v_mfma_f32_16x16x32_bf16 v[88:91], v[188:191], v[152:155], v[88:91]
	v_mfma_f32_16x16x32_bf16 v[84:87], v[184:187], v[156:159], v[84:87]
	v_mfma_f32_16x16x32_bf16 v[80:83], v[188:191], v[156:159], v[80:83]
	v_mfma_f32_16x16x32_bf16 v[76:79], v[184:187], v[168:171], v[76:79]
	v_mfma_f32_16x16x32_bf16 v[72:75], v[188:191], v[168:171], v[72:75]
	v_mfma_f32_16x16x32_bf16 v[68:71], v[184:187], v[172:175], v[68:71]
	v_mfma_f32_16x16x32_bf16 v[64:67], v[188:191], v[172:175], v[64:67]
	s_barrier
	s_mov_b32 m0, s64
	v_lshl_add_u64 v[194:195], v[192:193], 0, s[40:41]
	ds_read_b128 v[144:147], v226 offset:49152
	ds_read_b128 v[148:151], v226 offset:51200
	ds_read_b128 v[152:155], v227 offset:49152
	ds_read_b128 v[156:159], v227 offset:51200
	ds_read_b128 v[160:163], v226 offset:53248
	ds_read_b128 v[164:167], v226 offset:55296
	ds_read_b128 v[168:171], v227 offset:53248
	ds_read_b128 v[172:175], v227 offset:55296
	global_load_lds_dwordx4 v[194:195], off
	v_lshl_add_u64 v[192:193], v[192:193], 0, s[46:47]
	s_mov_b32 m0, s65
	s_nop 0
	global_load_lds_dwordx4 v[192:193], off
	s_barrier
	s_waitcnt lgkmcnt(0)
	v_mfma_f32_16x16x32_bf16 v[28:31], v[128:131], v[144:147], v[28:31]
	v_mfma_f32_16x16x32_bf16 v[24:27], v[132:135], v[144:147], v[24:27]
	v_mfma_f32_16x16x32_bf16 v[20:23], v[128:131], v[148:151], v[20:23]
	v_mfma_f32_16x16x32_bf16 v[16:19], v[132:135], v[148:151], v[16:19]
	v_mfma_f32_16x16x32_bf16 v[12:15], v[128:131], v[160:163], v[12:15]
	v_mfma_f32_16x16x32_bf16 v[8:11], v[132:135], v[160:163], v[8:11]
	v_mfma_f32_16x16x32_bf16 v[4:7], v[128:131], v[164:167], v[4:7]
	v_mfma_f32_16x16x32_bf16 v[0:3], v[132:135], v[164:167], v[0:3]
	v_mfma_f32_16x16x32_bf16 v[28:31], v[136:139], v[152:155], v[28:31]
	v_mfma_f32_16x16x32_bf16 v[24:27], v[140:143], v[152:155], v[24:27]
	v_mfma_f32_16x16x32_bf16 v[20:23], v[136:139], v[156:159], v[20:23]
	v_mfma_f32_16x16x32_bf16 v[16:19], v[140:143], v[156:159], v[16:19]
	v_mfma_f32_16x16x32_bf16 v[12:15], v[136:139], v[168:171], v[12:15]
	v_mfma_f32_16x16x32_bf16 v[8:11], v[140:143], v[168:171], v[8:11]
	v_mfma_f32_16x16x32_bf16 v[4:7], v[136:139], v[172:175], v[4:7]
	v_mfma_f32_16x16x32_bf16 v[0:3], v[140:143], v[172:175], v[0:3]
	s_barrier
	s_mov_b32 m0, s68
	v_lshl_add_u64 v[128:129], v[196:197], 0, s[40:41]
	global_load_lds_dwordx4 v[128:129], off
	v_lshl_add_u64 v[128:129], v[196:197], 0, s[46:47]
	s_mov_b32 m0, s69
	s_nop 0
	global_load_lds_dwordx4 v[128:129], off
	s_waitcnt vmcnt(6)
	s_barrier
	v_mfma_f32_16x16x32_bf16 v[32:35], v[176:179], v[144:147], v[32:35]
	v_mfma_f32_16x16x32_bf16 v[36:39], v[180:183], v[144:147], v[36:39]
	v_mfma_f32_16x16x32_bf16 v[40:43], v[176:179], v[148:151], v[40:43]
	v_mfma_f32_16x16x32_bf16 v[44:47], v[180:183], v[148:151], v[44:47]
	v_mfma_f32_16x16x32_bf16 v[48:51], v[176:179], v[160:163], v[48:51]
	v_mfma_f32_16x16x32_bf16 v[52:55], v[180:183], v[160:163], v[52:55]
	v_mfma_f32_16x16x32_bf16 v[56:59], v[176:179], v[164:167], v[56:59]
	v_mfma_f32_16x16x32_bf16 v[60:63], v[180:183], v[164:167], v[60:63]
	v_mfma_f32_16x16x32_bf16 v[32:35], v[184:187], v[152:155], v[32:35]
	v_mfma_f32_16x16x32_bf16 v[36:39], v[188:191], v[152:155], v[36:39]
	v_mfma_f32_16x16x32_bf16 v[40:43], v[184:187], v[156:159], v[40:43]
	v_mfma_f32_16x16x32_bf16 v[44:47], v[188:191], v[156:159], v[44:47]
	v_mfma_f32_16x16x32_bf16 v[48:51], v[184:187], v[168:171], v[48:51]
	v_mfma_f32_16x16x32_bf16 v[52:55], v[188:191], v[168:171], v[52:55]
	v_mfma_f32_16x16x32_bf16 v[56:59], v[184:187], v[172:175], v[56:59]
	v_mfma_f32_16x16x32_bf16 v[60:63], v[188:191], v[172:175], v[60:63]
	s_barrier
	s_add_i32 s77, s77, 2
	s_add_u32 s58, s58, 0x100
	s_addc_u32 s59, s59, 0
	s_add_u32 s52, s52, 0x100
	s_addc_u32 s53, s53, 0
	s_add_u32 s4, s4, 0x100
	s_addc_u32 s5, s5, 0
	s_cmp_lt_u32 s77, 28
	s_cbranch_scc1 .LBB0_423
; #define LDA(dst,b,h) _Pragma("unroll") for(int m=0;m<4;++m) _Pragma("unroll") for(int k=0;k<2;++k) \
;     dst[m][k]=*reinterpret_cast<const bf16x8*>(SA(b,h)+(wr*64+m*16)*128+koff[k])
; #define LDB(dst,b,h) _Pragma("unroll") for(int n=0;n<2;++n) _Pragma("unroll") for(int k=0;k<2;++k) \
;     dst[n][k]=*reinterpret_cast<const bf16x8*>(SB(b,h)+(wc*32+n*16)*128+koff[k])
; #define MMA(ai,bj,Af,Bf) do{__builtin_amdgcn_s_setprio(1); \
;     _Pragma("unroll") for(int m=0;m<4;++m) _Pragma("unroll") for(int n=0;n<2;++n) _Pragma("unroll") for(int k=0;k<2;++k) \
;       acc[ai][bj][m][n]=__builtin_amdgcn_mfma_f32_16x16x32_bf16(Bf[n][k],Af[m][k],acc[ai][bj][m][n],0,0,0); \
;     __builtin_amdgcn_s_setprio(0);}while(0)
; #define WAIT_L(n) asm volatile("s_waitcnt lgkmcnt(" #n ")":::"memory")
; #define BAR __builtin_amdgcn_s_barrier()
; #define SCHED __builtin_amdgcn_sched_barrier(0)
; #define STAGE_A(b,h,kt) do{ unsigned char* _d = SA(b,h) + wbase; \
;     if constexpr (BLK) { const char* _s = baseA + ((size_t)(h)*(K/64) + (kt)) * 16384; GLDS(_s + voa, _d); GLDS(_s + 8192 + voa, _d + 8192); } \
;     else { const char* _s = baseA + ((size_t)(h)*128*K + (kt)*64) * 2; GLDS(_s + voa, _d); GLDS(_s + (size_t)128*K + voa, _d + 8192); } }while(0)
; template <int K, int EPI, bool MIX = false>
; __device__ __forceinline__ void gemm_phase(const Params& p, const u16* __restrict__ A, const u16* __restrict__ Bt,
;                            const float* __restrict__ rs_in, float* __restrict__ ssq_out, float alpha, bool rev = false) {
;     ...
;     float rsq[2][4];
;     if constexpr (EPI == EPI_SWIGLU || EPI == EPI_Z || MIX) {
;       const float* rsrc = MIX ? p.ssqb : rs_in;
;       int fr_p = fr;
;       asm volatile("" : "+v"(fr_p));
; #pragma unroll
;       for (int ai = 0; ai < 2; ++ai)
; #pragma unroll
;         for (int m = 0; m < 4; ++m) rsq[ai][m] = rsrc[cpm * 256 + ai * 128 + wr * 64 + m * 16 + fr_p];
;     }
;     ++it;
;     id = item_id(it);
;     const bool more = id < ntiles;
;     if (rev) id = ntiles - 1 - id;
;     {
;       LDB(B0,0,0); SCHED; LDA(At,0,0); STAGE_A(1,1,nt-1);
;       WAIT_L(8); BAR; WAIT_L(0); MMA(0,0,At,B0); BAR; SCHED;
;       if (more) SETUP_TILE();
	v_mov_b32_e32 v128, v223
	s_lshl_b32 s59, s34, 8
	s_add_i32 s59, s59, s70
	v_add_u32_e32 v128, s59, v128
	v_readlane_b32 s80, v254, 32
	v_ashrrev_i32_e32 v129, 31, v128
	v_readlane_b32 s94, v254, 46
	v_readlane_b32 s95, v254, 47
	s_add_i32 s75, s75, 1
	s_mul_i32 s4, s75, s57
	v_lshl_add_u64 v[128:129], v[128:129], 2, s[94:95]
	global_load_dword v214, v[128:129], off
	global_load_dword v243, v[128:129], off offset:64
	global_load_dword v242, v[128:129], off offset:128
	global_load_dword v241, v[128:129], off offset:192
	global_load_dword v240, v[128:129], off offset:512
	global_load_dword v239, v[128:129], off offset:576
	global_load_dword v238, v[128:129], off offset:640
	global_load_dword v237, v[128:129], off offset:704
	ds_read_b128 v[136:139], v224
	ds_read_b128 v[140:143], v224 offset:2048
	ds_read_b128 v[148:151], v225
	ds_read_b128 v[144:147], v225 offset:2048
	s_add_i32 s4, s4, s56
	v_readlane_b32 s81, v254, 33
	v_readlane_b32 s82, v254, 34
	v_readlane_b32 s83, v254, 35
	v_readlane_b32 s84, v254, 36
	v_readlane_b32 s85, v254, 37
	v_readlane_b32 s86, v254, 38
	v_readlane_b32 s87, v254, 39
	v_readlane_b32 s88, v254, 40
	v_readlane_b32 s89, v254, 41
	v_readlane_b32 s90, v254, 42
	v_readlane_b32 s91, v254, 43
	v_readlane_b32 s92, v254, 44
	v_readlane_b32 s93, v254, 45
	v_lshl_add_u64 v[128:129], s[0:1], 0, v[212:213]
	s_mov_b32 m0, s72
	v_lshl_add_u64 v[130:131], v[128:129], 0, s[48:49]
	ds_read_b128 v[152:155], v226
	ds_read_b128 v[156:159], v226 offset:2048
	ds_read_b128 v[180:183], v227
	ds_read_b128 v[172:175], v227 offset:2048
	ds_read_b128 v[160:163], v226 offset:4096
	ds_read_b128 v[164:167], v226 offset:6144
	ds_read_b128 v[176:179], v227 offset:4096
	ds_read_b128 v[168:171], v227 offset:6144
	global_load_lds_dwordx4 v[130:131], off
	v_lshl_add_u64 v[128:129], v[128:129], 0, s[50:51]
	s_mov_b32 m0, s73
	s_nop 0
	global_load_lds_dwordx4 v[128:129], off
	s_waitcnt lgkmcnt(8)
	s_barrier
	s_waitcnt lgkmcnt(0)
	v_mfma_f32_16x16x32_bf16 v[124:127], v[136:139], v[152:155], v[124:127]
	s_cmpk_lt_i32 s4, 0x2100
	s_cselect_b64 s[52:53], -1, 0
	s_cmpk_gt_i32 s4, 0x20ff
	v_mfma_f32_16x16x32_bf16 v[120:123], v[140:143], v[152:155], v[120:123]
	v_mfma_f32_16x16x32_bf16 v[116:119], v[136:139], v[156:159], v[116:119]
	v_mfma_f32_16x16x32_bf16 v[112:115], v[140:143], v[156:159], v[112:115]
	v_mfma_f32_16x16x32_bf16 v[108:111], v[136:139], v[160:163], v[108:111]
	v_mfma_f32_16x16x32_bf16 v[104:107], v[140:143], v[160:163], v[104:107]
	v_mfma_f32_16x16x32_bf16 v[100:103], v[136:139], v[164:167], v[100:103]
	v_mfma_f32_16x16x32_bf16 v[96:99], v[140:143], v[164:167], v[96:99]
	v_mfma_f32_16x16x32_bf16 v[124:127], v[148:151], v[180:183], v[124:127]
	v_mfma_f32_16x16x32_bf16 v[120:123], v[144:147], v[180:183], v[120:123]
	v_mfma_f32_16x16x32_bf16 v[116:119], v[148:151], v[172:175], v[116:119]
	v_mfma_f32_16x16x32_bf16 v[112:115], v[144:147], v[172:175], v[112:115]
	v_mfma_f32_16x16x32_bf16 v[108:111], v[148:151], v[176:179], v[108:111]
	v_mfma_f32_16x16x32_bf16 v[104:107], v[144:147], v[176:179], v[104:107]
	v_mfma_f32_16x16x32_bf16 v[128:131], v[148:151], v[168:171], v[100:103]
	v_mfma_f32_16x16x32_bf16 v[132:135], v[144:147], v[168:171], v[96:99]
	s_barrier
	s_mov_b32 s58, s76
	s_cbranch_scc1 .LBB0_426
	s_mul_hi_i32 s0, s4, 0x2e8ba2e9
	s_lshr_b32 s1, s0, 31
	s_ashr_i32 s0, s0, 6
	s_add_i32 s0, s0, s1
	s_lshl_b32 s1, s0, 3
	s_mulk_i32 s0, 0xfea0
	s_add_i32 s0, s0, s4
	s_and_b32 s4, s4, 7
	s_or_b32 s34, s1, s4
	s_ashr_i32 s58, s0, 3
	s_lshl_b32 s0, s34, 8
	v_readlane_b32 s80, v254, 0
	s_ashr_i32 s1, s0, 31
	v_readlane_b32 s86, v254, 6
	v_readlane_b32 s87, v254, 7
	s_lshl_b64 s[0:1], s[0:1], 12
	s_mov_b64 s[10:11], s[86:87]
	v_readlane_b32 s81, v254, 1
	v_readlane_b32 s82, v254, 2
	v_readlane_b32 s83, v254, 3
	v_readlane_b32 s84, v254, 4
	v_readlane_b32 s85, v254, 5
	s_add_u32 s0, s10, s0
	s_addc_u32 s1, s11, s1
	s_lshl_b32 s4, s58, 7
	v_readlane_b32 s80, v254, 32
	s_ashr_i32 s5, s4, 31
	v_readlane_b32 s82, v254, 34
	v_readlane_b32 s83, v254, 35
	s_lshl_b64 s[4:5], s[4:5], 12
	s_mov_b64 s[78:79], s[82:83]
	s_add_u32 s8, s78, s4
	s_addc_u32 s9, s79, s5
	s_add_u32 s10, s8, 0x1600000
	s_addc_u32 s11, s9, 0
	v_readlane_b32 s81, v254, 33
	v_readlane_b32 s84, v254, 36
	v_readlane_b32 s85, v254, 37
	v_readlane_b32 s86, v254, 38
	v_readlane_b32 s87, v254, 39
	v_readlane_b32 s88, v254, 40
	v_readlane_b32 s89, v254, 41
	v_readlane_b32 s90, v254, 42
	v_readlane_b32 s91, v254, 43
	v_readlane_b32 s92, v254, 44
	v_readlane_b32 s93, v254, 45
	v_readlane_b32 s94, v254, 46
	v_readlane_b32 s95, v254, 47

; #define LDA(dst,b,h) _Pragma("unroll") for(int m=0;m<4;++m) _Pragma("unroll") for(int k=0;k<2;++k) \
;     dst[m][k]=*reinterpret_cast<const bf16x8*>(SA(b,h)+(wr*64+m*16)*128+koff[k])
; #define LDB(dst,b,h) _Pragma("unroll") for(int n=0;n<2;++n) _Pragma("unroll") for(int k=0;k<2;++k) \
;     dst[n][k]=*reinterpret_cast<const bf16x8*>(SB(b,h)+(wc*32+n*16)*128+koff[k])
; #define MMA(ai,bj,Af,Bf) do{__builtin_amdgcn_s_setprio(1); \
;     _Pragma("unroll") for(int m=0;m<4;++m) _Pragma("unroll") for(int n=0;n<2;++n) _Pragma("unroll") for(int k=0;k<2;++k) \
;       acc[ai][bj][m][n]=__builtin_amdgcn_mfma_f32_16x16x32_bf16(Bf[n][k],Af[m][k],acc[ai][bj][m][n],0,0,0); \
;     __builtin_amdgcn_s_setprio(0);}while(0)
; #define WAIT_V(n) asm volatile("s_waitcnt vmcnt(" #n ")":::"memory")
; #define WAIT_L(n) asm volatile("s_waitcnt lgkmcnt(" #n ")":::"memory")
; #define BAR __builtin_amdgcn_s_barrier()
; #define SCHED __builtin_amdgcn_sched_barrier(0)
; template <int K, int EPI, bool MIX = false>
; __device__ __forceinline__ void gemm_phase(const Params& p, const u16* __restrict__ A, const u16* __restrict__ Bt,
;                            const float* __restrict__ rs_in, float* __restrict__ ssq_out, float alpha, bool rev = false) {
;     ...
;       LDB(B0,0,0); SCHED; LDA(At,0,0); STAGE_A(1,1,nt-1);
;       WAIT_L(8); BAR; WAIT_L(0); MMA(0,0,At,B0); BAR; SCHED;
;       if (more) SETUP_TILE();
;       LDB(B1,0,1); if (more) STAGE_B(0,0,0);
;       BAR; WAIT_L(0); MMA(0,1,At,B1); BAR;
;       LDA(At,0,1); if (more) STAGE_A(0,0,0);
;       BAR; WAIT_L(0); MMA(1,0,At,B0); BAR; SCHED;
;       if (more) { STAGE_B(0,1,0); WAIT_V(6); } else { WAIT_V(0); }
;       BAR; MMA(1,1,At,B1); BAR;
;       LDB(B0,1,0); SCHED; LDA(At,1,0); if (more) STAGE_A(0,1,0);
;       WAIT_L(8); BAR; WAIT_L(0); MMA(0,0,At,B0); BAR; SCHED;
;       LDB(B1,1,1); if (more) STAGE_B(1,0,1);
;       BAR; WAIT_L(0); MMA(0,1,At,B1); BAR;
;       LDA(At,1,1); if (more) STAGE_A(1,0,1);
;       BAR; WAIT_L(0); MMA(1,0,At,B0); BAR; SCHED;
;       if (more) { STAGE_B(1,1,1); WAIT_V(6); }
;       BAR; MMA(1,1,At,B1); BAR;
.LBB0_428:
	s_barrier
	s_waitcnt lgkmcnt(0)
	v_mfma_f32_16x16x32_bf16 v[92:95], v[96:99], v[152:155], v[92:95]
	v_mfma_f32_16x16x32_bf16 v[88:91], v[100:103], v[152:155], v[88:91]
	v_mfma_f32_16x16x32_bf16 v[84:87], v[96:99], v[156:159], v[84:87]
	v_mfma_f32_16x16x32_bf16 v[80:83], v[100:103], v[156:159], v[80:83]
	v_mfma_f32_16x16x32_bf16 v[76:79], v[96:99], v[160:163], v[76:79]
	v_mfma_f32_16x16x32_bf16 v[72:75], v[100:103], v[160:163], v[72:75]
	v_mfma_f32_16x16x32_bf16 v[68:71], v[96:99], v[164:167], v[68:71]
	v_mfma_f32_16x16x32_bf16 v[64:67], v[100:103], v[164:167], v[64:67]
	v_mfma_f32_16x16x32_bf16 v[92:95], v[188:191], v[180:183], v[92:95]
	v_mfma_f32_16x16x32_bf16 v[88:91], v[184:187], v[180:183], v[88:91]
	v_mfma_f32_16x16x32_bf16 v[152:155], v[188:191], v[172:175], v[84:87]
	v_mfma_f32_16x16x32_bf16 v[156:159], v[184:187], v[172:175], v[80:83]
	v_mfma_f32_16x16x32_bf16 v[76:79], v[188:191], v[176:179], v[76:79]
	v_mfma_f32_16x16x32_bf16 v[72:75], v[184:187], v[176:179], v[72:75]
	v_mfma_f32_16x16x32_bf16 v[160:163], v[188:191], v[168:171], v[68:71]
	v_mfma_f32_16x16x32_bf16 v[64:67], v[184:187], v[168:171], v[64:67]
	s_barrier
	ds_read_b128 v[176:179], v226 offset:16384
	ds_read_b128 v[164:167], v226 offset:18432
	ds_read_b128 v[180:183], v227 offset:16384
	ds_read_b128 v[168:171], v227 offset:18432
	ds_read_b128 v[84:87], v226 offset:20480
	ds_read_b128 v[68:71], v226 offset:22528
	ds_read_b128 v[172:175], v227 offset:20480
	ds_read_b128 v[80:83], v227 offset:22528
	v_readlane_b32 s84, v254, 0
	v_readlane_b32 s92, v255, 6
	s_and_b64 vcc, exec, s[4:5]
	v_lshl_add_u64 v[218:219], s[0:1], 0, v[212:213]
	v_readlane_b32 s85, v254, 1
	v_readlane_b32 s90, v254, 6
	v_readlane_b32 s91, v254, 7
	v_readlane_b32 s93, v255, 7
	v_readlane_b32 s86, v254, 2
	v_readlane_b32 s87, v254, 3
	v_readlane_b32 s88, v254, 4
	v_readlane_b32 s89, v254, 5
	v_readlane_b32 s94, v255, 8
	v_readlane_b32 s95, v255, 9
	s_cbranch_vccnz .LBB0_430
	s_mov_b32 m0, s33
	v_lshl_add_u64 v[192:193], v[218:219], 0, s[6:7]
	global_load_lds_dwordx4 v[218:219], off
	s_mov_b32 m0, s43
	s_nop 0
	global_load_lds_dwordx4 v[192:193], off
.LBB0_430:
	s_barrier
	s_waitcnt lgkmcnt(0)
	v_mfma_f32_16x16x32_bf16 v[28:31], v[136:139], v[176:179], v[28:31]
	v_mfma_f32_16x16x32_bf16 v[24:27], v[140:143], v[176:179], v[24:27]
	v_mfma_f32_16x16x32_bf16 v[20:23], v[136:139], v[164:167], v[20:23]
	v_mfma_f32_16x16x32_bf16 v[16:19], v[140:143], v[164:167], v[16:19]
	v_mfma_f32_16x16x32_bf16 v[12:15], v[136:139], v[84:87], v[12:15]
	v_mfma_f32_16x16x32_bf16 v[8:11], v[140:143], v[84:87], v[8:11]
	v_mfma_f32_16x16x32_bf16 v[4:7], v[136:139], v[68:71], v[4:7]
	v_mfma_f32_16x16x32_bf16 v[0:3], v[140:143], v[68:71], v[0:3]
	v_mfma_f32_16x16x32_bf16 v[28:31], v[148:151], v[180:183], v[28:31]
	v_mfma_f32_16x16x32_bf16 v[24:27], v[144:147], v[180:183], v[24:27]
	v_mfma_f32_16x16x32_bf16 v[20:23], v[148:151], v[168:171], v[20:23]
	v_mfma_f32_16x16x32_bf16 v[16:19], v[144:147], v[168:171], v[16:19]
	v_mfma_f32_16x16x32_bf16 v[12:15], v[148:151], v[172:175], v[12:15]
	v_mfma_f32_16x16x32_bf16 v[8:11], v[144:147], v[172:175], v[8:11]
	v_mfma_f32_16x16x32_bf16 v[4:7], v[148:151], v[80:83], v[4:7]
	v_mfma_f32_16x16x32_bf16 v[0:3], v[144:147], v[80:83], v[0:3]
	s_barrier
	s_mov_b64 s[52:53], -1
	s_and_b64 vcc, exec, s[4:5]
	v_lshl_add_u64 v[220:221], s[10:11], 0, v[212:213]
	s_cbranch_vccnz .LBB0_432
	s_mov_b32 m0, s44
	v_lshl_add_u64 v[136:137], v[220:221], 0, s[6:7]
	global_load_lds_dwordx4 v[220:221], off
	s_mov_b32 m0, s45
	s_mov_b64 s[52:53], 0
	global_load_lds_dwordx4 v[136:137], off
	s_waitcnt vmcnt(6)

; #define LDA(dst,b,h) _Pragma("unroll") for(int m=0;m<4;++m) _Pragma("unroll") for(int k=0;k<2;++k) \
;     dst[m][k]=*reinterpret_cast<const bf16x8*>(SA(b,h)+(wr*64+m*16)*128+koff[k])
; #define LDB(dst,b,h) _Pragma("unroll") for(int n=0;n<2;++n) _Pragma("unroll") for(int k=0;k<2;++k) \
;     dst[n][k]=*reinterpret_cast<const bf16x8*>(SB(b,h)+(wc*32+n*16)*128+koff[k])
; #define MMA(ai,bj,Af,Bf) do{__builtin_amdgcn_s_setprio(1); \
;     _Pragma("unroll") for(int m=0;m<4;++m) _Pragma("unroll") for(int n=0;n<2;++n) _Pragma("unroll") for(int k=0;k<2;++k) \
;       acc[ai][bj][m][n]=__builtin_amdgcn_mfma_f32_16x16x32_bf16(Bf[n][k],Af[m][k],acc[ai][bj][m][n],0,0,0); \
;     __builtin_amdgcn_s_setprio(0);}while(0)
; #define WAIT_V(n) asm volatile("s_waitcnt vmcnt(" #n ")":::"memory")
; #define WAIT_L(n) asm volatile("s_waitcnt lgkmcnt(" #n ")":::"memory")
; #define BAR __builtin_amdgcn_s_barrier()
; #define SCHED __builtin_amdgcn_sched_barrier(0)
; template <int K, int EPI, bool MIX = false>
; __device__ __forceinline__ void gemm_phase(const Params& p, const u16* __restrict__ A, const u16* __restrict__ Bt,
;                            const float* __restrict__ rs_in, float* __restrict__ ssq_out, float alpha, bool rev = false) {
;     ...
;       LDB(B0,0,0); SCHED; LDA(At,0,0); STAGE_A(1,1,nt-1);
;       WAIT_L(8); BAR; WAIT_L(0); MMA(0,0,At,B0); BAR; SCHED;
;       if (more) SETUP_TILE();
;       LDB(B1,0,1); if (more) STAGE_B(0,0,0);
;       BAR; WAIT_L(0); MMA(0,1,At,B1); BAR;
;       LDA(At,0,1); if (more) STAGE_A(0,0,0);
;       BAR; WAIT_L(0); MMA(1,0,At,B0); BAR; SCHED;
;       if (more) { STAGE_B(0,1,0); WAIT_V(6); } else { WAIT_V(0); }
;       BAR; MMA(1,1,At,B1); BAR;
;       LDB(B0,1,0); SCHED; LDA(At,1,0); if (more) STAGE_A(0,1,0);
;       WAIT_L(8); BAR; WAIT_L(0); MMA(0,0,At,B0); BAR; SCHED;
;       LDB(B1,1,1); if (more) STAGE_B(1,0,1);
;       BAR; WAIT_L(0); MMA(0,1,At,B1); BAR;
;       LDA(At,1,1); if (more) STAGE_A(1,0,1);
;       BAR; WAIT_L(0); MMA(1,0,At,B0); BAR; SCHED;
;       if (more) { STAGE_B(1,1,1); WAIT_V(6); }
;       BAR; MMA(1,1,At,B1); BAR;
.LBB0_434:
	s_barrier
	v_mfma_f32_16x16x32_bf16 v[32:35], v[96:99], v[176:179], v[32:35]
	v_mfma_f32_16x16x32_bf16 v[136:139], v[188:191], v[180:183], v[32:35]
	v_mfma_f32_16x16x32_bf16 v[32:35], v[100:103], v[176:179], v[36:39]
	v_mfma_f32_16x16x32_bf16 v[36:39], v[184:187], v[180:183], v[32:35]
	v_mfma_f32_16x16x32_bf16 v[32:35], v[96:99], v[164:167], v[40:43]
	v_mfma_f32_16x16x32_bf16 v[140:143], v[188:191], v[168:171], v[32:35]
	v_mfma_f32_16x16x32_bf16 v[32:35], v[100:103], v[164:167], v[44:47]
	v_mfma_f32_16x16x32_bf16 v[144:147], v[184:187], v[168:171], v[32:35]
	v_mfma_f32_16x16x32_bf16 v[32:35], v[96:99], v[84:87], v[48:51]
	v_mfma_f32_16x16x32_bf16 v[148:151], v[188:191], v[172:175], v[32:35]
	v_mfma_f32_16x16x32_bf16 v[32:35], v[100:103], v[84:87], v[52:55]
	v_mfma_f32_16x16x32_bf16 v[164:167], v[184:187], v[172:175], v[32:35]
	v_mfma_f32_16x16x32_bf16 v[32:35], v[96:99], v[68:71], v[56:59]
	v_mfma_f32_16x16x32_bf16 v[168:171], v[188:191], v[80:83], v[32:35]
	v_mfma_f32_16x16x32_bf16 v[32:35], v[100:103], v[68:71], v[60:63]
	v_mfma_f32_16x16x32_bf16 v[172:175], v[184:187], v[80:83], v[32:35]
	s_barrier
	ds_read_b128 v[44:47], v232
	ds_read_b128 v[52:55], v232 offset:2048
	ds_read_b128 v[180:183], v233
	ds_read_b128 v[176:179], v233 offset:2048
	ds_read_b128 v[200:203], v226 offset:32768
	ds_read_b128 v[56:59], v226 offset:34816
	ds_read_b128 v[204:207], v227 offset:32768
	ds_read_b128 v[192:195], v227 offset:34816
	ds_read_b128 v[48:51], v226 offset:36864
	ds_read_b128 v[32:35], v226 offset:38912
	ds_read_b128 v[196:199], v227 offset:36864
	ds_read_b128 v[40:43], v227 offset:38912
	s_and_b64 vcc, exec, s[4:5]
	s_cbranch_vccnz .LBB0_436
	s_mov_b32 m0, s60
	v_lshl_add_u64 v[62:63], v[218:219], 0, s[12:13]
	v_lshl_add_u64 v[60:61], v[218:219], 0, s[14:15]
	global_load_lds_dwordx4 v[62:63], off
	s_mov_b32 m0, s61
	s_nop 0
	global_load_lds_dwordx4 v[60:61], off
.LBB0_436:
	s_waitcnt lgkmcnt(8)
	s_barrier
	s_waitcnt lgkmcnt(0)
	v_mfma_f32_16x16x32_bf16 v[60:63], v[44:47], v[200:203], v[124:127]
	v_mfma_f32_16x16x32_bf16 v[124:127], v[180:183], v[204:207], v[60:63]
	v_mfma_f32_16x16x32_bf16 v[60:63], v[52:55], v[200:203], v[120:123]
	v_mfma_f32_16x16x32_bf16 v[120:123], v[176:179], v[204:207], v[60:63]
	v_mfma_f32_16x16x32_bf16 v[60:63], v[44:47], v[56:59], v[116:119]
	v_mfma_f32_16x16x32_bf16 v[100:103], v[180:183], v[192:195], v[60:63]
	v_mfma_f32_16x16x32_bf16 v[60:63], v[52:55], v[56:59], v[112:115]
	v_mfma_f32_16x16x32_bf16 v[96:99], v[176:179], v[192:195], v[60:63]
	v_mfma_f32_16x16x32_bf16 v[60:63], v[44:47], v[48:51], v[108:111]
	v_mfma_f32_16x16x32_bf16 v[84:87], v[180:183], v[196:199], v[60:63]
	v_mfma_f32_16x16x32_bf16 v[60:63], v[52:55], v[48:51], v[104:107]
	v_mfma_f32_16x16x32_bf16 v[80:83], v[176:179], v[196:199], v[60:63]
	v_mfma_f32_16x16x32_bf16 v[60:63], v[44:47], v[32:35], v[128:131]
	v_mfma_f32_16x16x32_bf16 v[68:71], v[180:183], v[40:43], v[60:63]
	v_mfma_f32_16x16x32_bf16 v[60:63], v[52:55], v[32:35], v[132:135]
	v_mfma_f32_16x16x32_bf16 v[60:63], v[176:179], v[40:43], v[60:63]
	s_barrier
	ds_read_b128 v[128:131], v234
	ds_read_b128 v[132:135], v234 offset:2048
	ds_read_b128 v[188:191], v235
	ds_read_b128 v[184:187], v235 offset:2048
	s_and_b64 vcc, exec, s[4:5]
	s_cbranch_vccnz .LBB0_438
	s_mov_b32 m0, s62
	v_lshl_add_u64 v[106:107], v[208:209], 0, s[16:17]
	v_lshl_add_u64 v[104:105], v[208:209], 0, s[18:19]
	global_load_lds_dwordx4 v[106:107], off
	s_mov_b32 m0, s63
	s_nop 0
	global_load_lds_dwordx4 v[104:105], off
; #define LDA(dst,b,h) _Pragma("unroll") for(int m=0;m<4;++m) _Pragma("unroll") for(int k=0;k<2;++k) \
;     dst[m][k]=*reinterpret_cast<const bf16x8*>(SA(b,h)+(wr*64+m*16)*128+koff[k])
; #define LDB(dst,b,h) _Pragma("unroll") for(int n=0;n<2;++n) _Pragma("unroll") for(int k=0;k<2;++k) \
;     dst[n][k]=*reinterpret_cast<const bf16x8*>(SB(b,h)+(wc*32+n*16)*128+koff[k])
; #define MMA(ai,bj,Af,Bf) do{__builtin_amdgcn_s_setprio(1); \
;     _Pragma("unroll") for(int m=0;m<4;++m) _Pragma("unroll") for(int n=0;n<2;++n) _Pragma("unroll") for(int k=0;k<2;++k) \
;       acc[ai][bj][m][n]=__builtin_amdgcn_mfma_f32_16x16x32_bf16(Bf[n][k],Af[m][k],acc[ai][bj][m][n],0,0,0); \
;     __builtin_amdgcn_s_setprio(0);}while(0)
; #define WAIT_V(n) asm volatile("s_waitcnt vmcnt(" #n ")":::"memory")
; #define WAIT_L(n) asm volatile("s_waitcnt lgkmcnt(" #n ")":::"memory")
; #define BAR __builtin_amdgcn_s_barrier()
; #define SCHED __builtin_amdgcn_sched_barrier(0)
; #define STAGE_A(b,h,kt) do{ unsigned char* _d = SA(b,h) + wbase; \
;     if constexpr (BLK) { const char* _s = baseA + ((size_t)(h)*(K/64) + (kt)) * 16384; GLDS(_s + voa, _d); GLDS(_s + 8192 + voa, _d + 8192); } \
;     else { const char* _s = baseA + ((size_t)(h)*128*K + (kt)*64) * 2; GLDS(_s + voa, _d); GLDS(_s + (size_t)128*K + voa, _d + 8192); } }while(0)
; template <int K, int EPI, bool MIX = false>
; __device__ __forceinline__ void gemm_phase(const Params& p, const u16* __restrict__ A, const u16* __restrict__ Bt,
;                            const float* __restrict__ rs_in, float* __restrict__ ssq_out, float alpha, bool rev = false) {
;     ...
;       BAR; WAIT_L(0); MMA(1,0,At,B0); BAR; SCHED;
;       if (more) { STAGE_B(0,1,0); WAIT_V(6); } else { WAIT_V(0); }
;       BAR; MMA(1,1,At,B1); BAR;
;       LDB(B0,1,0); SCHED; LDA(At,1,0); if (more) STAGE_A(0,1,0);
;       WAIT_L(8); BAR; WAIT_L(0); MMA(0,0,At,B0); BAR; SCHED;
;       LDB(B1,1,1); if (more) STAGE_B(1,0,1);
;       BAR; WAIT_L(0); MMA(0,1,At,B1); BAR;
;       LDA(At,1,1); if (more) STAGE_A(1,0,1);
;       BAR; WAIT_L(0); MMA(1,0,At,B0); BAR; SCHED;
;       if (more) { STAGE_B(1,1,1); WAIT_V(6); }
;       BAR; MMA(1,1,At,B1); BAR;
;       if (!more && wr == 0) BAR;
;     }
.LBB0_438:
	s_barrier
	s_waitcnt lgkmcnt(0)
	v_mfma_f32_16x16x32_bf16 v[88:91], v[132:135], v[200:203], v[88:91]
	v_mfma_f32_16x16x32_bf16 v[112:115], v[184:187], v[204:207], v[88:91]
	v_mfma_f32_16x16x32_bf16 v[88:91], v[128:131], v[56:59], v[152:155]
	v_mfma_f32_16x16x32_bf16 v[56:59], v[132:135], v[56:59], v[156:159]
	v_mfma_f32_16x16x32_bf16 v[104:107], v[184:187], v[192:195], v[56:59]
	v_mfma_f32_16x16x32_bf16 v[56:59], v[128:131], v[48:51], v[76:79]
	v_mfma_f32_16x16x32_bf16 v[48:51], v[132:135], v[48:51], v[72:75]
	v_mfma_f32_16x16x32_bf16 v[92:95], v[128:131], v[200:203], v[92:95]
	v_mfma_f32_16x16x32_bf16 v[108:111], v[188:191], v[192:195], v[88:91]
	v_mfma_f32_16x16x32_bf16 v[88:91], v[184:187], v[196:199], v[48:51]
	v_mfma_f32_16x16x32_bf16 v[48:51], v[128:131], v[32:35], v[160:163]
	v_mfma_f32_16x16x32_bf16 v[32:35], v[132:135], v[32:35], v[64:67]
	v_mfma_f32_16x16x32_bf16 v[116:119], v[188:191], v[204:207], v[92:95]
	v_mfma_f32_16x16x32_bf16 v[92:95], v[188:191], v[196:199], v[56:59]
	v_mfma_f32_16x16x32_bf16 v[76:79], v[188:191], v[40:43], v[48:51]
	v_mfma_f32_16x16x32_bf16 v[72:75], v[184:187], v[40:43], v[32:35]
	s_barrier
	ds_read_b128 v[204:207], v226 offset:49152
	ds_read_b128 v[192:195], v226 offset:51200
	ds_read_b128 v[208:211], v227 offset:49152
	ds_read_b128 v[196:199], v227 offset:51200
	ds_read_b128 v[160:163], v226 offset:53248
	ds_read_b128 v[152:155], v226 offset:55296
	ds_read_b128 v[200:203], v227 offset:53248
	ds_read_b128 v[156:159], v227 offset:55296
	s_and_b64 vcc, exec, s[4:5]
	s_cbranch_vccnz .LBB0_440
	s_mov_b32 m0, s64
	v_lshl_add_u64 v[34:35], v[218:219], 0, s[16:17]
	v_lshl_add_u64 v[32:33], v[218:219], 0, s[18:19]
	global_load_lds_dwordx4 v[34:35], off
	s_mov_b32 m0, s65
	s_nop 0
	global_load_lds_dwordx4 v[32:33], off
.LBB0_440:
	s_barrier
	s_waitcnt lgkmcnt(0)
	v_mfma_f32_16x16x32_bf16 v[28:31], v[44:47], v[204:207], v[28:31]
	v_mfma_f32_16x16x32_bf16 v[24:27], v[52:55], v[204:207], v[24:27]
	v_mfma_f32_16x16x32_bf16 v[20:23], v[44:47], v[192:195], v[20:23]
	v_mfma_f32_16x16x32_bf16 v[16:19], v[52:55], v[192:195], v[16:19]
	v_mfma_f32_16x16x32_bf16 v[12:15], v[44:47], v[160:163], v[12:15]
	v_mfma_f32_16x16x32_bf16 v[8:11], v[52:55], v[160:163], v[8:11]
	v_mfma_f32_16x16x32_bf16 v[4:7], v[44:47], v[152:155], v[4:7]
	v_mfma_f32_16x16x32_bf16 v[0:3], v[52:55], v[152:155], v[0:3]
	v_mfma_f32_16x16x32_bf16 v[56:59], v[180:183], v[208:211], v[28:31]
	v_mfma_f32_16x16x32_bf16 v[48:51], v[176:179], v[208:211], v[24:27]
	v_mfma_f32_16x16x32_bf16 v[40:43], v[180:183], v[196:199], v[20:23]
	v_mfma_f32_16x16x32_bf16 v[32:35], v[176:179], v[196:199], v[16:19]
	v_mfma_f32_16x16x32_bf16 v[24:27], v[180:183], v[200:203], v[12:15]
	v_mfma_f32_16x16x32_bf16 v[16:19], v[176:179], v[200:203], v[8:11]
	v_mfma_f32_16x16x32_bf16 v[8:11], v[180:183], v[156:159], v[4:7]
	v_mfma_f32_16x16x32_bf16 v[0:3], v[176:179], v[156:159], v[0:3]
	s_barrier
	s_and_b64 vcc, exec, s[4:5]
	s_mov_b64 s[52:53], s[20:21]
	s_cbranch_vccnz .LBB0_442
	s_mov_b32 m0, s68
	v_lshl_add_u64 v[6:7], v[220:221], 0, s[16:17]
	v_lshl_add_u64 v[4:5], v[220:221], 0, s[18:19]
	global_load_lds_dwordx4 v[6:7], off
	s_mov_b32 m0, s69
	s_mov_b64 s[52:53], 0
	global_load_lds_dwordx4 v[4:5], off
	s_waitcnt vmcnt(6)
.LBB0_442:
	s_barrier
	v_mfma_f32_16x16x32_bf16 v[4:7], v[128:131], v[204:207], v[136:139]
	v_mfma_f32_16x16x32_bf16 v[64:67], v[188:191], v[208:211], v[4:7]
	v_mfma_f32_16x16x32_bf16 v[4:7], v[132:135], v[204:207], v[36:39]
	v_mfma_f32_16x16x32_bf16 v[52:55], v[184:187], v[208:211], v[4:7]
	v_mfma_f32_16x16x32_bf16 v[4:7], v[128:131], v[192:195], v[140:143]
	v_mfma_f32_16x16x32_bf16 v[44:47], v[188:191], v[196:199], v[4:7]
	v_mfma_f32_16x16x32_bf16 v[4:7], v[132:135], v[192:195], v[144:147]
	v_mfma_f32_16x16x32_bf16 v[36:39], v[184:187], v[196:199], v[4:7]
	v_mfma_f32_16x16x32_bf16 v[4:7], v[128:131], v[160:163], v[148:151]
	v_mfma_f32_16x16x32_bf16 v[28:31], v[188:191], v[200:203], v[4:7]
	v_mfma_f32_16x16x32_bf16 v[4:7], v[132:135], v[160:163], v[164:167]
	v_mfma_f32_16x16x32_bf16 v[20:23], v[184:187], v[200:203], v[4:7]
	v_mfma_f32_16x16x32_bf16 v[4:7], v[128:131], v[152:155], v[168:171]
	v_mfma_f32_16x16x32_bf16 v[12:15], v[188:191], v[156:159], v[4:7]
	v_mfma_f32_16x16x32_bf16 v[4:7], v[132:135], v[152:155], v[172:175]
	v_mfma_f32_16x16x32_bf16 v[4:7], v[184:187], v[156:159], v[4:7]
	s_or_b64 vcc, s[4:5], s[20:21]
	s_cbranch_scc0 .Llate_p6_defer
	s_barrier

.Llate_p7_done:
.LBB0_463:
	ds_read_b128 v[128:131], v225
	ds_read_b128 v[132:135], v225 offset:2048
	ds_read_b128 v[136:139], v226
	ds_read_b128 v[140:143], v226 offset:2048
	v_lshl_add_u64 v[192:193], s[50:51], 0, v[218:219]
	s_mov_b32 m0, s64
	v_lshl_add_u64 v[176:177], v[192:193], 0, s[18:19]
	ds_read_b128 v[144:147], v227
	ds_read_b128 v[148:151], v227 offset:2048
	ds_read_b128 v[152:155], v228
	ds_read_b128 v[156:159], v228 offset:2048
	ds_read_b128 v[160:163], v227 offset:4096
	ds_read_b128 v[164:167], v227 offset:6144
	ds_read_b128 v[168:171], v228 offset:4096
	ds_read_b128 v[172:175], v228 offset:6144
	global_load_lds_dwordx4 v[176:177], off
	v_lshl_add_u64 v[176:177], v[192:193], 0, s[20:21]
	s_mov_b32 m0, s65
	s_nop 0
	global_load_lds_dwordx4 v[176:177], off
	s_waitcnt lgkmcnt(8)
	s_barrier
	s_waitcnt lgkmcnt(0)
	v_mfma_f32_16x16x32_bf16 v[124:127], v[128:131], v[144:147], v[124:127]
	v_mfma_f32_16x16x32_bf16 v[120:123], v[132:135], v[144:147], v[120:123]
	v_mfma_f32_16x16x32_bf16 v[116:119], v[128:131], v[148:151], v[116:119]
	v_mfma_f32_16x16x32_bf16 v[112:115], v[132:135], v[148:151], v[112:115]
	v_mfma_f32_16x16x32_bf16 v[108:111], v[128:131], v[160:163], v[108:111]
	v_mfma_f32_16x16x32_bf16 v[104:107], v[132:135], v[160:163], v[104:107]
	v_mfma_f32_16x16x32_bf16 v[100:103], v[128:131], v[164:167], v[100:103]
	v_mfma_f32_16x16x32_bf16 v[96:99], v[132:135], v[164:167], v[96:99]
	v_mfma_f32_16x16x32_bf16 v[124:127], v[136:139], v[152:155], v[124:127]
	v_mfma_f32_16x16x32_bf16 v[120:123], v[140:143], v[152:155], v[120:123]
	v_mfma_f32_16x16x32_bf16 v[116:119], v[136:139], v[156:159], v[116:119]
	v_mfma_f32_16x16x32_bf16 v[112:115], v[140:143], v[156:159], v[112:115]
	v_mfma_f32_16x16x32_bf16 v[108:111], v[136:139], v[168:171], v[108:111]
	v_mfma_f32_16x16x32_bf16 v[104:107], v[140:143], v[168:171], v[104:107]
	v_mfma_f32_16x16x32_bf16 v[100:103], v[136:139], v[172:175], v[100:103]
	v_mfma_f32_16x16x32_bf16 v[96:99], v[140:143], v[172:175], v[96:99]
	s_barrier
	v_lshl_add_u64 v[194:195], s[52:53], 0, v[218:219]
	s_mov_b32 m0, s34
	v_lshl_add_u64 v[196:197], v[194:195], 0, s[26:27]
	ds_read_b128 v[176:179], v229
	ds_read_b128 v[180:183], v229 offset:2048
	ds_read_b128 v[184:187], v232
	ds_read_b128 v[188:191], v232 offset:2048
	global_load_lds_dwordx4 v[196:197], off
	v_lshl_add_u64 v[196:197], v[194:195], 0, s[28:29]
	s_mov_b32 m0, s35
	s_nop 0
	global_load_lds_dwordx4 v[196:197], off
	s_barrier
	s_waitcnt lgkmcnt(0)
	v_mfma_f32_16x16x32_bf16 v[92:95], v[176:179], v[144:147], v[92:95]
	v_mfma_f32_16x16x32_bf16 v[88:91], v[180:183], v[144:147], v[88:91]
	v_mfma_f32_16x16x32_bf16 v[84:87], v[176:179], v[148:151], v[84:87]
	v_mfma_f32_16x16x32_bf16 v[80:83], v[180:183], v[148:151], v[80:83]
	v_mfma_f32_16x16x32_bf16 v[76:79], v[176:179], v[160:163], v[76:79]
	v_mfma_f32_16x16x32_bf16 v[72:75], v[180:183], v[160:163], v[72:75]
	v_mfma_f32_16x16x32_bf16 v[68:71], v[176:179], v[164:167], v[68:71]
	v_mfma_f32_16x16x32_bf16 v[64:67], v[180:183], v[164:167], v[64:67]
	v_mfma_f32_16x16x32_bf16 v[92:95], v[184:187], v[152:155], v[92:95]
	v_mfma_f32_16x16x32_bf16 v[88:91], v[188:191], v[152:155], v[88:91]
	v_mfma_f32_16x16x32_bf16 v[84:87], v[184:187], v[156:159], v[84:87]
	v_mfma_f32_16x16x32_bf16 v[80:83], v[188:191], v[156:159], v[80:83]
	v_mfma_f32_16x16x32_bf16 v[76:79], v[184:187], v[168:171], v[76:79]
	v_mfma_f32_16x16x32_bf16 v[72:75], v[188:191], v[168:171], v[72:75]
	v_mfma_f32_16x16x32_bf16 v[68:71], v[184:187], v[172:175], v[68:71]
	v_mfma_f32_16x16x32_bf16 v[64:67], v[188:191], v[172:175], v[64:67]
	s_barrier
	s_mov_b32 m0, s33
	v_lshl_add_u64 v[196:197], v[192:193], 0, s[26:27]
	ds_read_b128 v[144:147], v227 offset:16384
	ds_read_b128 v[148:151], v227 offset:18432
	ds_read_b128 v[152:155], v228 offset:16384
	ds_read_b128 v[156:159], v228 offset:18432
	ds_read_b128 v[160:163], v227 offset:20480
	ds_read_b128 v[164:167], v227 offset:22528
	ds_read_b128 v[168:171], v228 offset:20480
	ds_read_b128 v[172:175], v228 offset:22528
	global_load_lds_dwordx4 v[196:197], off
	v_lshl_add_u64 v[196:197], v[192:193], 0, s[28:29]
	s_mov_b32 m0, s42
	s_nop 0
	global_load_lds_dwordx4 v[196:197], off
	s_barrier
	s_waitcnt lgkmcnt(0)
	v_mfma_f32_16x16x32_bf16 v[60:63], v[128:131], v[144:147], v[60:63]
	v_mfma_f32_16x16x32_bf16 v[56:59], v[132:135], v[144:147], v[56:59]
	v_mfma_f32_16x16x32_bf16 v[52:55], v[128:131], v[148:151], v[52:55]
	v_mfma_f32_16x16x32_bf16 v[48:51], v[132:135], v[148:151], v[48:51]
	v_mfma_f32_16x16x32_bf16 v[44:47], v[128:131], v[160:163], v[44:47]
	v_mfma_f32_16x16x32_bf16 v[40:43], v[132:135], v[160:163], v[40:43]
	v_mfma_f32_16x16x32_bf16 v[36:39], v[128:131], v[164:167], v[36:39]
	v_mfma_f32_16x16x32_bf16 v[32:35], v[132:135], v[164:167], v[32:35]
	v_mfma_f32_16x16x32_bf16 v[60:63], v[136:139], v[152:155], v[60:63]
	v_mfma_f32_16x16x32_bf16 v[56:59], v[140:143], v[152:155], v[56:59]
	v_mfma_f32_16x16x32_bf16 v[52:55], v[136:139], v[156:159], v[52:55]
	v_mfma_f32_16x16x32_bf16 v[48:51], v[140:143], v[156:159], v[48:51]
	v_mfma_f32_16x16x32_bf16 v[44:47], v[136:139], v[168:171], v[44:47]
	v_mfma_f32_16x16x32_bf16 v[40:43], v[140:143], v[168:171], v[40:43]
	v_mfma_f32_16x16x32_bf16 v[36:39], v[136:139], v[172:175], v[36:39]
	v_mfma_f32_16x16x32_bf16 v[32:35], v[140:143], v[172:175], v[32:35]
	s_barrier
	v_lshl_add_u64 v[196:197], s[2:3], 0, v[218:219]
	s_mov_b32 m0, s43
	v_lshl_add_u64 v[128:129], v[196:197], 0, s[26:27]
	global_load_lds_dwordx4 v[128:129], off
	v_lshl_add_u64 v[128:129], v[196:197], 0, s[28:29]
	s_mov_b32 m0, s44
	s_nop 0
	global_load_lds_dwordx4 v[128:129], off
	s_waitcnt vmcnt(6)
	s_barrier
	v_mfma_f32_16x16x32_bf16 v[28:31], v[176:179], v[144:147], v[28:31]
	v_mfma_f32_16x16x32_bf16 v[24:27], v[180:183], v[144:147], v[24:27]
	v_mfma_f32_16x16x32_bf16 v[20:23], v[176:179], v[148:151], v[20:23]
	v_mfma_f32_16x16x32_bf16 v[16:19], v[180:183], v[148:151], v[16:19]
	v_mfma_f32_16x16x32_bf16 v[12:15], v[176:179], v[160:163], v[12:15]
	v_mfma_f32_16x16x32_bf16 v[8:11], v[180:183], v[160:163], v[8:11]
	v_mfma_f32_16x16x32_bf16 v[4:7], v[176:179], v[164:167], v[4:7]
	v_mfma_f32_16x16x32_bf16 v[0:3], v[180:183], v[164:167], v[0:3]
	v_mfma_f32_16x16x32_bf16 v[28:31], v[184:187], v[152:155], v[28:31]
	v_mfma_f32_16x16x32_bf16 v[24:27], v[188:191], v[152:155], v[24:27]
	v_mfma_f32_16x16x32_bf16 v[20:23], v[184:187], v[156:159], v[20:23]
	v_mfma_f32_16x16x32_bf16 v[16:19], v[188:191], v[156:159], v[16:19]
	v_mfma_f32_16x16x32_bf16 v[12:15], v[184:187], v[168:171], v[12:15]
	v_mfma_f32_16x16x32_bf16 v[8:11], v[188:191], v[168:171], v[8:11]
	v_mfma_f32_16x16x32_bf16 v[4:7], v[184:187], v[172:175], v[4:7]
	v_mfma_f32_16x16x32_bf16 v[0:3], v[188:191], v[172:175], v[0:3]
	s_barrier
	ds_read_b128 v[128:131], v233
	ds_read_b128 v[132:135], v233 offset:2048
	ds_read_b128 v[136:139], v234
	ds_read_b128 v[140:143], v234 offset:2048
	s_mov_b32 m0, s45
	v_lshl_add_u64 v[176:177], v[192:193], 0, s[30:31]
	ds_read_b128 v[144:147], v227 offset:32768
	ds_read_b128 v[148:151], v227 offset:34816
	ds_read_b128 v[152:155], v228 offset:32768
	ds_read_b128 v[156:159], v228 offset:34816
	ds_read_b128 v[160:163], v227 offset:36864
	ds_read_b128 v[164:167], v227 offset:38912
	ds_read_b128 v[168:171], v228 offset:36864
	ds_read_b128 v[172:175], v228 offset:38912
	global_load_lds_dwordx4 v[176:177], off
	v_lshl_add_u64 v[176:177], v[192:193], 0, s[36:37]
	s_mov_b32 m0, s54
	s_nop 0
	global_load_lds_dwordx4 v[176:177], off
	s_waitcnt lgkmcnt(8)
	s_barrier
	s_waitcnt lgkmcnt(0)
	v_mfma_f32_16x16x32_bf16 v[124:127], v[128:131], v[144:147], v[124:127]
	v_mfma_f32_16x16x32_bf16 v[120:123], v[132:135], v[144:147], v[120:123]
	v_mfma_f32_16x16x32_bf16 v[116:119], v[128:131], v[148:151], v[116:119]
	v_mfma_f32_16x16x32_bf16 v[112:115], v[132:135], v[148:151], v[112:115]
	v_mfma_f32_16x16x32_bf16 v[108:111], v[128:131], v[160:163], v[108:111]
	v_mfma_f32_16x16x32_bf16 v[104:107], v[132:135], v[160:163], v[104:107]
	v_mfma_f32_16x16x32_bf16 v[100:103], v[128:131], v[164:167], v[100:103]
	v_mfma_f32_16x16x32_bf16 v[96:99], v[132:135], v[164:167], v[96:99]
	v_mfma_f32_16x16x32_bf16 v[124:127], v[136:139], v[152:155], v[124:127]
	v_mfma_f32_16x16x32_bf16 v[120:123], v[140:143], v[152:155], v[120:123]
	v_mfma_f32_16x16x32_bf16 v[116:119], v[136:139], v[156:159], v[116:119]
	v_mfma_f32_16x16x32_bf16 v[112:115], v[140:143], v[156:159], v[112:115]
	v_mfma_f32_16x16x32_bf16 v[108:111], v[136:139], v[168:171], v[108:111]
	v_mfma_f32_16x16x32_bf16 v[104:107], v[140:143], v[168:171], v[104:107]
	v_mfma_f32_16x16x32_bf16 v[100:103], v[136:139], v[172:175], v[100:103]
	v_mfma_f32_16x16x32_bf16 v[96:99], v[140:143], v[172:175], v[96:99]
	s_barrier
	s_mov_b32 m0, s55
	v_lshl_add_u64 v[198:199], v[194:195], 0, s[38:39]
	ds_read_b128 v[176:179], v235
	ds_read_b128 v[180:183], v235 offset:2048
	ds_read_b128 v[184:187], v236
	ds_read_b128 v[188:191], v236 offset:2048
	global_load_lds_dwordx4 v[198:199], off
	v_lshl_add_u64 v[194:195], v[194:195], 0, s[40:41]
	s_mov_b32 m0, s58
	s_nop 0
	global_load_lds_dwordx4 v[194:195], off
	s_barrier
	s_waitcnt lgkmcnt(0)
	v_mfma_f32_16x16x32_bf16 v[92:95], v[176:179], v[144:147], v[92:95]
	v_mfma_f32_16x16x32_bf16 v[88:91], v[180:183], v[144:147], v[88:91]
	v_mfma_f32_16x16x32_bf16 v[84:87], v[176:179], v[148:151], v[84:87]
	v_mfma_f32_16x16x32_bf16 v[80:83], v[180:183], v[148:151], v[80:83]
	v_mfma_f32_16x16x32_bf16 v[76:79], v[176:179], v[160:163], v[76:79]
	v_mfma_f32_16x16x32_bf16 v[72:75], v[180:183], v[160:163], v[72:75]
	v_mfma_f32_16x16x32_bf16 v[68:71], v[176:179], v[164:167], v[68:71]
	v_mfma_f32_16x16x32_bf16 v[64:67], v[180:183], v[164:167], v[64:67]
	v_mfma_f32_16x16x32_bf16 v[92:95], v[184:187], v[152:155], v[92:95]
	v_mfma_f32_16x16x32_bf16 v[88:91], v[188:191], v[152:155], v[88:91]
	v_mfma_f32_16x16x32_bf16 v[84:87], v[184:187], v[156:159], v[84:87]
	v_mfma_f32_16x16x32_bf16 v[80:83], v[188:191], v[156:159], v[80:83]
	v_mfma_f32_16x16x32_bf16 v[76:79], v[184:187], v[168:171], v[76:79]
	v_mfma_f32_16x16x32_bf16 v[72:75], v[188:191], v[168:171], v[72:75]
	v_mfma_f32_16x16x32_bf16 v[68:71], v[184:187], v[172:175], v[68:71]
	v_mfma_f32_16x16x32_bf16 v[64:67], v[188:191], v[172:175], v[64:67]
	s_barrier
	s_mov_b32 m0, s59
	v_lshl_add_u64 v[194:195], v[192:193], 0, s[38:39]
	ds_read_b128 v[144:147], v227 offset:49152
	ds_read_b128 v[148:151], v227 offset:51200
	ds_read_b128 v[152:155], v228 offset:49152
	ds_read_b128 v[156:159], v228 offset:51200
	ds_read_b128 v[160:163], v227 offset:53248
	ds_read_b128 v[164:167], v227 offset:55296
	ds_read_b128 v[168:171], v228 offset:53248
	ds_read_b128 v[172:175], v228 offset:55296
	global_load_lds_dwordx4 v[194:195], off
	v_lshl_add_u64 v[192:193], v[192:193], 0, s[40:41]
	s_mov_b32 m0, s60
	s_nop 0
	global_load_lds_dwordx4 v[192:193], off
	s_barrier
; #define LDA(dst,b,h) _Pragma("unroll") for(int m=0;m<4;++m) _Pragma("unroll") for(int k=0;k<2;++k) \
;     dst[m][k]=*reinterpret_cast<const bf16x8*>(SA(b,h)+(wr*64+m*16)*128+koff[k])
; #define LDB(dst,b,h) _Pragma("unroll") for(int n=0;n<2;++n) _Pragma("unroll") for(int k=0;k<2;++k) \
;     dst[n][k]=*reinterpret_cast<const bf16x8*>(SB(b,h)+(wc*32+n*16)*128+koff[k])
; #define MMA(ai,bj,Af,Bf) do{__builtin_amdgcn_s_setprio(1); \
;     _Pragma("unroll") for(int m=0;m<4;++m) _Pragma("unroll") for(int n=0;n<2;++n) _Pragma("unroll") for(int k=0;k<2;++k) \
;       acc[ai][bj][m][n]=__builtin_amdgcn_mfma_f32_16x16x32_bf16(Bf[n][k],Af[m][k],acc[ai][bj][m][n],0,0,0); \
;     __builtin_amdgcn_s_setprio(0);}while(0)
; #define WAIT_L(n) asm volatile("s_waitcnt lgkmcnt(" #n ")":::"memory")
; #define BAR __builtin_amdgcn_s_barrier()
; #define SCHED __builtin_amdgcn_sched_barrier(0)
; #define STAGE_A(b,h,kt) do{ unsigned char* _d = SA(b,h) + wbase; \
;     if constexpr (BLK) { const char* _s = baseA + ((size_t)(h)*(K/64) + (kt)) * 16384; GLDS(_s + voa, _d); GLDS(_s + 8192 + voa, _d + 8192); } \
;     else { const char* _s = baseA + ((size_t)(h)*128*K + (kt)*64) * 2; GLDS(_s + voa, _d); GLDS(_s + (size_t)128*K + voa, _d + 8192); } }while(0)
; #define STAGE_B(b,h,kt) do{ unsigned char* _d = SB(b,h) + wbase; \
;     if constexpr (BLK) { const char* _s = ((h)?baseB1:baseB0) + (size_t)(kt) * 16384; GLDS(_s + voa, _d); GLDS(_s + 8192 + voa, _d + 8192); } \
;     else { const char* _s = ((h)?baseB1:baseB0) + (kt)*128; GLDS(_s + voa, _d); GLDS(_s + (size_t)128*K + voa, _d + 8192); } }while(0)
; template <int K, int EPI, bool MIX = false>
; __device__ __forceinline__ void gemm_phase(const Params& p, const u16* __restrict__ A, const u16* __restrict__ Bt,
;                            const float* __restrict__ rs_in, float* __restrict__ ssq_out, float alpha, bool rev = false) {
;     ...
;     ++it;
;     id = item_id(it);
;     const bool more = id < ntiles;
;     if (rev) id = ntiles - 1 - id;
;     {
;       LDB(B0,0,0); SCHED; LDA(At,0,0); STAGE_A(1,1,nt-1);
;       WAIT_L(8); BAR; WAIT_L(0); MMA(0,0,At,B0); BAR; SCHED;
;       if (more) SETUP_TILE();
;       LDB(B1,0,1); if (more) STAGE_B(0,0,0);
;       BAR; WAIT_L(0); MMA(0,1,At,B1); BAR;
;       LDA(At,0,1); if (more) STAGE_A(0,0,0);
	s_waitcnt lgkmcnt(0)
	v_mfma_f32_16x16x32_bf16 v[60:63], v[128:131], v[144:147], v[60:63]
	v_mfma_f32_16x16x32_bf16 v[56:59], v[132:135], v[144:147], v[56:59]
	v_mfma_f32_16x16x32_bf16 v[52:55], v[128:131], v[148:151], v[52:55]
	v_mfma_f32_16x16x32_bf16 v[48:51], v[132:135], v[148:151], v[48:51]
	v_mfma_f32_16x16x32_bf16 v[44:47], v[128:131], v[160:163], v[44:47]
	v_mfma_f32_16x16x32_bf16 v[40:43], v[132:135], v[160:163], v[40:43]
	v_mfma_f32_16x16x32_bf16 v[36:39], v[128:131], v[164:167], v[36:39]
	v_mfma_f32_16x16x32_bf16 v[32:35], v[132:135], v[164:167], v[32:35]
	v_mfma_f32_16x16x32_bf16 v[60:63], v[136:139], v[152:155], v[60:63]
	v_mfma_f32_16x16x32_bf16 v[56:59], v[140:143], v[152:155], v[56:59]
	v_mfma_f32_16x16x32_bf16 v[52:55], v[136:139], v[156:159], v[52:55]
	v_mfma_f32_16x16x32_bf16 v[48:51], v[140:143], v[156:159], v[48:51]
	v_mfma_f32_16x16x32_bf16 v[44:47], v[136:139], v[168:171], v[44:47]
	v_mfma_f32_16x16x32_bf16 v[40:43], v[140:143], v[168:171], v[40:43]
	v_mfma_f32_16x16x32_bf16 v[36:39], v[136:139], v[172:175], v[36:39]
	v_mfma_f32_16x16x32_bf16 v[32:35], v[140:143], v[172:175], v[32:35]
	s_barrier
	s_mov_b32 m0, s61
	v_lshl_add_u64 v[128:129], v[196:197], 0, s[38:39]
	global_load_lds_dwordx4 v[128:129], off
	v_lshl_add_u64 v[128:129], v[196:197], 0, s[40:41]
	s_mov_b32 m0, s62
	s_nop 0
	global_load_lds_dwordx4 v[128:129], off
	s_waitcnt vmcnt(6)
	s_barrier
	v_mfma_f32_16x16x32_bf16 v[28:31], v[176:179], v[144:147], v[28:31]
	v_mfma_f32_16x16x32_bf16 v[24:27], v[180:183], v[144:147], v[24:27]
	v_mfma_f32_16x16x32_bf16 v[20:23], v[176:179], v[148:151], v[20:23]
	v_mfma_f32_16x16x32_bf16 v[16:19], v[180:183], v[148:151], v[16:19]
	v_mfma_f32_16x16x32_bf16 v[12:15], v[176:179], v[160:163], v[12:15]
	v_mfma_f32_16x16x32_bf16 v[8:11], v[180:183], v[160:163], v[8:11]
	v_mfma_f32_16x16x32_bf16 v[4:7], v[176:179], v[164:167], v[4:7]
	v_mfma_f32_16x16x32_bf16 v[0:3], v[180:183], v[164:167], v[0:3]
	v_mfma_f32_16x16x32_bf16 v[28:31], v[184:187], v[152:155], v[28:31]
	v_mfma_f32_16x16x32_bf16 v[24:27], v[188:191], v[152:155], v[24:27]
	v_mfma_f32_16x16x32_bf16 v[20:23], v[184:187], v[156:159], v[20:23]
	v_mfma_f32_16x16x32_bf16 v[16:19], v[188:191], v[156:159], v[16:19]
	v_mfma_f32_16x16x32_bf16 v[12:15], v[184:187], v[168:171], v[12:15]
	v_mfma_f32_16x16x32_bf16 v[8:11], v[188:191], v[168:171], v[8:11]
	v_mfma_f32_16x16x32_bf16 v[4:7], v[184:187], v[172:175], v[4:7]
	v_mfma_f32_16x16x32_bf16 v[0:3], v[188:191], v[172:175], v[0:3]
	s_barrier
	s_add_i32 s67, s67, 2
	s_add_u32 s52, s52, 0x8000
	s_addc_u32 s53, s53, 0
	s_add_u32 s50, s50, 0x8000
	s_addc_u32 s51, s51, 0
	s_add_u32 s2, s2, 0x8000
	s_addc_u32 s3, s3, 0
	s_cmpk_lt_u32 s67, 0x54
	s_cbranch_scc1 .LBB0_463
	ds_read_b128 v[144:147], v225
	ds_read_b128 v[148:151], v225 offset:2048
	ds_read_b128 v[156:159], v226
	ds_read_b128 v[152:155], v226 offset:2048
	s_add_i32 s66, s66, 1
	s_mul_i32 s2, s66, s76
	s_add_i32 s2, s2, s77
	s_cmpk_lt_i32 s2, 0x600
	s_cselect_b64 s[50:51], -1, 0
	s_cmpk_gt_i32 s2, 0x5ff
	v_lshl_add_u64 v[128:129], s[4:5], 0, v[216:217]
	s_mov_b32 m0, s64
	v_lshl_add_u64 v[130:131], v[128:129], 0, s[46:47]
	ds_read_b128 v[160:163], v227
	ds_read_b128 v[164:167], v227 offset:2048
	ds_read_b128 v[188:191], v228
	ds_read_b128 v[180:183], v228 offset:2048
	ds_read_b128 v[168:171], v227 offset:4096
	ds_read_b128 v[172:175], v227 offset:6144
	ds_read_b128 v[184:187], v228 offset:4096
	ds_read_b128 v[176:179], v228 offset:6144
	global_load_lds_dwordx4 v[130:131], off
	v_lshl_add_u64 v[128:129], v[128:129], 0, s[48:49]
	s_mov_b32 m0, s65
	s_nop 0
	global_load_lds_dwordx4 v[128:129], off
	s_waitcnt lgkmcnt(8)
	s_barrier
	s_waitcnt lgkmcnt(0)
	v_mfma_f32_16x16x32_bf16 v[124:127], v[144:147], v[160:163], v[124:127]
	v_mfma_f32_16x16x32_bf16 v[120:123], v[148:151], v[160:163], v[120:123]
	v_mfma_f32_16x16x32_bf16 v[116:119], v[144:147], v[164:167], v[116:119]
	v_mfma_f32_16x16x32_bf16 v[112:115], v[148:151], v[164:167], v[112:115]
	v_mfma_f32_16x16x32_bf16 v[108:111], v[144:147], v[168:171], v[108:111]
	v_mfma_f32_16x16x32_bf16 v[104:107], v[148:151], v[168:171], v[104:107]
	v_mfma_f32_16x16x32_bf16 v[100:103], v[144:147], v[172:175], v[100:103]
	v_mfma_f32_16x16x32_bf16 v[96:99], v[148:151], v[172:175], v[96:99]
	v_mfma_f32_16x16x32_bf16 v[124:127], v[156:159], v[188:191], v[124:127]
	v_mfma_f32_16x16x32_bf16 v[120:123], v[152:155], v[188:191], v[120:123]
	v_mfma_f32_16x16x32_bf16 v[128:131], v[156:159], v[180:183], v[116:119]
	v_mfma_f32_16x16x32_bf16 v[132:135], v[152:155], v[180:183], v[112:115]
	v_mfma_f32_16x16x32_bf16 v[108:111], v[156:159], v[184:187], v[108:111]
	v_mfma_f32_16x16x32_bf16 v[104:107], v[152:155], v[184:187], v[104:107]
	v_mfma_f32_16x16x32_bf16 v[136:139], v[156:159], v[176:179], v[100:103]
	v_mfma_f32_16x16x32_bf16 v[140:143], v[152:155], v[176:179], v[96:99]
	s_barrier
	s_mov_b32 s67, s69
	s_mov_b32 s68, s70
	s_cbranch_scc1 .LBB0_466
	s_sub_i32 s2, 0x5ff, s2
	s_lshr_b32 s3, s2, 3
	s_and_b32 s3, s3, 0x1ffffff8
	s_lshl_b32 s4, s3, 3
	s_sub_i32 s4, s2, s4
	s_and_b32 s2, s2, 7
	s_or_b32 s68, s3, s2
	s_ashr_i32 s67, s4, 3
	s_lshl_b32 s2, s68, 1
	s_mul_i32 s3, s68, 0x2c0000
	v_readlane_b32 s76, v254, 32
	s_mul_hi_u32 s2, s2, 0x160000
	s_add_u32 s4, s92, s3
	v_readlane_b32 s80, v254, 36
	v_readlane_b32 s81, v254, 37
	s_addc_u32 s5, s93, s2
	s_lshl_b32 s2, s67, 1
	s_mul_i32 s3, s67, 0x2c0000
	s_mov_b64 s[8:9], s[80:81]
	s_mul_hi_i32 s2, s2, 0x160000
	s_add_u32 s8, s8, s3
	v_readlane_b32 s84, v254, 40
	v_readlane_b32 s85, v254, 41
	v_readlane_b32 s86, v254, 42
	v_readlane_b32 s87, v254, 43
	v_readlane_b32 s88, v254, 44
	v_readlane_b32 s89, v254, 45
	v_readlane_b32 s90, v254, 46
	v_readlane_b32 s91, v254, 47
	s_addc_u32 s9, s9, s2
	v_readlane_b32 s77, v254, 33
	v_readlane_b32 s84, v254, 0
	s_add_u32 s10, s8, 0x160000
	s_mov_b32 s76, s57
	s_mov_b32 s77, s56
	v_readlane_b32 s85, v254, 1
	v_readlane_b32 s90, v254, 6
	v_readlane_b32 s91, v254, 7
	s_addc_u32 s11, s9, 0
	v_readlane_b32 s78, v254, 34
	v_readlane_b32 s79, v254, 35
	v_readlane_b32 s82, v254, 38
	v_readlane_b32 s83, v254, 39
	v_readlane_b32 s86, v254, 2
	v_readlane_b32 s87, v254, 3
	v_readlane_b32 s88, v254, 4
	v_readlane_b32 s89, v254, 5

; #define LDA(dst,b,h) _Pragma("unroll") for(int m=0;m<4;++m) _Pragma("unroll") for(int k=0;k<2;++k) \
;     dst[m][k]=*reinterpret_cast<const bf16x8*>(SA(b,h)+(wr*64+m*16)*128+koff[k])
; #define LDB(dst,b,h) _Pragma("unroll") for(int n=0;n<2;++n) _Pragma("unroll") for(int k=0;k<2;++k) \
;     dst[n][k]=*reinterpret_cast<const bf16x8*>(SB(b,h)+(wc*32+n*16)*128+koff[k])
; #define MMA(ai,bj,Af,Bf) do{__builtin_amdgcn_s_setprio(1); \
;     _Pragma("unroll") for(int m=0;m<4;++m) _Pragma("unroll") for(int n=0;n<2;++n) _Pragma("unroll") for(int k=0;k<2;++k) \
;       acc[ai][bj][m][n]=__builtin_amdgcn_mfma_f32_16x16x32_bf16(Bf[n][k],Af[m][k],acc[ai][bj][m][n],0,0,0); \
;     __builtin_amdgcn_s_setprio(0);}while(0)
; #define WAIT_V(n) asm volatile("s_waitcnt vmcnt(" #n ")":::"memory")
; #define WAIT_L(n) asm volatile("s_waitcnt lgkmcnt(" #n ")":::"memory")
; #define BAR __builtin_amdgcn_s_barrier()
; #define SCHED __builtin_amdgcn_sched_barrier(0)
; template <int K, int EPI, bool MIX = false>
; __device__ __forceinline__ void gemm_phase(const Params& p, const u16* __restrict__ A, const u16* __restrict__ Bt,
;                            const float* __restrict__ rs_in, float* __restrict__ ssq_out, float alpha, bool rev = false) {
;     ...
;       LDB(B0,0,0); SCHED; LDA(At,0,0); STAGE_A(1,1,nt-1);
;       WAIT_L(8); BAR; WAIT_L(0); MMA(0,0,At,B0); BAR; SCHED;
;       if (more) SETUP_TILE();
;       LDB(B1,0,1); if (more) STAGE_B(0,0,0);
;       BAR; WAIT_L(0); MMA(0,1,At,B1); BAR;
;       LDA(At,0,1); if (more) STAGE_A(0,0,0);
;       BAR; WAIT_L(0); MMA(1,0,At,B0); BAR; SCHED;
;       if (more) { STAGE_B(0,1,0); WAIT_V(6); } else { WAIT_V(0); }
;       BAR; MMA(1,1,At,B1); BAR;
;       LDB(B0,1,0); SCHED; LDA(At,1,0); if (more) STAGE_A(0,1,0);
;       WAIT_L(8); BAR; WAIT_L(0); MMA(0,0,At,B0); BAR; SCHED;
;       LDB(B1,1,1); if (more) STAGE_B(1,0,1);
;       BAR; WAIT_L(0); MMA(0,1,At,B1); BAR;
;       LDA(At,1,1); if (more) STAGE_A(1,0,1);
;       BAR; WAIT_L(0); MMA(1,0,At,B0); BAR; SCHED;
;       if (more) { STAGE_B(1,1,1); WAIT_V(6); }
;       BAR; MMA(1,1,At,B1); BAR;
.LBB0_468:
	s_barrier
	s_waitcnt lgkmcnt(0)
	v_mfma_f32_16x16x32_bf16 v[92:95], v[96:99], v[160:163], v[92:95]
	v_mfma_f32_16x16x32_bf16 v[88:91], v[100:103], v[160:163], v[88:91]
	v_mfma_f32_16x16x32_bf16 v[84:87], v[96:99], v[164:167], v[84:87]
	v_mfma_f32_16x16x32_bf16 v[80:83], v[100:103], v[164:167], v[80:83]
	v_mfma_f32_16x16x32_bf16 v[76:79], v[96:99], v[168:171], v[76:79]
	v_mfma_f32_16x16x32_bf16 v[72:75], v[100:103], v[168:171], v[72:75]
	v_mfma_f32_16x16x32_bf16 v[68:71], v[96:99], v[172:175], v[68:71]
	v_mfma_f32_16x16x32_bf16 v[64:67], v[100:103], v[172:175], v[64:67]
	v_mfma_f32_16x16x32_bf16 v[92:95], v[116:119], v[188:191], v[92:95]
	v_mfma_f32_16x16x32_bf16 v[88:91], v[112:115], v[188:191], v[88:91]
	v_mfma_f32_16x16x32_bf16 v[160:163], v[116:119], v[180:183], v[84:87]
	v_mfma_f32_16x16x32_bf16 v[164:167], v[112:115], v[180:183], v[80:83]
	v_mfma_f32_16x16x32_bf16 v[76:79], v[116:119], v[184:187], v[76:79]
	v_mfma_f32_16x16x32_bf16 v[72:75], v[112:115], v[184:187], v[72:75]
	v_mfma_f32_16x16x32_bf16 v[168:171], v[116:119], v[176:179], v[68:71]
	v_mfma_f32_16x16x32_bf16 v[172:175], v[112:115], v[176:179], v[64:67]
	s_barrier
	ds_read_b128 v[192:195], v227 offset:16384
	ds_read_b128 v[84:87], v227 offset:18432
	ds_read_b128 v[196:199], v228 offset:16384
	ds_read_b128 v[184:187], v228 offset:18432
	ds_read_b128 v[80:83], v227 offset:20480
	ds_read_b128 v[64:67], v227 offset:22528
	ds_read_b128 v[188:191], v228 offset:20480
	ds_read_b128 v[68:71], v228 offset:22528
	s_and_b64 vcc, exec, s[2:3]
	v_lshl_add_u64 v[222:223], s[4:5], 0, v[216:217]
	s_cbranch_vccnz .LBB0_470
	s_mov_b32 m0, s33
	v_lshl_add_u64 v[176:177], v[222:223], 0, s[6:7]
	global_load_lds_dwordx4 v[222:223], off
	s_mov_b32 m0, s42
	s_nop 0
	global_load_lds_dwordx4 v[176:177], off
.LBB0_470:
	s_barrier
	s_waitcnt lgkmcnt(0)
	v_mfma_f32_16x16x32_bf16 v[60:63], v[144:147], v[192:195], v[60:63]
	v_mfma_f32_16x16x32_bf16 v[56:59], v[148:151], v[192:195], v[56:59]
	v_mfma_f32_16x16x32_bf16 v[52:55], v[144:147], v[84:87], v[52:55]
	v_mfma_f32_16x16x32_bf16 v[48:51], v[148:151], v[84:87], v[48:51]
	v_mfma_f32_16x16x32_bf16 v[44:47], v[144:147], v[80:83], v[44:47]
	v_mfma_f32_16x16x32_bf16 v[40:43], v[148:151], v[80:83], v[40:43]
	v_mfma_f32_16x16x32_bf16 v[36:39], v[144:147], v[64:67], v[36:39]
	v_mfma_f32_16x16x32_bf16 v[32:35], v[148:151], v[64:67], v[32:35]
	v_mfma_f32_16x16x32_bf16 v[60:63], v[156:159], v[196:199], v[60:63]
	v_mfma_f32_16x16x32_bf16 v[56:59], v[152:155], v[196:199], v[56:59]
	v_mfma_f32_16x16x32_bf16 v[176:179], v[156:159], v[184:187], v[52:55]
	v_mfma_f32_16x16x32_bf16 v[180:183], v[152:155], v[184:187], v[48:51]
	v_mfma_f32_16x16x32_bf16 v[44:47], v[156:159], v[188:191], v[44:47]
	v_mfma_f32_16x16x32_bf16 v[40:43], v[152:155], v[188:191], v[40:43]
	v_mfma_f32_16x16x32_bf16 v[144:147], v[156:159], v[68:71], v[36:39]
	v_mfma_f32_16x16x32_bf16 v[148:151], v[152:155], v[68:71], v[32:35]
	s_barrier
	s_mov_b64 s[50:51], -1
	s_and_b64 vcc, exec, s[2:3]
	v_lshl_add_u64 v[220:221], s[10:11], 0, v[216:217]
	s_cbranch_vccnz .LBB0_472
	s_mov_b32 m0, s43
	v_lshl_add_u64 v[32:33], v[220:221], 0, s[6:7]
	global_load_lds_dwordx4 v[220:221], off
	s_mov_b32 m0, s44
	s_mov_b64 s[50:51], 0
	global_load_lds_dwordx4 v[32:33], off
	s_waitcnt vmcnt(6)

; #define LDA(dst,b,h) _Pragma("unroll") for(int m=0;m<4;++m) _Pragma("unroll") for(int k=0;k<2;++k) \
;     dst[m][k]=*reinterpret_cast<const bf16x8*>(SA(b,h)+(wr*64+m*16)*128+koff[k])
; #define LDB(dst,b,h) _Pragma("unroll") for(int n=0;n<2;++n) _Pragma("unroll") for(int k=0;k<2;++k) \
;     dst[n][k]=*reinterpret_cast<const bf16x8*>(SB(b,h)+(wc*32+n*16)*128+koff[k])
; #define MMA(ai,bj,Af,Bf) do{__builtin_amdgcn_s_setprio(1); \
;     _Pragma("unroll") for(int m=0;m<4;++m) _Pragma("unroll") for(int n=0;n<2;++n) _Pragma("unroll") for(int k=0;k<2;++k) \
;       acc[ai][bj][m][n]=__builtin_amdgcn_mfma_f32_16x16x32_bf16(Bf[n][k],Af[m][k],acc[ai][bj][m][n],0,0,0); \
;     __builtin_amdgcn_s_setprio(0);}while(0)
; #define WAIT_V(n) asm volatile("s_waitcnt vmcnt(" #n ")":::"memory")
; #define WAIT_L(n) asm volatile("s_waitcnt lgkmcnt(" #n ")":::"memory")
; #define BAR __builtin_amdgcn_s_barrier()
; #define SCHED __builtin_amdgcn_sched_barrier(0)
; template <int K, int EPI, bool MIX = false>
; __device__ __forceinline__ void gemm_phase(const Params& p, const u16* __restrict__ A, const u16* __restrict__ Bt,
;                            const float* __restrict__ rs_in, float* __restrict__ ssq_out, float alpha, bool rev = false) {
;     ...
;       LDB(B0,0,0); SCHED; LDA(At,0,0); STAGE_A(1,1,nt-1);
;       WAIT_L(8); BAR; WAIT_L(0); MMA(0,0,At,B0); BAR; SCHED;
;       if (more) SETUP_TILE();
;       LDB(B1,0,1); if (more) STAGE_B(0,0,0);
;       BAR; WAIT_L(0); MMA(0,1,At,B1); BAR;
;       LDA(At,0,1); if (more) STAGE_A(0,0,0);
;       BAR; WAIT_L(0); MMA(1,0,At,B0); BAR; SCHED;
;       if (more) { STAGE_B(0,1,0); WAIT_V(6); } else { WAIT_V(0); }
;       BAR; MMA(1,1,At,B1); BAR;
;       LDB(B0,1,0); SCHED; LDA(At,1,0); if (more) STAGE_A(0,1,0);
;       WAIT_L(8); BAR; WAIT_L(0); MMA(0,0,At,B0); BAR; SCHED;
;       LDB(B1,1,1); if (more) STAGE_B(1,0,1);
;       BAR; WAIT_L(0); MMA(0,1,At,B1); BAR;
;       LDA(At,1,1); if (more) STAGE_A(1,0,1);
;       BAR; WAIT_L(0); MMA(1,0,At,B0); BAR; SCHED;
;       if (more) { STAGE_B(1,1,1); WAIT_V(6); }
;       BAR; MMA(1,1,At,B1); BAR;
.LBB0_474:
	s_barrier
	v_mfma_f32_16x16x32_bf16 v[28:31], v[96:99], v[192:195], v[28:31]
	v_mfma_f32_16x16x32_bf16 v[24:27], v[100:103], v[192:195], v[24:27]
	v_mfma_f32_16x16x32_bf16 v[20:23], v[96:99], v[84:87], v[20:23]
	v_mfma_f32_16x16x32_bf16 v[16:19], v[100:103], v[84:87], v[16:19]
	v_mfma_f32_16x16x32_bf16 v[12:15], v[96:99], v[80:83], v[12:15]
	v_mfma_f32_16x16x32_bf16 v[8:11], v[100:103], v[80:83], v[8:11]
	v_mfma_f32_16x16x32_bf16 v[4:7], v[96:99], v[64:67], v[4:7]
	v_mfma_f32_16x16x32_bf16 v[0:3], v[100:103], v[64:67], v[0:3]
	v_mfma_f32_16x16x32_bf16 v[28:31], v[116:119], v[196:199], v[28:31]
	v_mfma_f32_16x16x32_bf16 v[24:27], v[112:115], v[196:199], v[24:27]
	v_mfma_f32_16x16x32_bf16 v[152:155], v[116:119], v[184:187], v[20:23]
	v_mfma_f32_16x16x32_bf16 v[156:159], v[112:115], v[184:187], v[16:19]
	v_mfma_f32_16x16x32_bf16 v[12:15], v[116:119], v[188:191], v[12:15]
	v_mfma_f32_16x16x32_bf16 v[8:11], v[112:115], v[188:191], v[8:11]
	v_mfma_f32_16x16x32_bf16 v[184:187], v[116:119], v[68:71], v[4:7]
	v_mfma_f32_16x16x32_bf16 v[188:191], v[112:115], v[68:71], v[0:3]
	s_barrier
	s_nop 0
	ds_read_b128 v[0:3], v233
	ds_read_b128 v[4:7], v233 offset:2048
	ds_read_b128 v[196:199], v234
	ds_read_b128 v[192:195], v234 offset:2048
	ds_read_b128 v[200:203], v227 offset:32768
	ds_read_b128 v[36:39], v227 offset:34816
	ds_read_b128 v[204:207], v228 offset:32768
	ds_read_b128 v[48:51], v228 offset:34816
	ds_read_b128 v[32:35], v227 offset:36864
	ds_read_b128 v[16:19], v227 offset:38912
	ds_read_b128 v[52:55], v228 offset:36864
	ds_read_b128 v[20:23], v228 offset:38912
	s_and_b64 vcc, exec, s[2:3]
	s_cbranch_vccnz .LBB0_476
	s_mov_b32 m0, s45
	v_lshl_add_u64 v[66:67], v[222:223], 0, s[0:1]
	v_lshl_add_u64 v[64:65], v[222:223], 0, s[12:13]
	global_load_lds_dwordx4 v[66:67], off
	s_mov_b32 m0, s54
	s_nop 0
	global_load_lds_dwordx4 v[64:65], off
.LBB0_476:
	s_waitcnt lgkmcnt(8)
	s_barrier
	s_waitcnt lgkmcnt(0)
	v_mfma_f32_16x16x32_bf16 v[64:67], v[0:3], v[200:203], v[124:127]
	v_mfma_f32_16x16x32_bf16 v[112:115], v[196:199], v[204:207], v[64:67]
	v_mfma_f32_16x16x32_bf16 v[64:67], v[4:7], v[200:203], v[120:123]
	v_mfma_f32_16x16x32_bf16 v[116:119], v[192:195], v[204:207], v[64:67]
	v_mfma_f32_16x16x32_bf16 v[64:67], v[0:3], v[36:39], v[128:131]
	v_mfma_f32_16x16x32_bf16 v[96:99], v[196:199], v[48:51], v[64:67]
	v_mfma_f32_16x16x32_bf16 v[64:67], v[4:7], v[36:39], v[132:135]
	v_mfma_f32_16x16x32_bf16 v[100:103], v[192:195], v[48:51], v[64:67]
	v_mfma_f32_16x16x32_bf16 v[64:67], v[0:3], v[32:35], v[108:111]
	v_mfma_f32_16x16x32_bf16 v[80:83], v[196:199], v[52:55], v[64:67]
	v_mfma_f32_16x16x32_bf16 v[64:67], v[4:7], v[32:35], v[104:107]
	v_mfma_f32_16x16x32_bf16 v[84:87], v[192:195], v[52:55], v[64:67]
	v_mfma_f32_16x16x32_bf16 v[64:67], v[0:3], v[16:19], v[136:139]
	v_mfma_f32_16x16x32_bf16 v[68:71], v[4:7], v[16:19], v[140:143]
	v_mfma_f32_16x16x32_bf16 v[64:67], v[196:199], v[20:23], v[64:67]
	v_mfma_f32_16x16x32_bf16 v[68:71], v[192:195], v[20:23], v[68:71]
	s_barrier
	ds_read_b128 v[128:131], v235
	ds_read_b128 v[132:135], v235 offset:2048
	ds_read_b128 v[140:143], v236
	ds_read_b128 v[136:139], v236 offset:2048
	s_and_b64 vcc, exec, s[2:3]
	s_cbranch_vccnz .LBB0_478
	s_mov_b32 m0, s55
	v_lshl_add_u64 v[106:107], v[208:209], 0, s[14:15]
	v_lshl_add_u64 v[104:105], v[208:209], 0, s[16:17]
	global_load_lds_dwordx4 v[106:107], off
	s_mov_b32 m0, s58
	s_nop 0
	global_load_lds_dwordx4 v[104:105], off
; #define LDA(dst,b,h) _Pragma("unroll") for(int m=0;m<4;++m) _Pragma("unroll") for(int k=0;k<2;++k) \
;     dst[m][k]=*reinterpret_cast<const bf16x8*>(SA(b,h)+(wr*64+m*16)*128+koff[k])
; #define LDB(dst,b,h) _Pragma("unroll") for(int n=0;n<2;++n) _Pragma("unroll") for(int k=0;k<2;++k) \
;     dst[n][k]=*reinterpret_cast<const bf16x8*>(SB(b,h)+(wc*32+n*16)*128+koff[k])
; #define MMA(ai,bj,Af,Bf) do{__builtin_amdgcn_s_setprio(1); \
;     _Pragma("unroll") for(int m=0;m<4;++m) _Pragma("unroll") for(int n=0;n<2;++n) _Pragma("unroll") for(int k=0;k<2;++k) \
;       acc[ai][bj][m][n]=__builtin_amdgcn_mfma_f32_16x16x32_bf16(Bf[n][k],Af[m][k],acc[ai][bj][m][n],0,0,0); \
;     __builtin_amdgcn_s_setprio(0);}while(0)
; #define WAIT_V(n) asm volatile("s_waitcnt vmcnt(" #n ")":::"memory")
; #define WAIT_L(n) asm volatile("s_waitcnt lgkmcnt(" #n ")":::"memory")
; #define BAR __builtin_amdgcn_s_barrier()
; #define SCHED __builtin_amdgcn_sched_barrier(0)
; #define STAGE_A(b,h,kt) do{ unsigned char* _d = SA(b,h) + wbase; \
;     if constexpr (BLK) { const char* _s = baseA + ((size_t)(h)*(K/64) + (kt)) * 16384; GLDS(_s + voa, _d); GLDS(_s + 8192 + voa, _d + 8192); } \
;     else { const char* _s = baseA + ((size_t)(h)*128*K + (kt)*64) * 2; GLDS(_s + voa, _d); GLDS(_s + (size_t)128*K + voa, _d + 8192); } }while(0)
; template <int K, int EPI, bool MIX = false>
; __device__ __forceinline__ void gemm_phase(const Params& p, const u16* __restrict__ A, const u16* __restrict__ Bt,
;                            const float* __restrict__ rs_in, float* __restrict__ ssq_out, float alpha, bool rev = false) {
;     ...
;       BAR; WAIT_L(0); MMA(1,0,At,B0); BAR; SCHED;
;       if (more) { STAGE_B(0,1,0); WAIT_V(6); } else { WAIT_V(0); }
;       BAR; MMA(1,1,At,B1); BAR;
;       LDB(B0,1,0); SCHED; LDA(At,1,0); if (more) STAGE_A(0,1,0);
;       WAIT_L(8); BAR; WAIT_L(0); MMA(0,0,At,B0); BAR; SCHED;
;       LDB(B1,1,1); if (more) STAGE_B(1,0,1);
;       BAR; WAIT_L(0); MMA(0,1,At,B1); BAR;
;       LDA(At,1,1); if (more) STAGE_A(1,0,1);
;       BAR; WAIT_L(0); MMA(1,0,At,B0); BAR; SCHED;
;       if (more) { STAGE_B(1,1,1); WAIT_V(6); }
;       BAR; MMA(1,1,At,B1); BAR;
;       if (!more && wr == 0) BAR;
;     }
.LBB0_478:
	s_barrier
	s_waitcnt lgkmcnt(0)
	v_mfma_f32_16x16x32_bf16 v[88:91], v[132:135], v[200:203], v[88:91]
	v_mfma_f32_16x16x32_bf16 v[120:123], v[136:139], v[204:207], v[88:91]
	v_mfma_f32_16x16x32_bf16 v[88:91], v[128:131], v[36:39], v[160:163]
	v_mfma_f32_16x16x32_bf16 v[36:39], v[132:135], v[36:39], v[164:167]
	v_mfma_f32_16x16x32_bf16 v[104:107], v[136:139], v[48:51], v[36:39]
	v_mfma_f32_16x16x32_bf16 v[36:39], v[128:131], v[32:35], v[76:79]
	v_mfma_f32_16x16x32_bf16 v[32:35], v[132:135], v[32:35], v[72:75]
	v_mfma_f32_16x16x32_bf16 v[92:95], v[128:131], v[200:203], v[92:95]
	v_mfma_f32_16x16x32_bf16 v[108:111], v[140:143], v[48:51], v[88:91]
	v_mfma_f32_16x16x32_bf16 v[88:91], v[136:139], v[52:55], v[32:35]
	v_mfma_f32_16x16x32_bf16 v[32:35], v[128:131], v[16:19], v[168:171]
	v_mfma_f32_16x16x32_bf16 v[16:19], v[132:135], v[16:19], v[172:175]
	v_mfma_f32_16x16x32_bf16 v[124:127], v[140:143], v[204:207], v[92:95]
	v_mfma_f32_16x16x32_bf16 v[92:95], v[140:143], v[52:55], v[36:39]
	v_mfma_f32_16x16x32_bf16 v[76:79], v[140:143], v[20:23], v[32:35]
	v_mfma_f32_16x16x32_bf16 v[72:75], v[136:139], v[20:23], v[16:19]
	s_barrier
	ds_read_b128 v[208:211], v227 offset:49152
	ds_read_b128 v[172:175], v227 offset:51200
	ds_read_b128 v[212:215], v228 offset:49152
	ds_read_b128 v[200:203], v228 offset:51200
	ds_read_b128 v[168:171], v227 offset:53248
	ds_read_b128 v[160:163], v227 offset:55296
	ds_read_b128 v[204:207], v228 offset:53248
	ds_read_b128 v[164:167], v228 offset:55296
	s_and_b64 vcc, exec, s[2:3]
	s_cbranch_vccnz .LBB0_480
	s_mov_b32 m0, s59
	v_lshl_add_u64 v[18:19], v[222:223], 0, s[14:15]
	v_lshl_add_u64 v[16:17], v[222:223], 0, s[16:17]
	global_load_lds_dwordx4 v[18:19], off
	s_mov_b32 m0, s60
	s_nop 0
	global_load_lds_dwordx4 v[16:17], off
.LBB0_480:
	s_barrier
	s_waitcnt lgkmcnt(0)
	v_mfma_f32_16x16x32_bf16 v[16:19], v[0:3], v[208:211], v[60:63]
	v_mfma_f32_16x16x32_bf16 v[48:51], v[196:199], v[212:215], v[16:19]
	v_mfma_f32_16x16x32_bf16 v[16:19], v[4:7], v[208:211], v[56:59]
	v_mfma_f32_16x16x32_bf16 v[52:55], v[192:195], v[212:215], v[16:19]
	v_mfma_f32_16x16x32_bf16 v[16:19], v[0:3], v[172:175], v[176:179]
	v_mfma_f32_16x16x32_bf16 v[32:35], v[196:199], v[200:203], v[16:19]
	v_mfma_f32_16x16x32_bf16 v[16:19], v[4:7], v[172:175], v[180:183]
	v_mfma_f32_16x16x32_bf16 v[36:39], v[192:195], v[200:203], v[16:19]
	v_mfma_f32_16x16x32_bf16 v[16:19], v[0:3], v[168:171], v[44:47]
	v_mfma_f32_16x16x32_bf16 v[20:23], v[4:7], v[168:171], v[40:43]
	v_mfma_f32_16x16x32_bf16 v[0:3], v[0:3], v[160:163], v[144:147]
	v_mfma_f32_16x16x32_bf16 v[4:7], v[4:7], v[160:163], v[148:151]
	v_mfma_f32_16x16x32_bf16 v[16:19], v[196:199], v[204:207], v[16:19]
	v_mfma_f32_16x16x32_bf16 v[20:23], v[192:195], v[204:207], v[20:23]
	v_mfma_f32_16x16x32_bf16 v[0:3], v[196:199], v[164:167], v[0:3]
	v_mfma_f32_16x16x32_bf16 v[4:7], v[192:195], v[164:167], v[4:7]
	s_barrier
	s_and_b64 vcc, exec, s[2:3]
	s_mov_b64 s[50:51], s[22:23]
	s_cbranch_vccnz .LBB0_482
	s_mov_b32 m0, s61
	v_lshl_add_u64 v[42:43], v[220:221], 0, s[14:15]
	v_lshl_add_u64 v[40:41], v[220:221], 0, s[16:17]
	global_load_lds_dwordx4 v[42:43], off
	s_mov_b32 m0, s62
	s_mov_b64 s[50:51], 0
	global_load_lds_dwordx4 v[40:41], off
	s_waitcnt vmcnt(6)
.LBB0_482:
	s_barrier
	v_mfma_f32_16x16x32_bf16 v[24:27], v[132:135], v[208:211], v[24:27]
	v_mfma_f32_16x16x32_bf16 v[56:59], v[136:139], v[212:215], v[24:27]
	v_mfma_f32_16x16x32_bf16 v[24:27], v[128:131], v[172:175], v[152:155]
	v_mfma_f32_16x16x32_bf16 v[44:47], v[140:143], v[200:203], v[24:27]
	v_mfma_f32_16x16x32_bf16 v[24:27], v[132:135], v[172:175], v[156:159]
	v_mfma_f32_16x16x32_bf16 v[8:11], v[132:135], v[168:171], v[8:11]
	v_mfma_f32_16x16x32_bf16 v[28:31], v[128:131], v[208:211], v[28:31]
	v_mfma_f32_16x16x32_bf16 v[40:43], v[136:139], v[200:203], v[24:27]
	v_mfma_f32_16x16x32_bf16 v[12:15], v[128:131], v[168:171], v[12:15]
	v_mfma_f32_16x16x32_bf16 v[24:27], v[136:139], v[204:207], v[8:11]
	v_mfma_f32_16x16x32_bf16 v[8:11], v[128:131], v[160:163], v[184:187]
	v_mfma_f32_16x16x32_bf16 v[60:63], v[140:143], v[212:215], v[28:31]
	v_mfma_f32_16x16x32_bf16 v[28:31], v[140:143], v[204:207], v[12:15]
	v_mfma_f32_16x16x32_bf16 v[12:15], v[140:143], v[164:167], v[8:11]
	v_mfma_f32_16x16x32_bf16 v[8:11], v[132:135], v[160:163], v[188:191]
	v_mfma_f32_16x16x32_bf16 v[8:11], v[136:139], v[164:167], v[8:11]
	s_or_b64 vcc, s[2:3], s[22:23]
	s_cbranch_scc0 .Llate_p7_defer
	s_barrier
